# GEMM K loops: first iteration peeled with SrcC=0, the 128 per-tile accumulator-zeroing v_movs removed (all 6 GEMM instances)
# speedup vs baseline: 1.0166x; 1.0166x over previous
.LBB0_195:
	v_mov_b32_e32 v127, 0
	s_andn2_b64 vcc, exec, s[80:81]
	v_mov_b32_e32 v126, v127
	v_mov_b32_e32 v125, v127
	v_mov_b32_e32 v124, v127
	v_mov_b32_e32 v123, v127
	v_mov_b32_e32 v122, v127
	v_mov_b32_e32 v121, v127
	v_mov_b32_e32 v120, v127
	v_mov_b32_e32 v111, v127
	v_mov_b32_e32 v110, v127
	v_mov_b32_e32 v109, v127
	v_mov_b32_e32 v108, v127
	v_mov_b32_e32 v107, v127
	v_mov_b32_e32 v106, v127
	v_mov_b32_e32 v105, v127
	v_mov_b32_e32 v104, v127
	v_mov_b32_e32 v95, v127
	v_mov_b32_e32 v94, v127
	v_mov_b32_e32 v93, v127
	v_mov_b32_e32 v92, v127
	v_mov_b32_e32 v91, v127
	v_mov_b32_e32 v90, v127
	v_mov_b32_e32 v89, v127
	v_mov_b32_e32 v88, v127
	v_mov_b32_e32 v79, v127
	v_mov_b32_e32 v78, v127
	v_mov_b32_e32 v77, v127
	v_mov_b32_e32 v76, v127
	v_mov_b32_e32 v75, v127
	v_mov_b32_e32 v74, v127
	v_mov_b32_e32 v73, v127
	v_mov_b32_e32 v72, v127
	v_mov_b32_e32 v119, v127
	v_mov_b32_e32 v118, v127
	v_mov_b32_e32 v117, v127
	v_mov_b32_e32 v116, v127
	v_mov_b32_e32 v115, v127
	v_mov_b32_e32 v114, v127
	v_mov_b32_e32 v113, v127
	v_mov_b32_e32 v112, v127
	v_mov_b32_e32 v103, v127
	v_mov_b32_e32 v102, v127
	v_mov_b32_e32 v101, v127
	v_mov_b32_e32 v100, v127
	v_mov_b32_e32 v99, v127
	v_mov_b32_e32 v98, v127
	v_mov_b32_e32 v97, v127
	v_mov_b32_e32 v96, v127
	v_mov_b32_e32 v87, v127
	v_mov_b32_e32 v86, v127
	v_mov_b32_e32 v85, v127
	v_mov_b32_e32 v84, v127
	v_mov_b32_e32 v83, v127
	v_mov_b32_e32 v82, v127
	v_mov_b32_e32 v81, v127
	v_mov_b32_e32 v80, v127
	v_mov_b32_e32 v71, v127
	v_mov_b32_e32 v70, v127
	v_mov_b32_e32 v69, v127
	v_mov_b32_e32 v68, v127
	v_mov_b32_e32 v67, v127
	v_mov_b32_e32 v66, v127
	v_mov_b32_e32 v65, v127
	v_mov_b32_e32 v64, v127
	v_mov_b32_e32 v63, v127
	v_mov_b32_e32 v62, v127
	v_mov_b32_e32 v61, v127
	v_mov_b32_e32 v60, v127
	v_mov_b32_e32 v59, v127
	v_mov_b32_e32 v58, v127
	v_mov_b32_e32 v57, v127
	v_mov_b32_e32 v56, v127
	v_mov_b32_e32 v47, v127
	v_mov_b32_e32 v46, v127
	v_mov_b32_e32 v45, v127
	v_mov_b32_e32 v44, v127
	v_mov_b32_e32 v43, v127
	v_mov_b32_e32 v42, v127
	v_mov_b32_e32 v41, v127
	v_mov_b32_e32 v40, v127
	v_mov_b32_e32 v31, v127
	v_mov_b32_e32 v30, v127
	v_mov_b32_e32 v29, v127
	v_mov_b32_e32 v28, v127
	v_mov_b32_e32 v27, v127
	v_mov_b32_e32 v26, v127
	v_mov_b32_e32 v25, v127
	v_mov_b32_e32 v24, v127
	v_mov_b32_e32 v15, v127
	v_mov_b32_e32 v14, v127
	v_mov_b32_e32 v13, v127
	v_mov_b32_e32 v12, v127
	v_mov_b32_e32 v11, v127
	v_mov_b32_e32 v10, v127
	v_mov_b32_e32 v9, v127
	v_mov_b32_e32 v8, v127
	v_mov_b32_e32 v55, v127
	v_mov_b32_e32 v54, v127
	v_mov_b32_e32 v53, v127
	v_mov_b32_e32 v52, v127
	v_mov_b32_e32 v51, v127
	v_mov_b32_e32 v50, v127
	v_mov_b32_e32 v49, v127
	v_mov_b32_e32 v48, v127
	v_mov_b32_e32 v39, v127
	v_mov_b32_e32 v38, v127
	v_mov_b32_e32 v37, v127
	v_mov_b32_e32 v36, v127
	v_mov_b32_e32 v35, v127
	v_mov_b32_e32 v34, v127
	v_mov_b32_e32 v33, v127
	v_mov_b32_e32 v32, v127
	v_mov_b32_e32 v23, v127
	v_mov_b32_e32 v22, v127
	v_mov_b32_e32 v21, v127
	v_mov_b32_e32 v20, v127
	v_mov_b32_e32 v19, v127
	v_mov_b32_e32 v18, v127
	v_mov_b32_e32 v17, v127
	v_mov_b32_e32 v16, v127
	v_mov_b32_e32 v7, v127
	v_mov_b32_e32 v6, v127
	v_mov_b32_e32 v5, v127
	v_mov_b32_e32 v4, v127
	v_mov_b32_e32 v3, v127
	v_mov_b32_e32 v2, v127
	v_mov_b32_e32 v1, v127
	v_mov_b32_e32 v0, v127
	s_cbranch_vccnz .LBB0_198
	s_add_u32 s10, s6, 0x100
	s_addc_u32 s40, s7, 0
	s_add_u32 s6, s38, 0x80
	s_addc_u32 s7, s39, 0
	s_mov_b32 s2, 0
	s_add_i32 s41, s2, 2
	s_add_u32 s21, s6, 0x80
	s_addc_u32 s3, s7, 0
	s_add_i32 s42, 0, 0x10000
	v_add_u32_e32 v140, s42, v154
	ds_read_b128 v[142:145], v140
	ds_read_b128 v[162:165], v140 offset:1024
	ds_read_b128 v[166:169], v140 offset:2048
	ds_read_b128 v[170:173], v140 offset:3072
	s_cmp_eq_u32 s9, s2
	s_cselect_b32 s2, s68, s21
	s_cselect_b32 s3, s69, s3
	s_cselect_b32 s39, s95, s40
	s_cselect_b32 s38, s94, s10
	v_lshl_add_u64 v[226:227], s[6:7], 0, v[138:139]
	s_add_i32 m0, s79, 0xc000
	ds_read_b128 v[174:177], v155
	ds_read_b128 v[178:181], v155 offset:1024
	ds_read_b128 v[182:185], v155 offset:2048
	ds_read_b128 v[186:189], v155 offset:3072
	ds_read_b128 v[206:209], v155 offset:4096
	ds_read_b128 v[214:217], v155 offset:5120
	ds_read_b128 v[218:221], v155 offset:6144
	ds_read_b128 v[222:225], v155 offset:7168
	global_load_lds_dwordx4 v[226:227], off
	v_lshl_add_u64 v[226:227], s[6:7], 0, v[136:137]
	s_add_i32 m0, s79, 0xe000
	s_nop 0
	global_load_lds_dwordx4 v[226:227], off
	s_waitcnt lgkmcnt(8)
	s_barrier
	s_waitcnt lgkmcnt(0)
	s_setprio 1
	s_waitcnt lgkmcnt(0)
	v_mfma_f32_16x16x32_bf16 v[124:127], v[142:145], v[174:177], 0
	v_mfma_f32_16x16x32_bf16 v[120:123], v[166:169], v[174:177], 0
	v_mfma_f32_16x16x32_bf16 v[108:111], v[142:145], v[182:185], 0
	v_mfma_f32_16x16x32_bf16 v[104:107], v[166:169], v[182:185], 0
	v_mfma_f32_16x16x32_bf16 v[92:95], v[142:145], v[206:209], 0
	v_mfma_f32_16x16x32_bf16 v[88:91], v[166:169], v[206:209], 0
	v_mfma_f32_16x16x32_bf16 v[76:79], v[142:145], v[218:221], 0
	v_mfma_f32_16x16x32_bf16 v[72:75], v[166:169], v[218:221], 0
	v_mfma_f32_16x16x32_bf16 v[124:127], v[162:165], v[178:181], v[124:127]
	v_mfma_f32_16x16x32_bf16 v[120:123], v[170:173], v[178:181], v[120:123]
	v_mfma_f32_16x16x32_bf16 v[108:111], v[162:165], v[186:189], v[108:111]
	v_mfma_f32_16x16x32_bf16 v[104:107], v[170:173], v[186:189], v[104:107]
	v_mfma_f32_16x16x32_bf16 v[92:95], v[162:165], v[214:217], v[92:95]
	v_mfma_f32_16x16x32_bf16 v[88:91], v[170:173], v[214:217], v[88:91]
	v_mfma_f32_16x16x32_bf16 v[76:79], v[162:165], v[222:225], v[76:79]
	v_mfma_f32_16x16x32_bf16 v[72:75], v[170:173], v[222:225], v[72:75]
	s_setprio 0
	s_barrier
	s_add_i32 s21, 0, 0x14000
	s_add_i32 s42, s42, s54
	v_add_u32_e32 v140, s21, v154
	v_lshl_add_u64 v[242:243], s[38:39], 0, v[130:131]
	s_mov_b32 m0, s42
	ds_read_b128 v[226:229], v140
	ds_read_b128 v[230:233], v140 offset:1024
	ds_read_b128 v[234:237], v140 offset:2048
	ds_read_b128 v[238:241], v140 offset:3072
	global_load_lds_dwordx4 v[242:243], off
	v_lshl_add_u64 v[244:245], s[38:39], 0, v[128:129]
	s_add_i32 m0, s42, 0x2000
	s_nop 0
	global_load_lds_dwordx4 v[244:245], off
	s_barrier
	s_waitcnt lgkmcnt(0)
	s_setprio 1
	s_waitcnt lgkmcnt(0)
	v_mfma_f32_16x16x32_bf16 v[116:119], v[226:229], v[174:177], 0
	v_mfma_f32_16x16x32_bf16 v[112:115], v[234:237], v[174:177], 0
	v_mfma_f32_16x16x32_bf16 v[100:103], v[226:229], v[182:185], 0
	v_mfma_f32_16x16x32_bf16 v[96:99], v[234:237], v[182:185], 0
	v_mfma_f32_16x16x32_bf16 v[84:87], v[226:229], v[206:209], 0
	v_mfma_f32_16x16x32_bf16 v[80:83], v[234:237], v[206:209], 0
	v_mfma_f32_16x16x32_bf16 v[68:71], v[226:229], v[218:221], 0
	v_mfma_f32_16x16x32_bf16 v[64:67], v[234:237], v[218:221], 0
	v_mfma_f32_16x16x32_bf16 v[116:119], v[230:233], v[178:181], v[116:119]
	v_mfma_f32_16x16x32_bf16 v[112:115], v[238:241], v[178:181], v[112:115]
	v_mfma_f32_16x16x32_bf16 v[100:103], v[230:233], v[186:189], v[100:103]
	v_mfma_f32_16x16x32_bf16 v[96:99], v[238:241], v[186:189], v[96:99]
	v_mfma_f32_16x16x32_bf16 v[84:87], v[230:233], v[214:217], v[84:87]
	v_mfma_f32_16x16x32_bf16 v[80:83], v[238:241], v[214:217], v[80:83]
	v_mfma_f32_16x16x32_bf16 v[68:71], v[230:233], v[222:225], v[68:71]
	v_mfma_f32_16x16x32_bf16 v[64:67], v[238:241], v[222:225], v[64:67]
	s_setprio 0
	s_mov_b32 m0, s79
	v_lshl_add_u64 v[246:247], s[2:3], 0, v[130:131]
	s_barrier
	ds_read_b128 v[174:177], v155 offset:16384
	ds_read_b128 v[178:181], v155 offset:17408
	ds_read_b128 v[182:185], v155 offset:18432
	ds_read_b128 v[186:189], v155 offset:19456
	ds_read_b128 v[206:209], v155 offset:20480
	ds_read_b128 v[214:217], v155 offset:21504
	ds_read_b128 v[218:221], v155 offset:22528
	ds_read_b128 v[222:225], v155 offset:23552
	global_load_lds_dwordx4 v[246:247], off
	v_lshl_add_u64 v[248:249], s[2:3], 0, v[128:129]
	s_mov_b32 m0, s34
	s_nop 0
	global_load_lds_dwordx4 v[248:249], off
	s_barrier
	s_waitcnt lgkmcnt(0)
	s_setprio 1
	s_waitcnt lgkmcnt(0)
	v_mfma_f32_16x16x32_bf16 v[60:63], v[142:145], v[174:177], 0
	v_mfma_f32_16x16x32_bf16 v[56:59], v[166:169], v[174:177], 0
	v_mfma_f32_16x16x32_bf16 v[44:47], v[142:145], v[182:185], 0
	v_mfma_f32_16x16x32_bf16 v[40:43], v[166:169], v[182:185], 0
	v_mfma_f32_16x16x32_bf16 v[28:31], v[142:145], v[206:209], 0
	v_mfma_f32_16x16x32_bf16 v[24:27], v[166:169], v[206:209], 0
	v_mfma_f32_16x16x32_bf16 v[12:15], v[142:145], v[218:221], 0
	v_mfma_f32_16x16x32_bf16 v[8:11], v[166:169], v[218:221], 0
	v_mfma_f32_16x16x32_bf16 v[60:63], v[162:165], v[178:181], v[60:63]
	v_mfma_f32_16x16x32_bf16 v[56:59], v[170:173], v[178:181], v[56:59]
	v_mfma_f32_16x16x32_bf16 v[44:47], v[162:165], v[186:189], v[44:47]
	v_mfma_f32_16x16x32_bf16 v[40:43], v[170:173], v[186:189], v[40:43]
	v_mfma_f32_16x16x32_bf16 v[28:31], v[162:165], v[214:217], v[28:31]
	v_mfma_f32_16x16x32_bf16 v[24:27], v[170:173], v[214:217], v[24:27]
	v_mfma_f32_16x16x32_bf16 v[12:15], v[162:165], v[222:225], v[12:15]
	v_mfma_f32_16x16x32_bf16 v[8:11], v[170:173], v[222:225], v[8:11]
	s_setprio 0
	s_barrier
	s_add_u32 s38, s38, s88
	s_addc_u32 s39, s39, s89
	s_add_i32 s21, s21, s54
	v_lshl_add_u64 v[250:251], s[38:39], 0, v[130:131]
	s_mov_b32 m0, s21
	v_lshl_add_u64 v[252:253], s[38:39], 0, v[128:129]
	global_load_lds_dwordx4 v[250:251], off
	s_add_i32 m0, s21, 0x2000
	s_nop 0
	global_load_lds_dwordx4 v[252:253], off
	s_waitcnt vmcnt(6)
	s_barrier
	s_setprio 1
	v_mfma_f32_16x16x32_bf16 v[52:55], v[226:229], v[174:177], 0
	v_mfma_f32_16x16x32_bf16 v[48:51], v[234:237], v[174:177], 0
	v_mfma_f32_16x16x32_bf16 v[36:39], v[226:229], v[182:185], 0
	v_mfma_f32_16x16x32_bf16 v[32:35], v[234:237], v[182:185], 0
	v_mfma_f32_16x16x32_bf16 v[20:23], v[226:229], v[206:209], 0
	v_mfma_f32_16x16x32_bf16 v[16:19], v[234:237], v[206:209], 0
	v_mfma_f32_16x16x32_bf16 v[4:7], v[226:229], v[218:221], 0
	v_mfma_f32_16x16x32_bf16 v[0:3], v[234:237], v[218:221], 0
	v_mfma_f32_16x16x32_bf16 v[52:55], v[230:233], v[178:181], v[52:55]
	v_mfma_f32_16x16x32_bf16 v[48:51], v[238:241], v[178:181], v[48:51]
	v_mfma_f32_16x16x32_bf16 v[36:39], v[230:233], v[186:189], v[36:39]
	v_mfma_f32_16x16x32_bf16 v[32:35], v[238:241], v[186:189], v[32:35]
	v_mfma_f32_16x16x32_bf16 v[20:23], v[230:233], v[214:217], v[20:23]
	v_mfma_f32_16x16x32_bf16 v[16:19], v[238:241], v[214:217], v[16:19]
	v_mfma_f32_16x16x32_bf16 v[4:7], v[230:233], v[222:225], v[4:7]
	v_mfma_f32_16x16x32_bf16 v[0:3], v[238:241], v[222:225], v[0:3]
	s_setprio 0
	s_add_i32 s21, 0, 0x18000
	v_add_u32_e32 v140, s21, v154
	s_barrier
	ds_read_b128 v[142:145], v140
	ds_read_b128 v[162:165], v140 offset:1024
	ds_read_b128 v[166:169], v140 offset:2048
	ds_read_b128 v[170:173], v140 offset:3072
	s_add_u32 s2, s2, s88
	s_addc_u32 s3, s3, s89
	s_mov_b32 m0, s35
	v_lshl_add_u64 v[226:227], s[2:3], 0, v[130:131]
	ds_read_b128 v[174:177], v155 offset:32768
	ds_read_b128 v[178:181], v155 offset:33792
	ds_read_b128 v[182:185], v155 offset:34816
	ds_read_b128 v[186:189], v155 offset:35840
	ds_read_b128 v[206:209], v155 offset:36864
	ds_read_b128 v[214:217], v155 offset:37888
	ds_read_b128 v[218:221], v155 offset:38912
	ds_read_b128 v[222:225], v155 offset:39936
	global_load_lds_dwordx4 v[226:227], off
	v_lshl_add_u64 v[226:227], s[2:3], 0, v[128:129]
	s_mov_b32 m0, s44
	s_nop 0
	global_load_lds_dwordx4 v[226:227], off
	s_waitcnt lgkmcnt(8)
	s_barrier
	s_waitcnt lgkmcnt(0)
	s_setprio 1
	s_waitcnt lgkmcnt(0)
	v_mfma_f32_16x16x32_bf16 v[124:127], v[142:145], v[174:177], v[124:127]
	v_mfma_f32_16x16x32_bf16 v[120:123], v[166:169], v[174:177], v[120:123]
	v_mfma_f32_16x16x32_bf16 v[108:111], v[142:145], v[182:185], v[108:111]
	v_mfma_f32_16x16x32_bf16 v[104:107], v[166:169], v[182:185], v[104:107]
	v_mfma_f32_16x16x32_bf16 v[92:95], v[142:145], v[206:209], v[92:95]
	v_mfma_f32_16x16x32_bf16 v[88:91], v[166:169], v[206:209], v[88:91]
	v_mfma_f32_16x16x32_bf16 v[76:79], v[142:145], v[218:221], v[76:79]
	v_mfma_f32_16x16x32_bf16 v[72:75], v[166:169], v[218:221], v[72:75]
	v_mfma_f32_16x16x32_bf16 v[124:127], v[162:165], v[178:181], v[124:127]
	v_mfma_f32_16x16x32_bf16 v[120:123], v[170:173], v[178:181], v[120:123]
	v_mfma_f32_16x16x32_bf16 v[108:111], v[162:165], v[186:189], v[108:111]
	v_mfma_f32_16x16x32_bf16 v[104:107], v[170:173], v[186:189], v[104:107]
	v_mfma_f32_16x16x32_bf16 v[92:95], v[162:165], v[214:217], v[92:95]
	v_mfma_f32_16x16x32_bf16 v[88:91], v[170:173], v[214:217], v[88:91]
	v_mfma_f32_16x16x32_bf16 v[76:79], v[162:165], v[222:225], v[76:79]
	v_mfma_f32_16x16x32_bf16 v[72:75], v[170:173], v[222:225], v[72:75]
	s_setprio 0
	s_barrier
	s_add_i32 s2, 0, 0x1c000
	s_add_i32 s3, s21, s54
	v_add_u32_e32 v140, s2, v154
	v_lshl_add_u64 v[242:243], v[242:243], 0, s[50:51]
	s_mov_b32 m0, s3
	ds_read_b128 v[226:229], v140
	ds_read_b128 v[230:233], v140 offset:1024
	ds_read_b128 v[234:237], v140 offset:2048
	ds_read_b128 v[238:241], v140 offset:3072
	global_load_lds_dwordx4 v[242:243], off
	v_lshl_add_u64 v[242:243], v[244:245], 0, s[50:51]
	s_add_i32 m0, s3, 0x2000
	s_nop 0
	global_load_lds_dwordx4 v[242:243], off
	s_barrier
	s_waitcnt lgkmcnt(0)
	s_setprio 1
	s_waitcnt lgkmcnt(0)
	v_mfma_f32_16x16x32_bf16 v[116:119], v[226:229], v[174:177], v[116:119]
	v_mfma_f32_16x16x32_bf16 v[112:115], v[234:237], v[174:177], v[112:115]
	v_mfma_f32_16x16x32_bf16 v[100:103], v[226:229], v[182:185], v[100:103]
	v_mfma_f32_16x16x32_bf16 v[96:99], v[234:237], v[182:185], v[96:99]
	v_mfma_f32_16x16x32_bf16 v[84:87], v[226:229], v[206:209], v[84:87]
	v_mfma_f32_16x16x32_bf16 v[80:83], v[234:237], v[206:209], v[80:83]
	v_mfma_f32_16x16x32_bf16 v[68:71], v[226:229], v[218:221], v[68:71]
	v_mfma_f32_16x16x32_bf16 v[64:67], v[234:237], v[218:221], v[64:67]
	v_mfma_f32_16x16x32_bf16 v[116:119], v[230:233], v[178:181], v[116:119]
	v_mfma_f32_16x16x32_bf16 v[112:115], v[238:241], v[178:181], v[112:115]
	v_mfma_f32_16x16x32_bf16 v[100:103], v[230:233], v[186:189], v[100:103]
	v_mfma_f32_16x16x32_bf16 v[96:99], v[238:241], v[186:189], v[96:99]
	v_mfma_f32_16x16x32_bf16 v[84:87], v[230:233], v[214:217], v[84:87]
	v_mfma_f32_16x16x32_bf16 v[80:83], v[238:241], v[214:217], v[80:83]
	v_mfma_f32_16x16x32_bf16 v[68:71], v[230:233], v[222:225], v[68:71]
	v_mfma_f32_16x16x32_bf16 v[64:67], v[238:241], v[222:225], v[64:67]
	s_setprio 0
	s_mov_b32 m0, s82
	v_lshl_add_u64 v[242:243], v[246:247], 0, s[50:51]
	s_barrier
	ds_read_b128 v[174:177], v155 offset:49152
	ds_read_b128 v[178:181], v155 offset:50176
	ds_read_b128 v[182:185], v155 offset:51200
	ds_read_b128 v[186:189], v155 offset:52224
	ds_read_b128 v[206:209], v155 offset:53248
	ds_read_b128 v[214:217], v155 offset:54272
	ds_read_b128 v[218:221], v155 offset:55296
	ds_read_b128 v[222:225], v155 offset:56320
	global_load_lds_dwordx4 v[242:243], off
	v_lshl_add_u64 v[242:243], v[248:249], 0, s[50:51]
	s_mov_b32 m0, s83
	s_nop 0
	global_load_lds_dwordx4 v[242:243], off
	s_barrier
	s_waitcnt lgkmcnt(0)
	s_setprio 1
	s_waitcnt lgkmcnt(0)
	v_mfma_f32_16x16x32_bf16 v[60:63], v[142:145], v[174:177], v[60:63]
	v_mfma_f32_16x16x32_bf16 v[56:59], v[166:169], v[174:177], v[56:59]
	v_mfma_f32_16x16x32_bf16 v[44:47], v[142:145], v[182:185], v[44:47]
	v_mfma_f32_16x16x32_bf16 v[40:43], v[166:169], v[182:185], v[40:43]
	v_mfma_f32_16x16x32_bf16 v[28:31], v[142:145], v[206:209], v[28:31]
	v_mfma_f32_16x16x32_bf16 v[24:27], v[166:169], v[206:209], v[24:27]
	v_mfma_f32_16x16x32_bf16 v[12:15], v[142:145], v[218:221], v[12:15]
	v_mfma_f32_16x16x32_bf16 v[8:11], v[166:169], v[218:221], v[8:11]
	v_mfma_f32_16x16x32_bf16 v[60:63], v[162:165], v[178:181], v[60:63]
	v_mfma_f32_16x16x32_bf16 v[56:59], v[170:173], v[178:181], v[56:59]
	v_mfma_f32_16x16x32_bf16 v[44:47], v[162:165], v[186:189], v[44:47]
	v_mfma_f32_16x16x32_bf16 v[40:43], v[170:173], v[186:189], v[40:43]
	v_mfma_f32_16x16x32_bf16 v[28:31], v[162:165], v[214:217], v[28:31]
	v_mfma_f32_16x16x32_bf16 v[24:27], v[170:173], v[214:217], v[24:27]
	v_mfma_f32_16x16x32_bf16 v[12:15], v[162:165], v[222:225], v[12:15]
	v_mfma_f32_16x16x32_bf16 v[8:11], v[170:173], v[222:225], v[8:11]
	s_setprio 0
	s_barrier
	s_add_i32 s2, s2, s54
	v_lshl_add_u64 v[142:143], v[250:251], 0, s[50:51]
	s_mov_b32 m0, s2
	s_nop 0
	global_load_lds_dwordx4 v[142:143], off
	v_lshl_add_u64 v[142:143], v[252:253], 0, s[50:51]
	s_add_i32 m0, s2, 0x2000
	s_nop 0
	global_load_lds_dwordx4 v[142:143], off
	s_waitcnt vmcnt(6)
	s_barrier
	s_setprio 1
	v_mfma_f32_16x16x32_bf16 v[52:55], v[226:229], v[174:177], v[52:55]
	v_mfma_f32_16x16x32_bf16 v[48:51], v[234:237], v[174:177], v[48:51]
	v_mfma_f32_16x16x32_bf16 v[36:39], v[226:229], v[182:185], v[36:39]
	v_mfma_f32_16x16x32_bf16 v[32:35], v[234:237], v[182:185], v[32:35]
	v_mfma_f32_16x16x32_bf16 v[20:23], v[226:229], v[206:209], v[20:23]
	v_mfma_f32_16x16x32_bf16 v[16:19], v[234:237], v[206:209], v[16:19]
	v_mfma_f32_16x16x32_bf16 v[4:7], v[226:229], v[218:221], v[4:7]
	v_mfma_f32_16x16x32_bf16 v[0:3], v[234:237], v[218:221], v[0:3]
	v_mfma_f32_16x16x32_bf16 v[52:55], v[230:233], v[178:181], v[52:55]
	v_mfma_f32_16x16x32_bf16 v[48:51], v[238:241], v[178:181], v[48:51]
	v_mfma_f32_16x16x32_bf16 v[36:39], v[230:233], v[186:189], v[36:39]
	v_mfma_f32_16x16x32_bf16 v[32:35], v[238:241], v[186:189], v[32:35]
	v_mfma_f32_16x16x32_bf16 v[20:23], v[230:233], v[214:217], v[20:23]
	v_mfma_f32_16x16x32_bf16 v[16:19], v[238:241], v[214:217], v[16:19]
	v_mfma_f32_16x16x32_bf16 v[4:7], v[230:233], v[222:225], v[4:7]
	v_mfma_f32_16x16x32_bf16 v[0:3], v[238:241], v[222:225], v[0:3]
	s_setprio 0
	s_add_u32 s10, s10, 0x100
	s_addc_u32 s40, s40, 0
	s_add_u32 s6, s6, 0x100
	s_addc_u32 s7, s7, 0
	s_cmp_ge_i32 s41, s66
	s_mov_b32 s2, s41
	s_barrier
	s_cbranch_scc1 .Lpost_197

.Lpost_197:
.LBB0_198:
	s_cmp_lt_i32 s25, 2
	s_cselect_b64 s[38:39], -1, 0
	s_and_b64 s[2:3], s[84:85], s[38:39]
	s_and_b64 vcc, exec, s[2:3]
	s_cbranch_vccnz .LBB0_190
	s_lshl_b32 s73, s24, 8
	v_readlane_b32 s2, v255, 21
	s_add_i32 s73, s73, s2
	s_lshl_b32 s2, s25, 1
	s_and_b32 s25, s2, 2
	v_readlane_b32 s2, v255, 22
	v_readlane_b32 s3, v255, 23
	s_add_i32 s6, s73, 0xffff8000
	s_nor_b64 s[2:3], s[38:39], s[2:3]
	s_ashr_i32 s10, s73, 12
	s_ashr_i32 s21, s6, 8
	s_cmpk_gt_i32 s24, 0x7f
	s_mov_b64 s[12:13], s[28:29]
	s_mov_b64 s[28:29], s[92:93]
	s_mov_b64 s[92:93], s[60:61]
	s_cselect_b64 s[40:41], -1, 0
	s_and_b64 s[6:7], s[40:41], exec
	v_bitop3_b32 v140, s73, v201, v149 bitop3:0xc8
	s_cselect_b32 s6, s21, s10
	v_or_b32_e32 v140, 0x1000, v140
	v_bitop3_b32 v142, s73, v202, v149 bitop3:0xc8
	s_lshl_b32 s60, s6, 2
	v_cndmask_b32_e64 v156, v142, v140, s[40:41]
	s_or_b32 s6, s60, s25
	s_ashr_i32 s7, s6, 31
	s_mov_b64 s[42:43], -1
	s_and_b64 vcc, exec, s[2:3]
	v_lshlrev_b32_e32 v144, 1, v156
	s_cbranch_vccz .LBB0_201
	s_lshl_b64 s[42:43], s[6:7], 6
	v_lshl_add_u64 v[142:143], s[42:43], 0, v[134:135]
	v_mov_b64_e32 v[162:163], s[48:49]
	v_mad_u64_u32 v[162:163], s[42:43], v142, s77, v[162:163]
	v_mad_i32_i24 v163, v143, s77, v163
	v_mov_b32_e32 v145, v157
	v_lshl_add_u64 v[142:143], v[162:163], 0, v[144:145]
	s_movk_i32 s10, 0x2000
	v_add_co_u32_e32 v162, vcc, s10, v142
	v_cvt_pk_bf16_f32 v140, v124, v157
	s_movk_i32 s10, 0x4000
	s_nop 0
	v_addc_co_u32_e32 v163, vcc, 0, v143, vcc
	global_store_short v[142:143], v140, off
	v_cvt_pk_bf16_f32 v140, v125, v157
	global_store_short v[162:163], v140, off offset:512
	v_add_co_u32_e32 v162, vcc, s10, v142
	s_movk_i32 s10, 0x6000
	s_nop 0
	v_addc_co_u32_e32 v163, vcc, 0, v143, vcc
	v_cvt_pk_bf16_f32 v140, v126, v157
	global_store_short v[162:163], v140, off offset:1024
	v_add_co_u32_e32 v162, vcc, s10, v142
	s_mov_b32 s10, 0x22000
	s_nop 0
	v_addc_co_u32_e32 v163, vcc, 0, v143, vcc
	v_cvt_pk_bf16_f32 v140, v127, v157
	global_store_short v[162:163], v140, off offset:1536
	v_add_co_u32_e32 v162, vcc, s10, v142
	s_mov_b32 s10, 0x24000
	s_nop 0
	v_addc_co_u32_e32 v163, vcc, 0, v143, vcc
	v_cvt_pk_bf16_f32 v140, v120, v157
	global_store_short v[162:163], v140, off
	v_add_co_u32_e32 v162, vcc, s10, v142
	v_cvt_pk_bf16_f32 v140, v121, v157
	s_mov_b64 s[42:43], 0
	s_nop 0
	v_addc_co_u32_e32 v163, vcc, 0, v143, vcc
	global_store_short v[162:163], v140, off offset:512
	v_add_co_u32_e32 v162, vcc, 0x26000, v142
	v_cvt_pk_bf16_f32 v140, v122, v157
	s_nop 1
	v_addc_co_u32_e32 v163, vcc, 0, v143, vcc
	v_add_co_u32_e32 v142, vcc, 0x28000, v142
	global_store_short v[162:163], v140, off offset:1024
	s_nop 0
	v_addc_co_u32_e32 v143, vcc, 0, v143, vcc
	v_cvt_pk_bf16_f32 v140, v123, v157
	global_store_short v[142:143], v140, off offset:1536

.LBB0_270:
	v_lshl_add_u64 v[0:1], s[40:41], 0, v[156:157]
	v_mov_b32_e32 v129, v157
	v_lshl_add_u64 v[4:5], s[2:3], 0, v[156:157]
	v_lshl_add_u64 v[6:7], s[2:3], 0, v[128:129]
	s_lshl_b32 s2, s19, 5
	s_add_i32 m0, s25, 0x18000
	v_lshl_add_u64 v[0:1], v[0:1], 0, s[50:51]
	s_and_b32 s19, s2, 0x60
	s_waitcnt vmcnt(4)
	s_barrier
	global_load_lds_dwordx4 v[0:1], off
	s_add_i32 m0, s25, 0x1a000
	v_lshl_add_u64 v[2:3], s[40:41], 0, v[128:129]
	s_add_u32 s2, s26, 0x1a4a4080
	v_lshl_add_u64 v[0:1], v[2:3], 0, s[50:51]
	s_addc_u32 s3, s27, 0
	s_add_i32 s45, s25, 0x8000
	global_load_lds_dwordx4 v[0:1], off
	v_lshl_add_u64 v[0:1], s[2:3], 0, v[156:157]
	s_mov_b32 m0, s45
	s_add_i32 s48, s25, 0xa000
	global_load_lds_dwordx4 v[0:1], off
	v_lshl_add_u64 v[0:1], s[2:3], 0, v[128:129]
	s_mov_b32 m0, s48
	v_mov_b32_e32 v127, 0
	global_load_lds_dwordx4 v[0:1], off
	s_add_i32 m0, s25, 0x1c000
	v_lshl_add_u64 v[0:1], v[4:5], 0, s[50:51]
	global_load_lds_dwordx4 v[0:1], off
	v_lshl_add_u64 v[0:1], v[6:7], 0, s[50:51]
	s_add_i32 m0, s25, 0x1e000
	v_lshl_or_b32 v134, s42, 6, v149
	global_load_lds_dwordx4 v[0:1], off
	s_waitcnt vmcnt(6)
	s_cmp_lt_i32 s6, 64
	v_mov_b32_e32 v126, v127
	v_mov_b32_e32 v125, v127
	v_mov_b32_e32 v124, v127
	v_mov_b32_e32 v123, v127
	v_mov_b32_e32 v122, v127
	v_mov_b32_e32 v121, v127
	v_mov_b32_e32 v120, v127
	v_mov_b32_e32 v111, v127
	v_mov_b32_e32 v110, v127
	v_mov_b32_e32 v109, v127
	v_mov_b32_e32 v108, v127
	v_mov_b32_e32 v107, v127
	v_mov_b32_e32 v106, v127
	v_mov_b32_e32 v105, v127
	v_mov_b32_e32 v104, v127
	v_mov_b32_e32 v95, v127
	v_mov_b32_e32 v94, v127
	v_mov_b32_e32 v93, v127
	v_mov_b32_e32 v92, v127
	v_mov_b32_e32 v91, v127
	v_mov_b32_e32 v90, v127
	v_mov_b32_e32 v89, v127
	v_mov_b32_e32 v88, v127
	v_mov_b32_e32 v79, v127
	v_mov_b32_e32 v78, v127
	v_mov_b32_e32 v77, v127
	v_mov_b32_e32 v76, v127
	v_mov_b32_e32 v75, v127
	v_mov_b32_e32 v74, v127
	v_mov_b32_e32 v73, v127
	v_mov_b32_e32 v72, v127
	v_mov_b32_e32 v119, v127
	v_mov_b32_e32 v118, v127
	v_mov_b32_e32 v117, v127
	v_mov_b32_e32 v116, v127
	v_mov_b32_e32 v115, v127
	v_mov_b32_e32 v114, v127
	v_mov_b32_e32 v113, v127
	v_mov_b32_e32 v112, v127
	v_mov_b32_e32 v103, v127
	v_mov_b32_e32 v102, v127
	v_mov_b32_e32 v101, v127
	v_mov_b32_e32 v100, v127
	v_mov_b32_e32 v99, v127
	v_mov_b32_e32 v98, v127
	v_mov_b32_e32 v97, v127
	v_mov_b32_e32 v96, v127
	v_mov_b32_e32 v87, v127
	v_mov_b32_e32 v86, v127
	v_mov_b32_e32 v85, v127
	v_mov_b32_e32 v84, v127
	v_mov_b32_e32 v83, v127
	v_mov_b32_e32 v82, v127
	v_mov_b32_e32 v81, v127
	v_mov_b32_e32 v80, v127
	v_mov_b32_e32 v71, v127
	v_mov_b32_e32 v70, v127
	v_mov_b32_e32 v69, v127
	v_mov_b32_e32 v68, v127
	v_mov_b32_e32 v67, v127
	v_mov_b32_e32 v66, v127
	v_mov_b32_e32 v65, v127
	v_mov_b32_e32 v64, v127
	v_mov_b32_e32 v63, v127
	v_mov_b32_e32 v62, v127
	v_mov_b32_e32 v61, v127
	v_mov_b32_e32 v60, v127
	v_mov_b32_e32 v59, v127
	v_mov_b32_e32 v58, v127
	v_mov_b32_e32 v57, v127
	v_mov_b32_e32 v56, v127
	v_mov_b32_e32 v47, v127
	v_mov_b32_e32 v46, v127
	v_mov_b32_e32 v45, v127
	v_mov_b32_e32 v44, v127
	v_mov_b32_e32 v43, v127
	v_mov_b32_e32 v42, v127
	v_mov_b32_e32 v41, v127
	v_mov_b32_e32 v40, v127
	v_mov_b32_e32 v31, v127
	v_mov_b32_e32 v30, v127
	v_mov_b32_e32 v29, v127
	v_mov_b32_e32 v28, v127
	v_mov_b32_e32 v27, v127
	v_mov_b32_e32 v26, v127
	v_mov_b32_e32 v25, v127
	v_mov_b32_e32 v24, v127
	v_mov_b32_e32 v15, v127
	v_mov_b32_e32 v14, v127
	v_mov_b32_e32 v13, v127
	v_mov_b32_e32 v12, v127
	v_mov_b32_e32 v11, v127
	v_mov_b32_e32 v10, v127
	v_mov_b32_e32 v9, v127
	v_mov_b32_e32 v8, v127
	v_mov_b32_e32 v55, v127
	v_mov_b32_e32 v54, v127
	v_mov_b32_e32 v53, v127
	v_mov_b32_e32 v52, v127
	v_mov_b32_e32 v51, v127
	v_mov_b32_e32 v50, v127
	v_mov_b32_e32 v49, v127
	v_mov_b32_e32 v48, v127
	v_mov_b32_e32 v39, v127
	v_mov_b32_e32 v38, v127
	v_mov_b32_e32 v37, v127
	v_mov_b32_e32 v36, v127
	v_mov_b32_e32 v35, v127
	v_mov_b32_e32 v34, v127
	v_mov_b32_e32 v33, v127
	v_mov_b32_e32 v32, v127
	v_mov_b32_e32 v23, v127
	v_mov_b32_e32 v22, v127
	v_mov_b32_e32 v21, v127
	v_mov_b32_e32 v20, v127
	v_mov_b32_e32 v19, v127
	v_mov_b32_e32 v18, v127
	v_mov_b32_e32 v17, v127
	v_mov_b32_e32 v16, v127
	v_mov_b32_e32 v7, v127
	v_mov_b32_e32 v6, v127
	v_mov_b32_e32 v5, v127
	v_mov_b32_e32 v4, v127
	v_mov_b32_e32 v3, v127
	v_mov_b32_e32 v2, v127
	v_mov_b32_e32 v1, v127
	v_mov_b32_e32 v0, v127
	s_barrier
	s_cbranch_scc1 .LBB0_273
	s_lshr_b32 s2, s7, 26
	s_add_i32 s2, s6, s2
	s_ashr_i32 s49, s2, 6
	v_lshlrev_b32_e32 v0, 6, v134
	s_movk_i32 s2, 0x3c0
	v_lshlrev_b32_e32 v1, 2, v134
	s_add_i32 s53, s49, -2
	v_and_or_b32 v0, v0, s2, v147
	s_lshl_b32 s2, s42, 13
	v_and_b32_e32 v1, 32, v1
	v_bitop3_b32 v2, v0, s2, v1 bitop3:0xde
	s_add_u32 s2, s26, s36
	v_add_u32_e32 v0, v132, v133
	s_addc_u32 s3, s27, s37
	v_add_lshl_u32 v0, v0, v146, 1
	v_mov_b32_e32 v1, v157
	v_lshl_add_u64 v[132:133], s[2:3], 0, v[0:1]
	v_lshl_or_b32 v135, s19, 7, v148
	v_lshl_add_u64 v[130:131], s[2:3], 0, v[128:129]
	s_mov_b32 s2, 0
	s_mov_b64 s[6:7], 0x1a4a4080
	v_add_u32_e32 v136, 0, v2
	s_add_i32 s54, s2, 2
	s_add_u32 s3, s6, 0xe5b5c080
	s_addc_u32 s21, s7, -1
	s_cmp_lg_u32 s53, s2
	s_cselect_b32 s42, s3, 0
	s_cselect_b32 s21, s21, 0
	s_add_u32 s2, s38, s42
	s_addc_u32 s3, s39, s21
	s_add_i32 s55, 0, 0x10000
	v_add_u32_e32 v137, s55, v135
	ds_read_b128 v[142:145], v137
	ds_read_b128 v[146:149], v137 offset:1024
	ds_read_b128 v[150:153], v137 offset:2048
	ds_read_b128 v[162:165], v137 offset:3072
	s_add_u32 s42, s40, s42
	s_addc_u32 s43, s41, s21
	v_lshl_add_u64 v[138:139], v[132:133], 0, s[6:7]
	s_add_i32 m0, s25, 0xc000
	ds_read_b128 v[166:169], v136
	ds_read_b128 v[170:173], v136 offset:1024
	ds_read_b128 v[174:177], v136 offset:2048
	ds_read_b128 v[178:181], v136 offset:3072
	ds_read_b128 v[182:185], v136 offset:4096
	ds_read_b128 v[186:189], v136 offset:5120
	ds_read_b128 v[206:209], v136 offset:6144
	ds_read_b128 v[214:217], v136 offset:7168
	global_load_lds_dwordx4 v[138:139], off
	v_lshl_add_u64 v[138:139], v[130:131], 0, s[6:7]
	s_add_i32 m0, s25, 0xe000
	s_nop 0
	global_load_lds_dwordx4 v[138:139], off
	s_waitcnt lgkmcnt(8)
	s_barrier
	s_waitcnt lgkmcnt(0)
	s_setprio 1
	s_waitcnt lgkmcnt(0)
	v_mfma_f32_16x16x32_bf16 v[124:127], v[142:145], v[166:169], 0
	v_mfma_f32_16x16x32_bf16 v[120:123], v[150:153], v[166:169], 0
	v_mfma_f32_16x16x32_bf16 v[108:111], v[142:145], v[174:177], 0
	v_mfma_f32_16x16x32_bf16 v[104:107], v[150:153], v[174:177], 0
	v_mfma_f32_16x16x32_bf16 v[92:95], v[142:145], v[182:185], 0
	v_mfma_f32_16x16x32_bf16 v[88:91], v[150:153], v[182:185], 0
	v_mfma_f32_16x16x32_bf16 v[76:79], v[142:145], v[206:209], 0
	v_mfma_f32_16x16x32_bf16 v[72:75], v[150:153], v[206:209], 0
	v_mfma_f32_16x16x32_bf16 v[124:127], v[146:149], v[170:173], v[124:127]
	v_mfma_f32_16x16x32_bf16 v[120:123], v[162:165], v[170:173], v[120:123]
	v_mfma_f32_16x16x32_bf16 v[108:111], v[146:149], v[178:181], v[108:111]
	v_mfma_f32_16x16x32_bf16 v[104:107], v[162:165], v[178:181], v[104:107]
	v_mfma_f32_16x16x32_bf16 v[92:95], v[146:149], v[186:189], v[92:95]
	v_mfma_f32_16x16x32_bf16 v[88:91], v[162:165], v[186:189], v[88:91]
	v_mfma_f32_16x16x32_bf16 v[76:79], v[146:149], v[214:217], v[76:79]
	v_mfma_f32_16x16x32_bf16 v[72:75], v[162:165], v[214:217], v[72:75]
	s_setprio 0
	s_barrier
	s_add_i32 s21, 0, 0x14000
	s_add_i32 s55, s55, s24
	v_add_u32_e32 v137, s21, v135
	v_lshl_add_u64 v[138:139], s[42:43], 0, v[156:157]
	s_mov_b32 m0, s55
	ds_read_b128 v[218:221], v137
	ds_read_b128 v[222:225], v137 offset:1024
	ds_read_b128 v[226:229], v137 offset:2048
	ds_read_b128 v[230:233], v137 offset:3072
	global_load_lds_dwordx4 v[138:139], off
	v_lshl_add_u64 v[154:155], s[42:43], 0, v[128:129]
	s_add_i32 m0, s55, 0x2000
	s_nop 0
	global_load_lds_dwordx4 v[154:155], off
	s_barrier
	s_waitcnt lgkmcnt(0)
	s_setprio 1
	s_waitcnt lgkmcnt(0)
	v_mfma_f32_16x16x32_bf16 v[116:119], v[218:221], v[166:169], 0
	v_mfma_f32_16x16x32_bf16 v[112:115], v[226:229], v[166:169], 0
	v_mfma_f32_16x16x32_bf16 v[100:103], v[218:221], v[174:177], 0
	v_mfma_f32_16x16x32_bf16 v[96:99], v[226:229], v[174:177], 0
	v_mfma_f32_16x16x32_bf16 v[84:87], v[218:221], v[182:185], 0
	v_mfma_f32_16x16x32_bf16 v[80:83], v[226:229], v[182:185], 0
	v_mfma_f32_16x16x32_bf16 v[68:71], v[218:221], v[206:209], 0
	v_mfma_f32_16x16x32_bf16 v[64:67], v[226:229], v[206:209], 0
	v_mfma_f32_16x16x32_bf16 v[116:119], v[222:225], v[170:173], v[116:119]
	v_mfma_f32_16x16x32_bf16 v[112:115], v[230:233], v[170:173], v[112:115]
	v_mfma_f32_16x16x32_bf16 v[100:103], v[222:225], v[178:181], v[100:103]
	v_mfma_f32_16x16x32_bf16 v[96:99], v[230:233], v[178:181], v[96:99]
	v_mfma_f32_16x16x32_bf16 v[84:87], v[222:225], v[186:189], v[84:87]
	v_mfma_f32_16x16x32_bf16 v[80:83], v[230:233], v[186:189], v[80:83]
	v_mfma_f32_16x16x32_bf16 v[68:71], v[222:225], v[214:217], v[68:71]
	v_mfma_f32_16x16x32_bf16 v[64:67], v[230:233], v[214:217], v[64:67]
	s_setprio 0
	s_mov_b32 m0, s25
	v_lshl_add_u64 v[234:235], s[2:3], 0, v[156:157]
	s_barrier
	ds_read_b128 v[166:169], v136 offset:16384
	ds_read_b128 v[170:173], v136 offset:17408
	ds_read_b128 v[174:177], v136 offset:18432
	ds_read_b128 v[178:181], v136 offset:19456
	ds_read_b128 v[182:185], v136 offset:20480
	ds_read_b128 v[186:189], v136 offset:21504
	ds_read_b128 v[206:209], v136 offset:22528
	ds_read_b128 v[214:217], v136 offset:23552
	global_load_lds_dwordx4 v[234:235], off
	v_lshl_add_u64 v[236:237], s[2:3], 0, v[128:129]
	s_mov_b32 m0, s34
	s_nop 0
	global_load_lds_dwordx4 v[236:237], off
	s_barrier
	s_waitcnt lgkmcnt(0)
	s_setprio 1
	s_waitcnt lgkmcnt(0)
	v_mfma_f32_16x16x32_bf16 v[60:63], v[142:145], v[166:169], 0
	v_mfma_f32_16x16x32_bf16 v[56:59], v[150:153], v[166:169], 0
	v_mfma_f32_16x16x32_bf16 v[44:47], v[142:145], v[174:177], 0
	v_mfma_f32_16x16x32_bf16 v[40:43], v[150:153], v[174:177], 0
	v_mfma_f32_16x16x32_bf16 v[28:31], v[142:145], v[182:185], 0
	v_mfma_f32_16x16x32_bf16 v[24:27], v[150:153], v[182:185], 0
	v_mfma_f32_16x16x32_bf16 v[12:15], v[142:145], v[206:209], 0
	v_mfma_f32_16x16x32_bf16 v[8:11], v[150:153], v[206:209], 0
	v_mfma_f32_16x16x32_bf16 v[60:63], v[146:149], v[170:173], v[60:63]
	v_mfma_f32_16x16x32_bf16 v[56:59], v[162:165], v[170:173], v[56:59]
	v_mfma_f32_16x16x32_bf16 v[44:47], v[146:149], v[178:181], v[44:47]
	v_mfma_f32_16x16x32_bf16 v[40:43], v[162:165], v[178:181], v[40:43]
	v_mfma_f32_16x16x32_bf16 v[28:31], v[146:149], v[186:189], v[28:31]
	v_mfma_f32_16x16x32_bf16 v[24:27], v[162:165], v[186:189], v[24:27]
	v_mfma_f32_16x16x32_bf16 v[12:15], v[146:149], v[214:217], v[12:15]
	v_mfma_f32_16x16x32_bf16 v[8:11], v[162:165], v[214:217], v[8:11]
	s_setprio 0
	s_barrier
	s_add_u32 s42, s42, s36
	s_addc_u32 s43, s43, s37
	s_add_i32 s21, s21, s24
	v_lshl_add_u64 v[238:239], s[42:43], 0, v[156:157]
	s_mov_b32 m0, s21
	v_lshl_add_u64 v[240:241], s[42:43], 0, v[128:129]
	global_load_lds_dwordx4 v[238:239], off
	s_add_i32 m0, s21, 0x2000
	s_nop 0
	global_load_lds_dwordx4 v[240:241], off
	s_waitcnt vmcnt(6)
	s_barrier
	s_setprio 1
	v_mfma_f32_16x16x32_bf16 v[52:55], v[218:221], v[166:169], 0
	v_mfma_f32_16x16x32_bf16 v[48:51], v[226:229], v[166:169], 0
	v_mfma_f32_16x16x32_bf16 v[36:39], v[218:221], v[174:177], 0
	v_mfma_f32_16x16x32_bf16 v[32:35], v[226:229], v[174:177], 0
	v_mfma_f32_16x16x32_bf16 v[20:23], v[218:221], v[182:185], 0
	v_mfma_f32_16x16x32_bf16 v[16:19], v[226:229], v[182:185], 0
	v_mfma_f32_16x16x32_bf16 v[4:7], v[218:221], v[206:209], 0
	v_mfma_f32_16x16x32_bf16 v[0:3], v[226:229], v[206:209], 0
	v_mfma_f32_16x16x32_bf16 v[52:55], v[222:225], v[170:173], v[52:55]
	v_mfma_f32_16x16x32_bf16 v[48:51], v[230:233], v[170:173], v[48:51]
	v_mfma_f32_16x16x32_bf16 v[36:39], v[222:225], v[178:181], v[36:39]
	v_mfma_f32_16x16x32_bf16 v[32:35], v[230:233], v[178:181], v[32:35]
	v_mfma_f32_16x16x32_bf16 v[20:23], v[222:225], v[186:189], v[20:23]
	v_mfma_f32_16x16x32_bf16 v[16:19], v[230:233], v[186:189], v[16:19]
	v_mfma_f32_16x16x32_bf16 v[4:7], v[222:225], v[214:217], v[4:7]
	v_mfma_f32_16x16x32_bf16 v[0:3], v[230:233], v[214:217], v[0:3]
	s_setprio 0
	s_add_i32 s21, 0, 0x18000
	v_add_u32_e32 v137, s21, v135
	s_barrier
	ds_read_b128 v[142:145], v137
	ds_read_b128 v[146:149], v137 offset:1024
	ds_read_b128 v[150:153], v137 offset:2048
	ds_read_b128 v[162:165], v137 offset:3072
	s_add_u32 s2, s2, s36
	s_addc_u32 s3, s3, s37
	s_mov_b32 m0, s35
	v_lshl_add_u64 v[218:219], s[2:3], 0, v[156:157]
	ds_read_b128 v[166:169], v136 offset:32768
	ds_read_b128 v[170:173], v136 offset:33792
	ds_read_b128 v[174:177], v136 offset:34816
	ds_read_b128 v[178:181], v136 offset:35840
	ds_read_b128 v[182:185], v136 offset:36864
	ds_read_b128 v[186:189], v136 offset:37888
	ds_read_b128 v[206:209], v136 offset:38912
	ds_read_b128 v[214:217], v136 offset:39936
	global_load_lds_dwordx4 v[218:219], off
	v_lshl_add_u64 v[218:219], s[2:3], 0, v[128:129]
	s_mov_b32 m0, s44
	s_nop 0
	global_load_lds_dwordx4 v[218:219], off
	s_waitcnt lgkmcnt(8)
	s_barrier
	s_waitcnt lgkmcnt(0)
	s_setprio 1
	s_waitcnt lgkmcnt(0)
	v_mfma_f32_16x16x32_bf16 v[124:127], v[142:145], v[166:169], v[124:127]
	v_mfma_f32_16x16x32_bf16 v[120:123], v[150:153], v[166:169], v[120:123]
	v_mfma_f32_16x16x32_bf16 v[108:111], v[142:145], v[174:177], v[108:111]
	v_mfma_f32_16x16x32_bf16 v[104:107], v[150:153], v[174:177], v[104:107]
	v_mfma_f32_16x16x32_bf16 v[92:95], v[142:145], v[182:185], v[92:95]
	v_mfma_f32_16x16x32_bf16 v[88:91], v[150:153], v[182:185], v[88:91]
	v_mfma_f32_16x16x32_bf16 v[76:79], v[142:145], v[206:209], v[76:79]
	v_mfma_f32_16x16x32_bf16 v[72:75], v[150:153], v[206:209], v[72:75]
	v_mfma_f32_16x16x32_bf16 v[124:127], v[146:149], v[170:173], v[124:127]
	v_mfma_f32_16x16x32_bf16 v[120:123], v[162:165], v[170:173], v[120:123]
	v_mfma_f32_16x16x32_bf16 v[108:111], v[146:149], v[178:181], v[108:111]
	v_mfma_f32_16x16x32_bf16 v[104:107], v[162:165], v[178:181], v[104:107]
	v_mfma_f32_16x16x32_bf16 v[92:95], v[146:149], v[186:189], v[92:95]
	v_mfma_f32_16x16x32_bf16 v[88:91], v[162:165], v[186:189], v[88:91]
	v_mfma_f32_16x16x32_bf16 v[76:79], v[146:149], v[214:217], v[76:79]
	v_mfma_f32_16x16x32_bf16 v[72:75], v[162:165], v[214:217], v[72:75]
	s_setprio 0
	s_barrier
	s_add_i32 s2, 0, 0x1c000
	s_add_i32 s3, s21, s24
	v_add_u32_e32 v137, s2, v135
	v_lshl_add_u64 v[138:139], v[138:139], 0, s[50:51]
	s_mov_b32 m0, s3
	ds_read_b128 v[218:221], v137
	ds_read_b128 v[222:225], v137 offset:1024
	ds_read_b128 v[226:229], v137 offset:2048
	ds_read_b128 v[230:233], v137 offset:3072
	global_load_lds_dwordx4 v[138:139], off
	v_lshl_add_u64 v[138:139], v[154:155], 0, s[50:51]
	s_add_i32 m0, s3, 0x2000
	s_nop 0
	global_load_lds_dwordx4 v[138:139], off
	s_barrier
	s_waitcnt lgkmcnt(0)
	s_setprio 1
	s_waitcnt lgkmcnt(0)
	v_mfma_f32_16x16x32_bf16 v[116:119], v[218:221], v[166:169], v[116:119]
	v_mfma_f32_16x16x32_bf16 v[112:115], v[226:229], v[166:169], v[112:115]
	v_mfma_f32_16x16x32_bf16 v[100:103], v[218:221], v[174:177], v[100:103]
	v_mfma_f32_16x16x32_bf16 v[96:99], v[226:229], v[174:177], v[96:99]
	v_mfma_f32_16x16x32_bf16 v[84:87], v[218:221], v[182:185], v[84:87]
	v_mfma_f32_16x16x32_bf16 v[80:83], v[226:229], v[182:185], v[80:83]
	v_mfma_f32_16x16x32_bf16 v[68:71], v[218:221], v[206:209], v[68:71]
	v_mfma_f32_16x16x32_bf16 v[64:67], v[226:229], v[206:209], v[64:67]
	v_mfma_f32_16x16x32_bf16 v[116:119], v[222:225], v[170:173], v[116:119]
	v_mfma_f32_16x16x32_bf16 v[112:115], v[230:233], v[170:173], v[112:115]
	v_mfma_f32_16x16x32_bf16 v[100:103], v[222:225], v[178:181], v[100:103]
	v_mfma_f32_16x16x32_bf16 v[96:99], v[230:233], v[178:181], v[96:99]
	v_mfma_f32_16x16x32_bf16 v[84:87], v[222:225], v[186:189], v[84:87]
	v_mfma_f32_16x16x32_bf16 v[80:83], v[230:233], v[186:189], v[80:83]
	v_mfma_f32_16x16x32_bf16 v[68:71], v[222:225], v[214:217], v[68:71]
	v_mfma_f32_16x16x32_bf16 v[64:67], v[230:233], v[214:217], v[64:67]
	s_setprio 0
	s_mov_b32 m0, s45
	v_lshl_add_u64 v[138:139], v[234:235], 0, s[50:51]
	s_barrier
	ds_read_b128 v[166:169], v136 offset:49152
	ds_read_b128 v[170:173], v136 offset:50176
	ds_read_b128 v[174:177], v136 offset:51200
	ds_read_b128 v[178:181], v136 offset:52224
	ds_read_b128 v[182:185], v136 offset:53248
	ds_read_b128 v[186:189], v136 offset:54272
	ds_read_b128 v[206:209], v136 offset:55296
	ds_read_b128 v[214:217], v136 offset:56320
	global_load_lds_dwordx4 v[138:139], off
	v_lshl_add_u64 v[138:139], v[236:237], 0, s[50:51]
	s_mov_b32 m0, s48
	s_nop 0
	global_load_lds_dwordx4 v[138:139], off
	s_barrier
	s_waitcnt lgkmcnt(0)
	s_setprio 1
	s_waitcnt lgkmcnt(0)
	v_mfma_f32_16x16x32_bf16 v[60:63], v[142:145], v[166:169], v[60:63]
	v_mfma_f32_16x16x32_bf16 v[56:59], v[150:153], v[166:169], v[56:59]
	v_mfma_f32_16x16x32_bf16 v[44:47], v[142:145], v[174:177], v[44:47]
	v_mfma_f32_16x16x32_bf16 v[40:43], v[150:153], v[174:177], v[40:43]
	v_mfma_f32_16x16x32_bf16 v[28:31], v[142:145], v[182:185], v[28:31]
	v_mfma_f32_16x16x32_bf16 v[24:27], v[150:153], v[182:185], v[24:27]
	v_mfma_f32_16x16x32_bf16 v[12:15], v[142:145], v[206:209], v[12:15]
	v_mfma_f32_16x16x32_bf16 v[8:11], v[150:153], v[206:209], v[8:11]
	v_mfma_f32_16x16x32_bf16 v[60:63], v[146:149], v[170:173], v[60:63]
	v_mfma_f32_16x16x32_bf16 v[56:59], v[162:165], v[170:173], v[56:59]
	v_mfma_f32_16x16x32_bf16 v[44:47], v[146:149], v[178:181], v[44:47]
	v_mfma_f32_16x16x32_bf16 v[40:43], v[162:165], v[178:181], v[40:43]
	v_mfma_f32_16x16x32_bf16 v[28:31], v[146:149], v[186:189], v[28:31]
	v_mfma_f32_16x16x32_bf16 v[24:27], v[162:165], v[186:189], v[24:27]
	v_mfma_f32_16x16x32_bf16 v[12:15], v[146:149], v[214:217], v[12:15]
	v_mfma_f32_16x16x32_bf16 v[8:11], v[162:165], v[214:217], v[8:11]
	s_setprio 0
	s_barrier
	s_add_i32 s2, s2, s24
	v_lshl_add_u64 v[138:139], v[238:239], 0, s[50:51]
	s_mov_b32 m0, s2
	s_nop 0
	global_load_lds_dwordx4 v[138:139], off
	v_lshl_add_u64 v[138:139], v[240:241], 0, s[50:51]
	s_add_i32 m0, s2, 0x2000
	s_nop 0
	global_load_lds_dwordx4 v[138:139], off
	s_waitcnt vmcnt(6)
	s_barrier
	s_setprio 1
	v_mfma_f32_16x16x32_bf16 v[52:55], v[218:221], v[166:169], v[52:55]
	v_mfma_f32_16x16x32_bf16 v[48:51], v[226:229], v[166:169], v[48:51]
	v_mfma_f32_16x16x32_bf16 v[36:39], v[218:221], v[174:177], v[36:39]
	v_mfma_f32_16x16x32_bf16 v[32:35], v[226:229], v[174:177], v[32:35]
	v_mfma_f32_16x16x32_bf16 v[20:23], v[218:221], v[182:185], v[20:23]
	v_mfma_f32_16x16x32_bf16 v[16:19], v[226:229], v[182:185], v[16:19]
	v_mfma_f32_16x16x32_bf16 v[4:7], v[218:221], v[206:209], v[4:7]
	v_mfma_f32_16x16x32_bf16 v[0:3], v[226:229], v[206:209], v[0:3]
	v_mfma_f32_16x16x32_bf16 v[52:55], v[222:225], v[170:173], v[52:55]
	v_mfma_f32_16x16x32_bf16 v[48:51], v[230:233], v[170:173], v[48:51]
	v_mfma_f32_16x16x32_bf16 v[36:39], v[222:225], v[178:181], v[36:39]
	v_mfma_f32_16x16x32_bf16 v[32:35], v[230:233], v[178:181], v[32:35]
	v_mfma_f32_16x16x32_bf16 v[20:23], v[222:225], v[186:189], v[20:23]
	v_mfma_f32_16x16x32_bf16 v[16:19], v[230:233], v[186:189], v[16:19]
	v_mfma_f32_16x16x32_bf16 v[4:7], v[222:225], v[214:217], v[4:7]
	v_mfma_f32_16x16x32_bf16 v[0:3], v[230:233], v[214:217], v[0:3]
	s_setprio 0
	s_add_u32 s6, s6, 0x100
	s_addc_u32 s7, s7, 0
	s_cmp_ge_i32 s54, s49
	s_mov_b32 s2, s54
	s_barrier
	s_cbranch_scc1 .Lpost_272

.Lpost_272:
.LBB0_273:
	s_lshl_b32 s2, s19, 1
	s_add_u32 s2, s58, s2
	v_lshl_add_u32 v130, s10, 8, v134
	s_addc_u32 s3, s59, 0
	v_lshlrev_b32_e32 v156, 3, v141
	v_ashrrev_i32_e32 v131, 31, v130
	v_lshl_add_u64 v[128:129], s[2:3], 0, v[156:157]
	v_lshlrev_b64 v[130:131], 11, v[130:131]
	v_lshl_add_u64 v[128:129], v[128:129], 0, v[130:131]
	s_mov_b64 s[2:3], 0x4000000
	v_lshl_add_u64 v[130:131], v[128:129], 0, s[2:3]
	s_brev_b32 s2, 32
	v_cvt_pk_bf16_f32 v124, v124, v125
	v_cvt_pk_bf16_f32 v125, v126, v127
	v_add_co_u32_e32 v126, vcc, s2, v128
	s_mov_b64 s[2:3], 0x4008000
	s_nop 0
	v_addc_co_u32_e32 v127, vcc, 0, v129, vcc
	global_store_dwordx2 v[126:127], v[124:125], off
	v_cvt_pk_bf16_f32 v120, v120, v121
	v_cvt_pk_bf16_f32 v121, v122, v123
	global_store_dwordx2 v[130:131], v[120:121], off offset:32
	v_cvt_pk_bf16_f32 v116, v116, v117
	v_cvt_pk_bf16_f32 v117, v118, v119
	global_store_dwordx2 v[130:131], v[116:117], off offset:256
	v_cvt_pk_bf16_f32 v112, v112, v113
	v_cvt_pk_bf16_f32 v113, v114, v115
	global_store_dwordx2 v[130:131], v[112:113], off offset:288
	v_lshl_add_u64 v[112:113], v[128:129], 0, s[2:3]
	s_mov_b32 s2, 0x4008000
	v_cvt_pk_bf16_f32 v108, v108, v109
	v_cvt_pk_bf16_f32 v109, v110, v111
	v_add_co_u32_e32 v110, vcc, s2, v128
	s_mov_b64 s[2:3], 0x4010000
	s_nop 0
	v_addc_co_u32_e32 v111, vcc, 0, v129, vcc
	global_store_dwordx2 v[110:111], v[108:109], off
	v_cvt_pk_bf16_f32 v104, v104, v105
	v_cvt_pk_bf16_f32 v105, v106, v107
	global_store_dwordx2 v[112:113], v[104:105], off offset:32
	v_cvt_pk_bf16_f32 v100, v100, v101
	v_cvt_pk_bf16_f32 v101, v102, v103
	global_store_dwordx2 v[112:113], v[100:101], off offset:256
	v_cvt_pk_bf16_f32 v96, v96, v97
	v_cvt_pk_bf16_f32 v97, v98, v99
	global_store_dwordx2 v[112:113], v[96:97], off offset:288
	v_lshl_add_u64 v[96:97], v[128:129], 0, s[2:3]
	s_mov_b32 s2, 0x4010000
	v_cvt_pk_bf16_f32 v92, v92, v93
	v_cvt_pk_bf16_f32 v93, v94, v95
	v_add_co_u32_e32 v94, vcc, s2, v128
	s_mov_b64 s[2:3], 0x4018000
	s_nop 0
	v_addc_co_u32_e32 v95, vcc, 0, v129, vcc
	global_store_dwordx2 v[94:95], v[92:93], off
	v_cvt_pk_bf16_f32 v88, v88, v89
	v_cvt_pk_bf16_f32 v89, v90, v91
	global_store_dwordx2 v[96:97], v[88:89], off offset:32
	v_cvt_pk_bf16_f32 v84, v84, v85
	v_cvt_pk_bf16_f32 v85, v86, v87
	global_store_dwordx2 v[96:97], v[84:85], off offset:256
	v_cvt_pk_bf16_f32 v80, v80, v81
	v_cvt_pk_bf16_f32 v81, v82, v83
	global_store_dwordx2 v[96:97], v[80:81], off offset:288
	v_lshl_add_u64 v[80:81], v[128:129], 0, s[2:3]
	s_mov_b32 s2, 0x4018000
	v_cvt_pk_bf16_f32 v76, v76, v77
	v_cvt_pk_bf16_f32 v77, v78, v79
	v_add_co_u32_e32 v78, vcc, s2, v128
	s_mov_b64 s[2:3], 0x4040000
	s_nop 0
	v_addc_co_u32_e32 v79, vcc, 0, v129, vcc
	global_store_dwordx2 v[78:79], v[76:77], off
	v_cvt_pk_bf16_f32 v72, v72, v73
	v_cvt_pk_bf16_f32 v73, v74, v75
	global_store_dwordx2 v[80:81], v[72:73], off offset:32
	v_cvt_pk_bf16_f32 v68, v68, v69
	v_cvt_pk_bf16_f32 v69, v70, v71
	global_store_dwordx2 v[80:81], v[68:69], off offset:256
	v_cvt_pk_bf16_f32 v64, v64, v65
	v_cvt_pk_bf16_f32 v65, v66, v67
	global_store_dwordx2 v[80:81], v[64:65], off offset:288
	v_lshl_add_u64 v[64:65], v[128:129], 0, s[2:3]
	s_mov_b32 s2, 0x4040000
	v_cvt_pk_bf16_f32 v60, v60, v61
	v_cvt_pk_bf16_f32 v61, v62, v63
	v_add_co_u32_e32 v62, vcc, s2, v128
	s_mov_b64 s[2:3], 0x4048000
	s_nop 0
	v_addc_co_u32_e32 v63, vcc, 0, v129, vcc
	global_store_dwordx2 v[62:63], v[60:61], off
	v_cvt_pk_bf16_f32 v56, v56, v57
	v_cvt_pk_bf16_f32 v57, v58, v59
	global_store_dwordx2 v[64:65], v[56:57], off offset:32
	v_cvt_pk_bf16_f32 v52, v52, v53
	v_cvt_pk_bf16_f32 v53, v54, v55
	global_store_dwordx2 v[64:65], v[52:53], off offset:256
	v_cvt_pk_bf16_f32 v48, v48, v49
	v_cvt_pk_bf16_f32 v49, v50, v51
	global_store_dwordx2 v[64:65], v[48:49], off offset:288
	v_lshl_add_u64 v[48:49], v[128:129], 0, s[2:3]
	s_mov_b32 s2, 0x4048000
	v_cvt_pk_bf16_f32 v44, v44, v45
	v_cvt_pk_bf16_f32 v45, v46, v47
	v_add_co_u32_e32 v46, vcc, s2, v128
	s_mov_b64 s[2:3], 0x4050000
	s_nop 0
	v_addc_co_u32_e32 v47, vcc, 0, v129, vcc
	global_store_dwordx2 v[46:47], v[44:45], off
	v_cvt_pk_bf16_f32 v40, v40, v41
	v_cvt_pk_bf16_f32 v41, v42, v43
	global_store_dwordx2 v[48:49], v[40:41], off offset:32
	v_cvt_pk_bf16_f32 v36, v36, v37
	v_cvt_pk_bf16_f32 v37, v38, v39
	global_store_dwordx2 v[48:49], v[36:37], off offset:256
	v_cvt_pk_bf16_f32 v32, v32, v33
	v_cvt_pk_bf16_f32 v33, v34, v35
	global_store_dwordx2 v[48:49], v[32:33], off offset:288
	v_lshl_add_u64 v[32:33], v[128:129], 0, s[2:3]
	s_mov_b32 s2, 0x4050000
	v_cvt_pk_bf16_f32 v28, v28, v29
	v_cvt_pk_bf16_f32 v29, v30, v31
	v_add_co_u32_e32 v30, vcc, s2, v128
	s_mov_b64 s[2:3], 0x4058000
	s_nop 0
	v_addc_co_u32_e32 v31, vcc, 0, v129, vcc
	global_store_dwordx2 v[30:31], v[28:29], off
	v_cvt_pk_bf16_f32 v24, v24, v25
	v_cvt_pk_bf16_f32 v25, v26, v27
	global_store_dwordx2 v[32:33], v[24:25], off offset:32
	v_cvt_pk_bf16_f32 v20, v20, v21
	v_cvt_pk_bf16_f32 v21, v22, v23
	global_store_dwordx2 v[32:33], v[20:21], off offset:256
	v_cvt_pk_bf16_f32 v16, v16, v17
	v_cvt_pk_bf16_f32 v17, v18, v19
	global_store_dwordx2 v[32:33], v[16:17], off offset:288
	v_lshl_add_u64 v[16:17], v[128:129], 0, s[2:3]
	s_mov_b32 s2, 0x4058000
	v_cvt_pk_bf16_f32 v12, v12, v13
	v_cvt_pk_bf16_f32 v13, v14, v15
	v_add_co_u32_e32 v14, vcc, s2, v128
	s_cmpk_lt_u32 s9, 0x100
	s_nop 0
	v_addc_co_u32_e32 v15, vcc, 0, v129, vcc
	global_store_dwordx2 v[14:15], v[12:13], off
	v_cvt_pk_bf16_f32 v8, v8, v9
	v_cvt_pk_bf16_f32 v9, v10, v11
	global_store_dwordx2 v[16:17], v[8:9], off offset:32
	v_cvt_pk_bf16_f32 v4, v4, v5
	v_cvt_pk_bf16_f32 v5, v6, v7
	global_store_dwordx2 v[16:17], v[4:5], off offset:256
	v_cvt_pk_bf16_f32 v0, v0, v1
	v_cvt_pk_bf16_f32 v1, v2, v3
	global_store_dwordx2 v[16:17], v[0:1], off offset:288
	s_waitcnt vmcnt(0)
	s_cbranch_scc0 .LBB0_275
	s_barrier

.LBB0_285:
	v_bfe_u32 v14, v160, 4, 2
	v_and_b32_e32 v131, 15, v160
	v_lshlrev_b32_e32 v130, 4, v14
	v_lshlrev_b32_e32 v15, 2, v160
	v_lshl_or_b32 v14, v131, 6, v130
	s_lshl_b32 s21, s44, 13
	v_and_b32_e32 v15, 32, v15
	v_bitop3_b32 v16, v14, s21, v15 bitop3:0xde
	s_lshl_b32 s21, s45, 5
	s_lshl_b32 s35, s44, 6
	s_and_b32 s44, s21, 0x60
	s_add_i32 m0, s19, 0x18000
	v_lshl_add_u64 v[6:7], v[6:7], 0, s[50:51]
	s_lshl_b32 s21, s44, 7
	s_waitcnt vmcnt(4)
	s_barrier
	global_load_lds_dwordx4 v[6:7], off
	v_lshl_add_u64 v[4:5], v[4:5], 0, s[50:51]
	s_add_i32 m0, s19, 0x1a000
	s_add_i32 s45, s19, 0x8000
	s_add_i32 s53, s19, 0xa000
	global_load_lds_dwordx4 v[4:5], off
	v_lshl_add_u64 v[2:3], v[2:3], 0, s[50:51]
	s_mov_b32 m0, s45
	s_add_u32 s54, s42, 0x80080
	global_load_lds_dwordx4 v[2:3], off
	v_lshl_add_u64 v[0:1], v[0:1], 0, s[50:51]
	s_mov_b32 m0, s53
	s_addc_u32 s55, s43, 0
	global_load_lds_dwordx4 v[0:1], off
	s_add_i32 m0, s19, 0x1c000
	v_lshl_add_u64 v[0:1], s[54:55], 0, v[156:157]
	global_load_lds_dwordx4 v[0:1], off
	v_lshl_add_u64 v[0:1], s[54:55], 0, v[128:129]
	s_add_i32 m0, s19, 0x1e000
	s_add_u32 s2, s6, s2
	global_load_lds_dwordx4 v[0:1], off
	s_addc_u32 s3, s7, s3
	v_lshlrev_b32_e32 v0, 15, v11
	v_and_b32_e32 v0, 0xffff0000, v0
	s_add_u32 s2, s26, s2
	v_lshl_add_u32 v0, v12, 12, v0
	v_and_b32_e32 v1, 1, v11
	s_addc_u32 s3, s27, s3
	v_lshl_or_b32 v0, v1, 6, v0
	s_add_u32 s2, s2, 0x19524080
	v_lshl_add_u32 v0, v13, 1, v0
	v_mov_b32_e32 v1, v157
	s_addc_u32 s3, s3, 0
	v_lshl_add_u64 v[132:133], s[2:3], 0, v[0:1]
	v_lshlrev_b32_e32 v0, 15, v8
	v_and_b32_e32 v0, 0xffff0000, v0
	v_lshl_add_u32 v0, v9, 12, v0
	v_and_b32_e32 v1, 1, v8
	v_lshl_or_b32 v0, v1, 6, v0
	s_waitcnt vmcnt(6)
	v_lshl_add_u32 v0, v10, 1, v0
	v_mov_b32_e32 v1, v157
	v_lshl_add_u64 v[134:135], s[2:3], 0, v[0:1]
	v_bitop3_b32 v136, s21, v14, v15 bitop3:0xf6
	s_mov_b32 s54, -2
	s_mov_b64 s[6:7], 0
	v_add_u32_e32 v137, 0, v16
	s_barrier
	s_add_u32 s60, s6, 0x100
	s_addc_u32 s61, s7, 0
	s_cmp_lg_u32 s54, 28
	s_cselect_b32 s55, s60, 0
	s_cselect_b32 s21, s61, 0
	s_add_u32 s2, s48, s55
	s_addc_u32 s3, s49, s21
	s_add_i32 s66, 0, 0x10000
	v_add_u32_e32 v150, s66, v136
	ds_read_b128 v[138:141], v150
	ds_read_b128 v[142:145], v150 offset:1024
	ds_read_b128 v[146:149], v150 offset:2048
	ds_read_b128 v[150:153], v150 offset:3072
	s_add_u32 s62, s42, s55
	s_addc_u32 s63, s43, s21
	v_lshl_add_u64 v[154:155], v[134:135], 0, s[6:7]
	s_add_i32 m0, s19, 0xc000
	ds_read_b128 v[162:165], v137
	ds_read_b128 v[166:169], v137 offset:1024
	ds_read_b128 v[170:173], v137 offset:2048
	ds_read_b128 v[174:177], v137 offset:3072
	ds_read_b128 v[178:181], v137 offset:4096
	ds_read_b128 v[182:185], v137 offset:5120
	ds_read_b128 v[186:189], v137 offset:6144
	ds_read_b128 v[206:209], v137 offset:7168
	global_load_lds_dwordx4 v[154:155], off
	v_lshl_add_u64 v[154:155], v[132:133], 0, s[6:7]
	s_add_i32 m0, s19, 0xe000
	s_nop 0
	global_load_lds_dwordx4 v[154:155], off
	s_waitcnt lgkmcnt(8)
	s_barrier
	s_waitcnt lgkmcnt(0)
	s_setprio 1
	s_waitcnt lgkmcnt(0)
	v_mfma_f32_16x16x32_bf16 v[124:127], v[138:141], v[162:165], 0
	v_mfma_f32_16x16x32_bf16 v[120:123], v[146:149], v[162:165], 0
	v_mfma_f32_16x16x32_bf16 v[116:119], v[138:141], v[170:173], 0
	v_mfma_f32_16x16x32_bf16 v[112:115], v[146:149], v[170:173], 0
	v_mfma_f32_16x16x32_bf16 v[108:111], v[138:141], v[178:181], 0
	v_mfma_f32_16x16x32_bf16 v[100:103], v[146:149], v[178:181], 0
	v_mfma_f32_16x16x32_bf16 v[92:95], v[138:141], v[186:189], 0
	v_mfma_f32_16x16x32_bf16 v[84:87], v[146:149], v[186:189], 0
	v_mfma_f32_16x16x32_bf16 v[124:127], v[142:145], v[166:169], v[124:127]
	v_mfma_f32_16x16x32_bf16 v[120:123], v[150:153], v[166:169], v[120:123]
	v_mfma_f32_16x16x32_bf16 v[116:119], v[142:145], v[174:177], v[116:119]
	v_mfma_f32_16x16x32_bf16 v[112:115], v[150:153], v[174:177], v[112:115]
	v_mfma_f32_16x16x32_bf16 v[108:111], v[142:145], v[182:185], v[108:111]
	v_mfma_f32_16x16x32_bf16 v[100:103], v[150:153], v[182:185], v[100:103]
	v_mfma_f32_16x16x32_bf16 v[92:95], v[142:145], v[206:209], v[92:95]
	v_mfma_f32_16x16x32_bf16 v[84:87], v[150:153], v[206:209], v[84:87]
	s_setprio 0
	s_barrier
	s_add_i32 s21, 0, 0x14000
	v_add_u32_e32 v154, s21, v136
	s_add_i32 s6, s66, s10
	ds_read_b128 v[214:217], v154
	ds_read_b128 v[218:221], v154 offset:1024
	ds_read_b128 v[222:225], v154 offset:2048
	ds_read_b128 v[226:229], v154 offset:3072
	v_lshl_add_u64 v[154:155], s[62:63], 0, v[156:157]
	s_mov_b32 m0, s6
	v_lshl_add_u64 v[230:231], s[62:63], 0, v[128:129]
	global_load_lds_dwordx4 v[154:155], off
	s_add_i32 m0, s6, 0x2000
	s_nop 0
	global_load_lds_dwordx4 v[230:231], off
	s_barrier
	s_waitcnt lgkmcnt(0)
	s_setprio 1
	s_waitcnt lgkmcnt(0)
	v_mfma_f32_16x16x32_bf16 v[104:107], v[214:217], v[162:165], 0
	v_mfma_f32_16x16x32_bf16 v[96:99], v[222:225], v[162:165], 0
	v_mfma_f32_16x16x32_bf16 v[88:91], v[214:217], v[170:173], 0
	v_mfma_f32_16x16x32_bf16 v[80:83], v[222:225], v[170:173], 0
	v_mfma_f32_16x16x32_bf16 v[76:79], v[214:217], v[178:181], 0
	v_mfma_f32_16x16x32_bf16 v[72:75], v[222:225], v[178:181], 0
	v_mfma_f32_16x16x32_bf16 v[68:71], v[214:217], v[186:189], 0
	v_mfma_f32_16x16x32_bf16 v[64:67], v[222:225], v[186:189], 0
	v_mfma_f32_16x16x32_bf16 v[104:107], v[218:221], v[166:169], v[104:107]
	v_mfma_f32_16x16x32_bf16 v[96:99], v[226:229], v[166:169], v[96:99]
	v_mfma_f32_16x16x32_bf16 v[88:91], v[218:221], v[174:177], v[88:91]
	v_mfma_f32_16x16x32_bf16 v[80:83], v[226:229], v[174:177], v[80:83]
	v_mfma_f32_16x16x32_bf16 v[76:79], v[218:221], v[182:185], v[76:79]
	v_mfma_f32_16x16x32_bf16 v[72:75], v[226:229], v[182:185], v[72:75]
	v_mfma_f32_16x16x32_bf16 v[68:71], v[218:221], v[206:209], v[68:71]
	v_mfma_f32_16x16x32_bf16 v[64:67], v[226:229], v[206:209], v[64:67]
	s_setprio 0
	s_mov_b32 m0, s19
	v_lshl_add_u64 v[232:233], s[2:3], 0, v[156:157]
	s_barrier
	ds_read_b128 v[162:165], v137 offset:16384
	ds_read_b128 v[166:169], v137 offset:17408
	ds_read_b128 v[170:173], v137 offset:18432
	ds_read_b128 v[174:177], v137 offset:19456
	ds_read_b128 v[178:181], v137 offset:20480
	ds_read_b128 v[182:185], v137 offset:21504
	ds_read_b128 v[186:189], v137 offset:22528
	ds_read_b128 v[206:209], v137 offset:23552
	global_load_lds_dwordx4 v[232:233], off
	v_lshl_add_u64 v[234:235], s[2:3], 0, v[128:129]
	s_mov_b32 m0, s24
	s_nop 0
	global_load_lds_dwordx4 v[234:235], off
	s_barrier
	s_waitcnt lgkmcnt(0)
	s_setprio 1
	s_waitcnt lgkmcnt(0)
	v_mfma_f32_16x16x32_bf16 v[60:63], v[138:141], v[162:165], 0
	v_mfma_f32_16x16x32_bf16 v[56:59], v[146:149], v[162:165], 0
	v_mfma_f32_16x16x32_bf16 v[52:55], v[138:141], v[170:173], 0
	v_mfma_f32_16x16x32_bf16 v[48:51], v[146:149], v[170:173], 0
	v_mfma_f32_16x16x32_bf16 v[40:43], v[138:141], v[178:181], 0
	v_mfma_f32_16x16x32_bf16 v[32:35], v[146:149], v[178:181], 0
	v_mfma_f32_16x16x32_bf16 v[24:27], v[138:141], v[186:189], 0
	v_mfma_f32_16x16x32_bf16 v[16:19], v[146:149], v[186:189], 0
	v_mfma_f32_16x16x32_bf16 v[60:63], v[142:145], v[166:169], v[60:63]
	v_mfma_f32_16x16x32_bf16 v[56:59], v[150:153], v[166:169], v[56:59]
	v_mfma_f32_16x16x32_bf16 v[52:55], v[142:145], v[174:177], v[52:55]
	v_mfma_f32_16x16x32_bf16 v[48:51], v[150:153], v[174:177], v[48:51]
	v_mfma_f32_16x16x32_bf16 v[40:43], v[142:145], v[182:185], v[40:43]
	v_mfma_f32_16x16x32_bf16 v[32:35], v[150:153], v[182:185], v[32:35]
	v_mfma_f32_16x16x32_bf16 v[24:27], v[142:145], v[206:209], v[24:27]
	v_mfma_f32_16x16x32_bf16 v[16:19], v[150:153], v[206:209], v[16:19]
	s_setprio 0
	s_barrier
	s_add_u32 s6, s62, 0x80000
	s_addc_u32 s7, s63, 0
	s_add_i32 s21, s21, s10
	v_lshl_add_u64 v[138:139], s[6:7], 0, v[156:157]
	s_mov_b32 m0, s21
	s_nop 0
	global_load_lds_dwordx4 v[138:139], off
	v_lshl_add_u64 v[138:139], s[6:7], 0, v[128:129]
	s_add_i32 m0, s21, 0x2000
	s_nop 0
	global_load_lds_dwordx4 v[138:139], off
	s_waitcnt vmcnt(6)
	s_barrier
	s_setprio 1
	v_mfma_f32_16x16x32_bf16 v[44:47], v[214:217], v[162:165], 0
	v_mfma_f32_16x16x32_bf16 v[36:39], v[222:225], v[162:165], 0
	v_mfma_f32_16x16x32_bf16 v[28:31], v[214:217], v[170:173], 0
	v_mfma_f32_16x16x32_bf16 v[20:23], v[222:225], v[170:173], 0
	v_mfma_f32_16x16x32_bf16 v[12:15], v[214:217], v[178:181], 0
	v_mfma_f32_16x16x32_bf16 v[8:11], v[222:225], v[178:181], 0
	v_mfma_f32_16x16x32_bf16 v[4:7], v[214:217], v[186:189], 0
	v_mfma_f32_16x16x32_bf16 v[0:3], v[222:225], v[186:189], 0
	v_mfma_f32_16x16x32_bf16 v[44:47], v[218:221], v[166:169], v[44:47]
	v_mfma_f32_16x16x32_bf16 v[36:39], v[226:229], v[166:169], v[36:39]
	v_mfma_f32_16x16x32_bf16 v[28:31], v[218:221], v[174:177], v[28:31]
	v_mfma_f32_16x16x32_bf16 v[20:23], v[226:229], v[174:177], v[20:23]
	v_mfma_f32_16x16x32_bf16 v[12:15], v[218:221], v[182:185], v[12:15]
	v_mfma_f32_16x16x32_bf16 v[8:11], v[226:229], v[182:185], v[8:11]
	v_mfma_f32_16x16x32_bf16 v[4:7], v[218:221], v[206:209], v[4:7]
	v_mfma_f32_16x16x32_bf16 v[0:3], v[226:229], v[206:209], v[0:3]
	s_setprio 0
	s_add_i32 s6, 0, 0x18000
	v_add_u32_e32 v150, s6, v136
	s_barrier
	ds_read_b128 v[138:141], v150
	ds_read_b128 v[142:145], v150 offset:1024
	ds_read_b128 v[146:149], v150 offset:2048
	ds_read_b128 v[150:153], v150 offset:3072
	s_add_u32 s2, s2, 0x80000
	s_addc_u32 s3, s3, 0
	s_mov_b32 m0, s25
	v_lshl_add_u64 v[214:215], s[2:3], 0, v[156:157]
	ds_read_b128 v[162:165], v137 offset:32768
	ds_read_b128 v[166:169], v137 offset:33792
	ds_read_b128 v[170:173], v137 offset:34816
	ds_read_b128 v[174:177], v137 offset:35840
	ds_read_b128 v[178:181], v137 offset:36864
	ds_read_b128 v[182:185], v137 offset:37888
	ds_read_b128 v[186:189], v137 offset:38912
	ds_read_b128 v[206:209], v137 offset:39936
	global_load_lds_dwordx4 v[214:215], off
	v_lshl_add_u64 v[214:215], s[2:3], 0, v[128:129]
	s_mov_b32 m0, s34
	s_nop 0
	global_load_lds_dwordx4 v[214:215], off
	s_waitcnt lgkmcnt(8)
	s_barrier
	s_waitcnt lgkmcnt(0)
	s_setprio 1
	s_waitcnt lgkmcnt(0)
	v_mfma_f32_16x16x32_bf16 v[124:127], v[138:141], v[162:165], v[124:127]
	v_mfma_f32_16x16x32_bf16 v[120:123], v[146:149], v[162:165], v[120:123]
	v_mfma_f32_16x16x32_bf16 v[116:119], v[138:141], v[170:173], v[116:119]
	v_mfma_f32_16x16x32_bf16 v[112:115], v[146:149], v[170:173], v[112:115]
	v_mfma_f32_16x16x32_bf16 v[108:111], v[138:141], v[178:181], v[108:111]
	v_mfma_f32_16x16x32_bf16 v[100:103], v[146:149], v[178:181], v[100:103]
	v_mfma_f32_16x16x32_bf16 v[92:95], v[138:141], v[186:189], v[92:95]
	v_mfma_f32_16x16x32_bf16 v[84:87], v[146:149], v[186:189], v[84:87]
	v_mfma_f32_16x16x32_bf16 v[124:127], v[142:145], v[166:169], v[124:127]
	v_mfma_f32_16x16x32_bf16 v[120:123], v[150:153], v[166:169], v[120:123]
	v_mfma_f32_16x16x32_bf16 v[116:119], v[142:145], v[174:177], v[116:119]
	v_mfma_f32_16x16x32_bf16 v[112:115], v[150:153], v[174:177], v[112:115]
	v_mfma_f32_16x16x32_bf16 v[108:111], v[142:145], v[182:185], v[108:111]
	v_mfma_f32_16x16x32_bf16 v[100:103], v[150:153], v[182:185], v[100:103]
	v_mfma_f32_16x16x32_bf16 v[92:95], v[142:145], v[206:209], v[92:95]
	v_mfma_f32_16x16x32_bf16 v[84:87], v[150:153], v[206:209], v[84:87]
	s_setprio 0
	s_barrier
	s_add_i32 s7, 0, 0x1c000
	s_add_i32 s2, s6, s10
	v_add_u32_e32 v161, s7, v136
	v_lshl_add_u64 v[154:155], v[154:155], 0, s[50:51]
	s_mov_b32 m0, s2
	ds_read_b128 v[214:217], v161
	ds_read_b128 v[218:221], v161 offset:1024
	ds_read_b128 v[222:225], v161 offset:2048
	ds_read_b128 v[226:229], v161 offset:3072
	global_load_lds_dwordx4 v[154:155], off
	v_lshl_add_u64 v[154:155], v[230:231], 0, s[50:51]
	s_add_i32 m0, s2, 0x2000
	s_nop 0
	global_load_lds_dwordx4 v[154:155], off
	s_barrier
	s_waitcnt lgkmcnt(0)
	s_setprio 1
	s_waitcnt lgkmcnt(0)
	v_mfma_f32_16x16x32_bf16 v[104:107], v[214:217], v[162:165], v[104:107]
	v_mfma_f32_16x16x32_bf16 v[96:99], v[222:225], v[162:165], v[96:99]
	v_mfma_f32_16x16x32_bf16 v[88:91], v[214:217], v[170:173], v[88:91]
	v_mfma_f32_16x16x32_bf16 v[80:83], v[222:225], v[170:173], v[80:83]
	v_mfma_f32_16x16x32_bf16 v[76:79], v[214:217], v[178:181], v[76:79]
	v_mfma_f32_16x16x32_bf16 v[72:75], v[222:225], v[178:181], v[72:75]
	v_mfma_f32_16x16x32_bf16 v[68:71], v[214:217], v[186:189], v[68:71]
	v_mfma_f32_16x16x32_bf16 v[64:67], v[222:225], v[186:189], v[64:67]
	v_mfma_f32_16x16x32_bf16 v[104:107], v[218:221], v[166:169], v[104:107]
	v_mfma_f32_16x16x32_bf16 v[96:99], v[226:229], v[166:169], v[96:99]
	v_mfma_f32_16x16x32_bf16 v[88:91], v[218:221], v[174:177], v[88:91]
	v_mfma_f32_16x16x32_bf16 v[80:83], v[226:229], v[174:177], v[80:83]
	v_mfma_f32_16x16x32_bf16 v[76:79], v[218:221], v[182:185], v[76:79]
	v_mfma_f32_16x16x32_bf16 v[72:75], v[226:229], v[182:185], v[72:75]
	v_mfma_f32_16x16x32_bf16 v[68:71], v[218:221], v[206:209], v[68:71]
	v_mfma_f32_16x16x32_bf16 v[64:67], v[226:229], v[206:209], v[64:67]
	s_setprio 0
	s_mov_b32 m0, s45
	v_lshl_add_u64 v[154:155], v[232:233], 0, s[50:51]
	s_barrier
	ds_read_b128 v[162:165], v137 offset:49152
	ds_read_b128 v[166:169], v137 offset:50176
	ds_read_b128 v[170:173], v137 offset:51200
	ds_read_b128 v[174:177], v137 offset:52224
	ds_read_b128 v[178:181], v137 offset:53248
	ds_read_b128 v[182:185], v137 offset:54272
	ds_read_b128 v[186:189], v137 offset:55296
	ds_read_b128 v[206:209], v137 offset:56320
	global_load_lds_dwordx4 v[154:155], off
	v_lshl_add_u64 v[154:155], v[234:235], 0, s[50:51]
	s_mov_b32 m0, s53
	s_nop 0
	global_load_lds_dwordx4 v[154:155], off
	s_barrier
	s_waitcnt lgkmcnt(0)
	s_setprio 1
	s_waitcnt lgkmcnt(0)
	v_mfma_f32_16x16x32_bf16 v[60:63], v[138:141], v[162:165], v[60:63]
	v_mfma_f32_16x16x32_bf16 v[56:59], v[146:149], v[162:165], v[56:59]
	v_mfma_f32_16x16x32_bf16 v[52:55], v[138:141], v[170:173], v[52:55]
	v_mfma_f32_16x16x32_bf16 v[48:51], v[146:149], v[170:173], v[48:51]
	v_mfma_f32_16x16x32_bf16 v[40:43], v[138:141], v[178:181], v[40:43]
	v_mfma_f32_16x16x32_bf16 v[32:35], v[146:149], v[178:181], v[32:35]
	v_mfma_f32_16x16x32_bf16 v[24:27], v[138:141], v[186:189], v[24:27]
	v_mfma_f32_16x16x32_bf16 v[16:19], v[146:149], v[186:189], v[16:19]
	v_mfma_f32_16x16x32_bf16 v[60:63], v[142:145], v[166:169], v[60:63]
	v_mfma_f32_16x16x32_bf16 v[56:59], v[150:153], v[166:169], v[56:59]
	v_mfma_f32_16x16x32_bf16 v[52:55], v[142:145], v[174:177], v[52:55]
	v_mfma_f32_16x16x32_bf16 v[48:51], v[150:153], v[174:177], v[48:51]
	v_mfma_f32_16x16x32_bf16 v[40:43], v[142:145], v[182:185], v[40:43]
	v_mfma_f32_16x16x32_bf16 v[32:35], v[150:153], v[182:185], v[32:35]
	v_mfma_f32_16x16x32_bf16 v[24:27], v[142:145], v[206:209], v[24:27]
	v_mfma_f32_16x16x32_bf16 v[16:19], v[150:153], v[206:209], v[16:19]
	s_setprio 0
	s_barrier
	s_add_u32 s2, s62, 0x80080
	s_addc_u32 s3, s63, 0
	s_add_i32 s6, s7, s10
	v_lshl_add_u64 v[138:139], s[2:3], 0, v[156:157]
	s_mov_b32 m0, s6
	s_nop 0
	global_load_lds_dwordx4 v[138:139], off
	v_lshl_add_u64 v[138:139], s[2:3], 0, v[128:129]
	s_add_i32 m0, s6, 0x2000
	s_nop 0
	global_load_lds_dwordx4 v[138:139], off
	s_waitcnt vmcnt(6)
	s_barrier
	s_setprio 1
	v_mfma_f32_16x16x32_bf16 v[44:47], v[214:217], v[162:165], v[44:47]
	v_mfma_f32_16x16x32_bf16 v[36:39], v[222:225], v[162:165], v[36:39]
	v_mfma_f32_16x16x32_bf16 v[28:31], v[214:217], v[170:173], v[28:31]
	v_mfma_f32_16x16x32_bf16 v[20:23], v[222:225], v[170:173], v[20:23]
	v_mfma_f32_16x16x32_bf16 v[12:15], v[214:217], v[178:181], v[12:15]
	v_mfma_f32_16x16x32_bf16 v[8:11], v[222:225], v[178:181], v[8:11]
	v_mfma_f32_16x16x32_bf16 v[4:7], v[214:217], v[186:189], v[4:7]
	v_mfma_f32_16x16x32_bf16 v[0:3], v[222:225], v[186:189], v[0:3]
	v_mfma_f32_16x16x32_bf16 v[44:47], v[218:221], v[166:169], v[44:47]
	v_mfma_f32_16x16x32_bf16 v[36:39], v[226:229], v[166:169], v[36:39]
	v_mfma_f32_16x16x32_bf16 v[28:31], v[218:221], v[174:177], v[28:31]
	v_mfma_f32_16x16x32_bf16 v[20:23], v[226:229], v[174:177], v[20:23]
	v_mfma_f32_16x16x32_bf16 v[12:15], v[218:221], v[182:185], v[12:15]
	v_mfma_f32_16x16x32_bf16 v[8:11], v[226:229], v[182:185], v[8:11]
	v_mfma_f32_16x16x32_bf16 v[4:7], v[218:221], v[206:209], v[4:7]
	v_mfma_f32_16x16x32_bf16 v[0:3], v[226:229], v[206:209], v[0:3]
	s_setprio 0
	s_add_i32 s54, s54, 2
	s_cmp_gt_u32 s54, 29
	s_mov_b64 s[6:7], s[60:61]
	s_barrier
	s_cbranch_scc1 .Lpost_286

.Lpost_286:
	s_and_b64 s[2:3], s[36:37], exec
	s_mov_b32 s2, 0x125e0000
	s_cselect_b32 s2, s2, 0x135e0000
	s_add_u32 s2, s26, s2
	s_addc_u32 s3, s27, 0
	s_ashr_i32 s6, s35, 31
	v_mov_b32_e32 v129, s6
	s_lshl_b32 s6, s44, 2
	s_add_u32 s2, s2, s6
	v_or_b32_e32 v128, s35, v131
	s_addc_u32 s3, s3, 0
	v_mov_b32_e32 v131, v157
	v_lshl_add_u64 v[130:131], s[2:3], 0, v[130:131]
	s_lshl_b64 s[2:3], s[40:41], 21
	s_lshl_b64 s[6:7], s[38:39], 18
	v_lshl_add_u64 v[130:131], v[130:131], 0, s[2:3]
	v_lshlrev_b64 v[128:129], 10, v[128:129]
	v_lshl_add_u64 v[130:131], v[130:131], 0, s[6:7]
	v_lshl_add_u64 v[128:129], v[130:131], 0, v[128:129]
	s_movk_i32 s2, 0x4000
	global_store_dwordx4 v[128:129], v[124:127], off
	global_store_dwordx4 v[128:129], v[120:123], off offset:64
	global_store_dwordx4 v[128:129], v[104:107], off offset:512
	global_store_dwordx4 v[128:129], v[96:99], off offset:576
	s_cmpk_lt_u32 s9, 0x100
	s_nop 0
	v_add_co_u32_e32 v96, vcc, s2, v128
	s_mov_b32 s2, 0xc000
	s_nop 0
	v_addc_co_u32_e32 v97, vcc, 0, v129, vcc
	global_store_dwordx4 v[96:97], v[116:119], off
	global_store_dwordx4 v[96:97], v[112:115], off offset:64
	global_store_dwordx4 v[96:97], v[88:91], off offset:512
	global_store_dwordx4 v[96:97], v[80:83], off offset:576
	s_nop 1
	v_add_co_u32_e32 v80, vcc, s73, v128
	s_nop 1
	v_addc_co_u32_e32 v81, vcc, 0, v129, vcc
	global_store_dwordx4 v[80:81], v[108:111], off
	global_store_dwordx4 v[80:81], v[100:103], off offset:64
	global_store_dwordx4 v[80:81], v[76:79], off offset:512
	global_store_dwordx4 v[80:81], v[72:75], off offset:576
	s_nop 1
	v_add_co_u32_e32 v72, vcc, s2, v128
	s_mov_b32 s2, 0x20000
	s_nop 0
	v_addc_co_u32_e32 v73, vcc, 0, v129, vcc
	global_store_dwordx4 v[72:73], v[92:95], off
	global_store_dwordx4 v[72:73], v[84:87], off offset:64
	global_store_dwordx4 v[72:73], v[68:71], off offset:512
	global_store_dwordx4 v[72:73], v[64:67], off offset:576
	s_nop 1
	v_add_co_u32_e32 v64, vcc, s2, v128
	s_mov_b32 s2, 0x24000
	s_nop 0
	v_addc_co_u32_e32 v65, vcc, 0, v129, vcc
	global_store_dwordx4 v[64:65], v[60:63], off
	global_store_dwordx4 v[64:65], v[56:59], off offset:64
	global_store_dwordx4 v[64:65], v[44:47], off offset:512
	global_store_dwordx4 v[64:65], v[36:39], off offset:576
	s_nop 1
	v_add_co_u32_e32 v36, vcc, s2, v128
	s_mov_b32 s2, 0x28000
	s_nop 0
	v_addc_co_u32_e32 v37, vcc, 0, v129, vcc
	global_store_dwordx4 v[36:37], v[52:55], off
	global_store_dwordx4 v[36:37], v[48:51], off offset:64
	global_store_dwordx4 v[36:37], v[28:31], off offset:512
	global_store_dwordx4 v[36:37], v[20:23], off offset:576
	s_nop 1
	v_add_co_u32_e32 v20, vcc, s2, v128
	s_nop 1
	v_addc_co_u32_e32 v21, vcc, 0, v129, vcc
	global_store_dwordx4 v[20:21], v[40:43], off
	global_store_dwordx4 v[20:21], v[32:35], off offset:64
	global_store_dwordx4 v[20:21], v[12:15], off offset:512
	global_store_dwordx4 v[20:21], v[8:11], off offset:576
	s_nop 1
	v_add_co_u32_e32 v8, vcc, 0x2c000, v128
	s_nop 1
	v_addc_co_u32_e32 v9, vcc, 0, v129, vcc
	global_store_dwordx4 v[8:9], v[24:27], off
	global_store_dwordx4 v[8:9], v[16:19], off offset:64
	global_store_dwordx4 v[8:9], v[4:7], off offset:512
	global_store_dwordx4 v[8:9], v[0:3], off offset:576
	s_waitcnt vmcnt(0)
	s_cbranch_scc0 .LBB0_289
	s_barrier

.LBB0_325:
	s_add_i32 s83, s83, 1
	s_mul_i32 s6, s83, s18
	s_add_i32 s10, s6, s20
	s_cmpk_lt_i32 s10, 0x3b8
	s_cselect_b64 s[6:7], -1, 0
	s_cmpk_gt_i32 s10, 0x3b7
	s_cselect_b64 s[68:69], -1, 0
	s_and_b64 s[24:25], s[6:7], exec
	s_cselect_b32 s10, s10, 0
	s_ashr_i32 s21, s10, 31
	s_lshr_b32 s21, s21, 29
	s_add_i32 s21, s10, s21
	s_ashr_i32 s24, s21, 3
	s_and_b32 s21, s21, -8
	s_sub_i32 s10, s10, s21
	s_cmp_lt_i32 s10, 0
	s_movk_i32 s21, 0x78
	s_cselect_b32 s21, s21, 0x77
	s_mul_i32 s10, s21, s10
	s_add_i32 s21, s10, s24
	s_mul_hi_i32 s10, s21, 0x92492493
	s_add_i32 s10, s10, s21
	s_lshr_b32 s24, s10, 31
	s_ashr_i32 s10, s10, 4
	s_add_i32 s25, s10, s24
	s_lshl_b32 s37, s25, 2
	s_sub_i32 s10, 0x88, s37
	s_min_i32 s44, s10, 4
	s_abs_i32 s45, s44
	v_cvt_f32_u32_e32 v0, s45
	s_sub_i32 s46, 0, s45
	s_mul_i32 s25, s25, 28
	s_sub_i32 s21, s21, s25
	v_rcp_iflag_f32_e32 v0, v0
	s_mov_b32 s24, s36
	s_abs_i32 s36, s21
	s_xor_b32 s25, s21, s44
	v_mul_f32_e32 v0, 0x4f7ffffe, v0
	v_cvt_u32_f32_e32 v0, v0
	s_mov_b64 s[42:43], s[48:49]
	s_ashr_i32 s25, s25, 31
	s_mov_b32 s10, s66
	v_readfirstlane_b32 s47, v0
	s_mul_i32 s46, s46, s47
	s_mul_hi_u32 s46, s47, s46
	s_add_i32 s47, s47, s46
	s_mul_hi_u32 s46, s36, s47
	s_mul_i32 s47, s46, s45
	s_sub_i32 s36, s36, s47
	s_add_i32 s47, s46, 1
	s_sub_i32 s48, s36, s45
	s_cmp_ge_u32 s36, s45
	s_cselect_b32 s46, s47, s46
	s_cselect_b32 s36, s48, s36
	s_add_i32 s47, s46, 1
	s_cmp_ge_u32 s36, s45
	s_cselect_b32 s36, s47, s46
	s_xor_b32 s36, s36, s25
	s_sub_i32 s66, s36, s25
	s_mul_i32 s25, s66, s44
	s_sub_i32 s21, s21, s25
	s_add_i32 s36, s37, s21
	s_ashr_i32 s37, s36, 31
	s_lshl_b64 s[44:45], s[36:37], 19
	s_mov_b64 s[2:3], s[62:63]
	s_add_u32 s62, s58, s44
	s_addc_u32 s63, s59, s45
	s_and_b64 s[44:45], s[6:7], exec
	s_cselect_b32 s25, s63, s3
	s_cselect_b32 s37, s62, s2
	s_ashr_i32 s67, s66, 31
	s_lshl_b64 s[44:45], s[66:67], 19
	s_add_u32 s48, s19, s44
	s_addc_u32 s49, s34, s45
	s_and_b64 s[6:7], s[6:7], exec
	s_cselect_b32 s44, s49, s43
	s_cselect_b32 s45, s48, s42
	s_add_u32 s46, s42, 0x100
	s_addc_u32 s47, s43, 0
	s_add_u32 s6, s2, 0x40080
	s_addc_u32 s7, s3, 0
	s_mov_b32 s60, -2
	s_add_u32 s2, s6, 0xfffc0080
	s_addc_u32 s3, s7, -1
	s_add_i32 s21, 0, 0x10000
	v_add_u32_e32 v154, s21, v141
	ds_read_b128 v[136:139], v154
	ds_read_b128 v[150:153], v154 offset:1024
	ds_read_b128 v[162:165], v154 offset:2048
	ds_read_b128 v[166:169], v154 offset:3072
	s_cmp_eq_u32 s60, 12
	s_cselect_b32 s3, s25, s3
	s_cselect_b32 s2, s37, s2
	s_cselect_b32 s43, s44, s47
	s_cselect_b32 s42, s45, s46
	v_lshl_add_u64 v[154:155], s[6:7], 0, v[134:135]
	s_add_i32 m0, s53, 0xc000
	ds_read_b128 v[170:173], v149
	ds_read_b128 v[174:177], v149 offset:1024
	ds_read_b128 v[178:181], v149 offset:2048
	ds_read_b128 v[182:185], v149 offset:3072
	ds_read_b128 v[186:189], v149 offset:4096
	ds_read_b128 v[206:209], v149 offset:5120
	ds_read_b128 v[214:217], v149 offset:6144
	ds_read_b128 v[218:221], v149 offset:7168
	global_load_lds_dwordx4 v[154:155], off
	v_lshl_add_u64 v[154:155], s[6:7], 0, v[132:133]
	s_add_i32 m0, s53, 0xe000
	s_nop 0
	global_load_lds_dwordx4 v[154:155], off
	s_waitcnt lgkmcnt(8)
	s_barrier
	s_waitcnt lgkmcnt(0)
	s_setprio 1
	s_waitcnt lgkmcnt(0)
	v_mfma_f32_16x16x32_bf16 v[124:127], v[136:139], v[170:173], 0
	v_mfma_f32_16x16x32_bf16 v[120:123], v[162:165], v[170:173], 0
	v_mfma_f32_16x16x32_bf16 v[108:111], v[136:139], v[178:181], 0
	v_mfma_f32_16x16x32_bf16 v[104:107], v[162:165], v[178:181], 0
	v_mfma_f32_16x16x32_bf16 v[92:95], v[136:139], v[186:189], 0
	v_mfma_f32_16x16x32_bf16 v[88:91], v[162:165], v[186:189], 0
	v_mfma_f32_16x16x32_bf16 v[76:79], v[136:139], v[214:217], 0
	v_mfma_f32_16x16x32_bf16 v[72:75], v[162:165], v[214:217], 0
	v_mfma_f32_16x16x32_bf16 v[124:127], v[150:153], v[174:177], v[124:127]
	v_mfma_f32_16x16x32_bf16 v[120:123], v[166:169], v[174:177], v[120:123]
	v_mfma_f32_16x16x32_bf16 v[108:111], v[150:153], v[182:185], v[108:111]
	v_mfma_f32_16x16x32_bf16 v[104:107], v[166:169], v[182:185], v[104:107]
	v_mfma_f32_16x16x32_bf16 v[92:95], v[150:153], v[206:209], v[92:95]
	v_mfma_f32_16x16x32_bf16 v[88:91], v[166:169], v[206:209], v[88:91]
	v_mfma_f32_16x16x32_bf16 v[76:79], v[150:153], v[218:221], v[76:79]
	v_mfma_f32_16x16x32_bf16 v[72:75], v[166:169], v[218:221], v[72:75]
	s_setprio 0
	s_barrier
	s_add_i32 s61, 0, 0x14000
	v_add_u32_e32 v154, s61, v141
	s_add_i32 s21, s21, s35
	ds_read_b128 v[222:225], v154
	ds_read_b128 v[226:229], v154 offset:1024
	ds_read_b128 v[230:233], v154 offset:2048
	ds_read_b128 v[234:237], v154 offset:3072
	v_lshl_add_u64 v[154:155], s[42:43], 0, v[130:131]
	s_mov_b32 m0, s21
	v_lshl_add_u64 v[238:239], s[42:43], 0, v[128:129]
	global_load_lds_dwordx4 v[154:155], off
	s_add_i32 m0, s21, 0x2000
	s_nop 0
	global_load_lds_dwordx4 v[238:239], off
	s_barrier
	s_waitcnt lgkmcnt(0)
	s_setprio 1
	s_waitcnt lgkmcnt(0)
	v_mfma_f32_16x16x32_bf16 v[116:119], v[222:225], v[170:173], 0
	v_mfma_f32_16x16x32_bf16 v[112:115], v[230:233], v[170:173], 0
	v_mfma_f32_16x16x32_bf16 v[100:103], v[222:225], v[178:181], 0
	v_mfma_f32_16x16x32_bf16 v[96:99], v[230:233], v[178:181], 0
	v_mfma_f32_16x16x32_bf16 v[84:87], v[222:225], v[186:189], 0
	v_mfma_f32_16x16x32_bf16 v[80:83], v[230:233], v[186:189], 0
	v_mfma_f32_16x16x32_bf16 v[68:71], v[222:225], v[214:217], 0
	v_mfma_f32_16x16x32_bf16 v[64:67], v[230:233], v[214:217], 0
	v_mfma_f32_16x16x32_bf16 v[116:119], v[226:229], v[174:177], v[116:119]
	v_mfma_f32_16x16x32_bf16 v[112:115], v[234:237], v[174:177], v[112:115]
	v_mfma_f32_16x16x32_bf16 v[100:103], v[226:229], v[182:185], v[100:103]
	v_mfma_f32_16x16x32_bf16 v[96:99], v[234:237], v[182:185], v[96:99]
	v_mfma_f32_16x16x32_bf16 v[84:87], v[226:229], v[206:209], v[84:87]
	v_mfma_f32_16x16x32_bf16 v[80:83], v[234:237], v[206:209], v[80:83]
	v_mfma_f32_16x16x32_bf16 v[68:71], v[226:229], v[218:221], v[68:71]
	v_mfma_f32_16x16x32_bf16 v[64:67], v[234:237], v[218:221], v[64:67]
	s_setprio 0
	s_mov_b32 m0, s53
	v_lshl_add_u64 v[240:241], s[2:3], 0, v[130:131]
	s_barrier
	ds_read_b128 v[170:173], v149 offset:16384
	ds_read_b128 v[174:177], v149 offset:17408
	ds_read_b128 v[178:181], v149 offset:18432
	ds_read_b128 v[182:185], v149 offset:19456
	ds_read_b128 v[186:189], v149 offset:20480
	ds_read_b128 v[206:209], v149 offset:21504
	ds_read_b128 v[214:217], v149 offset:22528
	ds_read_b128 v[218:221], v149 offset:23552
	global_load_lds_dwordx4 v[240:241], off
	v_lshl_add_u64 v[242:243], s[2:3], 0, v[128:129]
	s_mov_b32 m0, s54
	s_nop 0
	global_load_lds_dwordx4 v[242:243], off
	s_barrier
	s_waitcnt lgkmcnt(0)
	s_setprio 1
	s_waitcnt lgkmcnt(0)
	v_mfma_f32_16x16x32_bf16 v[60:63], v[136:139], v[170:173], 0
	v_mfma_f32_16x16x32_bf16 v[56:59], v[162:165], v[170:173], 0
	v_mfma_f32_16x16x32_bf16 v[44:47], v[136:139], v[178:181], 0
	v_mfma_f32_16x16x32_bf16 v[40:43], v[162:165], v[178:181], 0
	v_mfma_f32_16x16x32_bf16 v[28:31], v[136:139], v[186:189], 0
	v_mfma_f32_16x16x32_bf16 v[24:27], v[162:165], v[186:189], 0
	v_mfma_f32_16x16x32_bf16 v[12:15], v[136:139], v[214:217], 0
	v_mfma_f32_16x16x32_bf16 v[8:11], v[162:165], v[214:217], 0
	v_mfma_f32_16x16x32_bf16 v[60:63], v[150:153], v[174:177], v[60:63]
	v_mfma_f32_16x16x32_bf16 v[56:59], v[166:169], v[174:177], v[56:59]
	v_mfma_f32_16x16x32_bf16 v[44:47], v[150:153], v[182:185], v[44:47]
	v_mfma_f32_16x16x32_bf16 v[40:43], v[166:169], v[182:185], v[40:43]
	v_mfma_f32_16x16x32_bf16 v[28:31], v[150:153], v[206:209], v[28:31]
	v_mfma_f32_16x16x32_bf16 v[24:27], v[166:169], v[206:209], v[24:27]
	v_mfma_f32_16x16x32_bf16 v[12:15], v[150:153], v[218:221], v[12:15]
	v_mfma_f32_16x16x32_bf16 v[8:11], v[166:169], v[218:221], v[8:11]
	s_setprio 0
	s_barrier
	s_add_u32 s80, s42, 0x40000
	s_addc_u32 s81, s43, 0
	s_add_i32 s21, s61, s35
	v_lshl_add_u64 v[136:137], s[80:81], 0, v[130:131]
	s_mov_b32 m0, s21
	s_nop 0
	global_load_lds_dwordx4 v[136:137], off
	v_lshl_add_u64 v[136:137], s[80:81], 0, v[128:129]
	s_add_i32 m0, s21, 0x2000
	s_nop 0
	global_load_lds_dwordx4 v[136:137], off
	s_waitcnt vmcnt(6)
	s_barrier
	s_setprio 1
	v_mfma_f32_16x16x32_bf16 v[52:55], v[222:225], v[170:173], 0
	v_mfma_f32_16x16x32_bf16 v[48:51], v[230:233], v[170:173], 0
	v_mfma_f32_16x16x32_bf16 v[36:39], v[222:225], v[178:181], 0
	v_mfma_f32_16x16x32_bf16 v[32:35], v[230:233], v[178:181], 0
	v_mfma_f32_16x16x32_bf16 v[20:23], v[222:225], v[186:189], 0
	v_mfma_f32_16x16x32_bf16 v[16:19], v[230:233], v[186:189], 0
	v_mfma_f32_16x16x32_bf16 v[4:7], v[222:225], v[214:217], 0
	v_mfma_f32_16x16x32_bf16 v[0:3], v[230:233], v[214:217], 0
	v_mfma_f32_16x16x32_bf16 v[52:55], v[226:229], v[174:177], v[52:55]
	v_mfma_f32_16x16x32_bf16 v[48:51], v[234:237], v[174:177], v[48:51]
	v_mfma_f32_16x16x32_bf16 v[36:39], v[226:229], v[182:185], v[36:39]
	v_mfma_f32_16x16x32_bf16 v[32:35], v[234:237], v[182:185], v[32:35]
	v_mfma_f32_16x16x32_bf16 v[20:23], v[226:229], v[206:209], v[20:23]
	v_mfma_f32_16x16x32_bf16 v[16:19], v[234:237], v[206:209], v[16:19]
	v_mfma_f32_16x16x32_bf16 v[4:7], v[226:229], v[218:221], v[4:7]
	v_mfma_f32_16x16x32_bf16 v[0:3], v[234:237], v[218:221], v[0:3]
	s_setprio 0
	s_add_i32 s21, 0, 0x18000
	v_add_u32_e32 v156, s21, v141
	s_barrier
	ds_read_b128 v[136:139], v156
	ds_read_b128 v[150:153], v156 offset:1024
	ds_read_b128 v[162:165], v156 offset:2048
	ds_read_b128 v[166:169], v156 offset:3072
	s_add_u32 s2, s2, 0x40000
	s_addc_u32 s3, s3, 0
	s_mov_b32 m0, s55
	v_lshl_add_u64 v[222:223], s[2:3], 0, v[130:131]
	ds_read_b128 v[170:173], v149 offset:32768
	ds_read_b128 v[174:177], v149 offset:33792
	ds_read_b128 v[178:181], v149 offset:34816
	ds_read_b128 v[182:185], v149 offset:35840
	ds_read_b128 v[186:189], v149 offset:36864
	ds_read_b128 v[206:209], v149 offset:37888
	ds_read_b128 v[214:217], v149 offset:38912
	ds_read_b128 v[218:221], v149 offset:39936
	global_load_lds_dwordx4 v[222:223], off
	v_lshl_add_u64 v[222:223], s[2:3], 0, v[128:129]
	s_mov_b32 m0, s78
	s_nop 0
	global_load_lds_dwordx4 v[222:223], off
	s_waitcnt lgkmcnt(8)
	s_barrier
	s_waitcnt lgkmcnt(0)
	s_setprio 1
	s_waitcnt lgkmcnt(0)
	v_mfma_f32_16x16x32_bf16 v[124:127], v[136:139], v[170:173], v[124:127]
	v_mfma_f32_16x16x32_bf16 v[120:123], v[162:165], v[170:173], v[120:123]
	v_mfma_f32_16x16x32_bf16 v[108:111], v[136:139], v[178:181], v[108:111]
	v_mfma_f32_16x16x32_bf16 v[104:107], v[162:165], v[178:181], v[104:107]
	v_mfma_f32_16x16x32_bf16 v[92:95], v[136:139], v[186:189], v[92:95]
	v_mfma_f32_16x16x32_bf16 v[88:91], v[162:165], v[186:189], v[88:91]
	v_mfma_f32_16x16x32_bf16 v[76:79], v[136:139], v[214:217], v[76:79]
	v_mfma_f32_16x16x32_bf16 v[72:75], v[162:165], v[214:217], v[72:75]
	v_mfma_f32_16x16x32_bf16 v[124:127], v[150:153], v[174:177], v[124:127]
	v_mfma_f32_16x16x32_bf16 v[120:123], v[166:169], v[174:177], v[120:123]
	v_mfma_f32_16x16x32_bf16 v[108:111], v[150:153], v[182:185], v[108:111]
	v_mfma_f32_16x16x32_bf16 v[104:107], v[166:169], v[182:185], v[104:107]
	v_mfma_f32_16x16x32_bf16 v[92:95], v[150:153], v[206:209], v[92:95]
	v_mfma_f32_16x16x32_bf16 v[88:91], v[166:169], v[206:209], v[88:91]
	v_mfma_f32_16x16x32_bf16 v[76:79], v[150:153], v[218:221], v[76:79]
	v_mfma_f32_16x16x32_bf16 v[72:75], v[166:169], v[218:221], v[72:75]
	s_setprio 0
	s_barrier
	s_add_i32 s61, 0, 0x1c000
	s_add_i32 s2, s21, s35
	v_add_u32_e32 v156, s61, v141
	v_lshl_add_u64 v[154:155], v[154:155], 0, s[50:51]
	s_mov_b32 m0, s2
	ds_read_b128 v[222:225], v156
	ds_read_b128 v[226:229], v156 offset:1024
	ds_read_b128 v[230:233], v156 offset:2048
	ds_read_b128 v[234:237], v156 offset:3072
	global_load_lds_dwordx4 v[154:155], off
	v_lshl_add_u64 v[154:155], v[238:239], 0, s[50:51]
	s_add_i32 m0, s2, 0x2000
	s_nop 0
	global_load_lds_dwordx4 v[154:155], off
	s_barrier
	s_waitcnt lgkmcnt(0)
	s_setprio 1
	s_waitcnt lgkmcnt(0)
	v_mfma_f32_16x16x32_bf16 v[116:119], v[222:225], v[170:173], v[116:119]
	v_mfma_f32_16x16x32_bf16 v[112:115], v[230:233], v[170:173], v[112:115]
	v_mfma_f32_16x16x32_bf16 v[100:103], v[222:225], v[178:181], v[100:103]
	v_mfma_f32_16x16x32_bf16 v[96:99], v[230:233], v[178:181], v[96:99]
	v_mfma_f32_16x16x32_bf16 v[84:87], v[222:225], v[186:189], v[84:87]
	v_mfma_f32_16x16x32_bf16 v[80:83], v[230:233], v[186:189], v[80:83]
	v_mfma_f32_16x16x32_bf16 v[68:71], v[222:225], v[214:217], v[68:71]
	v_mfma_f32_16x16x32_bf16 v[64:67], v[230:233], v[214:217], v[64:67]
	v_mfma_f32_16x16x32_bf16 v[116:119], v[226:229], v[174:177], v[116:119]
	v_mfma_f32_16x16x32_bf16 v[112:115], v[234:237], v[174:177], v[112:115]
	v_mfma_f32_16x16x32_bf16 v[100:103], v[226:229], v[182:185], v[100:103]
	v_mfma_f32_16x16x32_bf16 v[96:99], v[234:237], v[182:185], v[96:99]
	v_mfma_f32_16x16x32_bf16 v[84:87], v[226:229], v[206:209], v[84:87]
	v_mfma_f32_16x16x32_bf16 v[80:83], v[234:237], v[206:209], v[80:83]
	v_mfma_f32_16x16x32_bf16 v[68:71], v[226:229], v[218:221], v[68:71]
	v_mfma_f32_16x16x32_bf16 v[64:67], v[234:237], v[218:221], v[64:67]
	s_setprio 0
	s_mov_b32 m0, s79
	v_lshl_add_u64 v[154:155], v[240:241], 0, s[50:51]
	s_barrier
	ds_read_b128 v[170:173], v149 offset:49152
	ds_read_b128 v[174:177], v149 offset:50176
	ds_read_b128 v[178:181], v149 offset:51200
	ds_read_b128 v[182:185], v149 offset:52224
	ds_read_b128 v[186:189], v149 offset:53248
	ds_read_b128 v[206:209], v149 offset:54272
	ds_read_b128 v[214:217], v149 offset:55296
	ds_read_b128 v[218:221], v149 offset:56320
	global_load_lds_dwordx4 v[154:155], off
	v_lshl_add_u64 v[154:155], v[242:243], 0, s[50:51]
	s_mov_b32 m0, s82
	s_nop 0
	global_load_lds_dwordx4 v[154:155], off
	s_barrier
	s_waitcnt lgkmcnt(0)
	s_setprio 1
	s_waitcnt lgkmcnt(0)
	v_mfma_f32_16x16x32_bf16 v[60:63], v[136:139], v[170:173], v[60:63]
	v_mfma_f32_16x16x32_bf16 v[56:59], v[162:165], v[170:173], v[56:59]
	v_mfma_f32_16x16x32_bf16 v[44:47], v[136:139], v[178:181], v[44:47]
	v_mfma_f32_16x16x32_bf16 v[40:43], v[162:165], v[178:181], v[40:43]
	v_mfma_f32_16x16x32_bf16 v[28:31], v[136:139], v[186:189], v[28:31]
	v_mfma_f32_16x16x32_bf16 v[24:27], v[162:165], v[186:189], v[24:27]
	v_mfma_f32_16x16x32_bf16 v[12:15], v[136:139], v[214:217], v[12:15]
	v_mfma_f32_16x16x32_bf16 v[8:11], v[162:165], v[214:217], v[8:11]
	v_mfma_f32_16x16x32_bf16 v[60:63], v[150:153], v[174:177], v[60:63]
	v_mfma_f32_16x16x32_bf16 v[56:59], v[166:169], v[174:177], v[56:59]
	v_mfma_f32_16x16x32_bf16 v[44:47], v[150:153], v[182:185], v[44:47]
	v_mfma_f32_16x16x32_bf16 v[40:43], v[166:169], v[182:185], v[40:43]
	v_mfma_f32_16x16x32_bf16 v[28:31], v[150:153], v[206:209], v[28:31]
	v_mfma_f32_16x16x32_bf16 v[24:27], v[166:169], v[206:209], v[24:27]
	v_mfma_f32_16x16x32_bf16 v[12:15], v[150:153], v[218:221], v[12:15]
	v_mfma_f32_16x16x32_bf16 v[8:11], v[166:169], v[218:221], v[8:11]
	s_setprio 0
	s_barrier
	s_add_u32 s2, s42, 0x40080
	s_addc_u32 s3, s43, 0
	s_add_i32 s21, s61, s35
	v_lshl_add_u64 v[136:137], s[2:3], 0, v[130:131]
	s_mov_b32 m0, s21
	s_nop 0
	global_load_lds_dwordx4 v[136:137], off
	v_lshl_add_u64 v[136:137], s[2:3], 0, v[128:129]
	s_add_i32 m0, s21, 0x2000
	s_nop 0
	global_load_lds_dwordx4 v[136:137], off
	s_waitcnt vmcnt(6)
	s_barrier
	s_setprio 1
	v_mfma_f32_16x16x32_bf16 v[52:55], v[222:225], v[170:173], v[52:55]
	v_mfma_f32_16x16x32_bf16 v[48:51], v[230:233], v[170:173], v[48:51]
	v_mfma_f32_16x16x32_bf16 v[36:39], v[222:225], v[178:181], v[36:39]
	v_mfma_f32_16x16x32_bf16 v[32:35], v[230:233], v[178:181], v[32:35]
	v_mfma_f32_16x16x32_bf16 v[20:23], v[222:225], v[186:189], v[20:23]
	v_mfma_f32_16x16x32_bf16 v[16:19], v[230:233], v[186:189], v[16:19]
	v_mfma_f32_16x16x32_bf16 v[4:7], v[222:225], v[214:217], v[4:7]
	v_mfma_f32_16x16x32_bf16 v[0:3], v[230:233], v[214:217], v[0:3]
	v_mfma_f32_16x16x32_bf16 v[52:55], v[226:229], v[174:177], v[52:55]
	v_mfma_f32_16x16x32_bf16 v[48:51], v[234:237], v[174:177], v[48:51]
	v_mfma_f32_16x16x32_bf16 v[36:39], v[226:229], v[182:185], v[36:39]
	v_mfma_f32_16x16x32_bf16 v[32:35], v[234:237], v[182:185], v[32:35]
	v_mfma_f32_16x16x32_bf16 v[20:23], v[226:229], v[206:209], v[20:23]
	v_mfma_f32_16x16x32_bf16 v[16:19], v[234:237], v[206:209], v[16:19]
	v_mfma_f32_16x16x32_bf16 v[4:7], v[226:229], v[218:221], v[4:7]
	v_mfma_f32_16x16x32_bf16 v[0:3], v[234:237], v[218:221], v[0:3]
	s_setprio 0
	s_add_i32 s60, s60, 2
	s_add_u32 s46, s46, 0x100
	s_addc_u32 s47, s47, 0
	s_add_u32 s6, s6, 0x100
	s_addc_u32 s7, s7, 0
	s_cmp_gt_u32 s60, 13
	s_barrier
	s_cbranch_scc1 .Lpost_326

.Lpost_326:
	s_lshl_b32 s25, s24, 8
	s_cmp_gt_i32 s10, 1
	s_mov_b64 s[2:3], -1
	s_cbranch_scc1 .LBB0_329
	s_and_b64 vcc, exec, s[2:3]
	s_cbranch_vccz .LBB0_324
	s_branch .LBB0_373

.LBB0_513:
	s_add_i32 s82, s84, -2
	s_add_u32 s83, s6, 0x100
	s_addc_u32 vcc_lo, s7, 0
	s_add_u32 s6, s60, 0x80
	s_addc_u32 s7, s61, 0
	s_mov_b32 s2, 0
	s_add_i32 vcc_hi, s2, 2
	s_add_u32 s21, s6, 0x80
	s_addc_u32 s3, s7, 0
	s_add_i32 s74, 0, 0x10000
	v_add_u32_e32 v140, s74, v161
	ds_read_b128 v[128:131], v140
	ds_read_b128 v[132:135], v140 offset:1024
	ds_read_b128 v[136:139], v140 offset:2048
	ds_read_b128 v[140:143], v140 offset:3072
	s_cmp_eq_u32 s82, s2
	s_cselect_b32 s2, s80, s21
	s_cselect_b32 s3, s81, s3
	s_cselect_b32 s61, s39, vcc_lo
	s_cselect_b32 s60, s38, s83
	v_lshl_add_u64 v[206:207], s[6:7], 0, v[168:169]
	s_add_i32 m0, s88, 0xc000
	ds_read_b128 v[144:147], v214
	ds_read_b128 v[148:151], v214 offset:1024
	ds_read_b128 v[152:155], v214 offset:2048
	ds_read_b128 v[170:173], v214 offset:3072
	ds_read_b128 v[174:177], v214 offset:4096
	ds_read_b128 v[178:181], v214 offset:5120
	ds_read_b128 v[182:185], v214 offset:6144
	ds_read_b128 v[186:189], v214 offset:7168
	global_load_lds_dwordx4 v[206:207], off
	v_lshl_add_u64 v[206:207], s[6:7], 0, v[166:167]
	s_add_i32 m0, s88, 0xe000
	s_nop 0
	global_load_lds_dwordx4 v[206:207], off
	s_waitcnt lgkmcnt(8)
	s_barrier
	s_waitcnt lgkmcnt(0)
	s_setprio 1
	s_waitcnt lgkmcnt(0)
	v_mfma_f32_16x16x32_bf16 v[124:127], v[128:131], v[144:147], 0
	v_mfma_f32_16x16x32_bf16 v[120:123], v[136:139], v[144:147], 0
	v_mfma_f32_16x16x32_bf16 v[116:119], v[128:131], v[152:155], 0
	v_mfma_f32_16x16x32_bf16 v[108:111], v[136:139], v[152:155], 0
	v_mfma_f32_16x16x32_bf16 v[100:103], v[128:131], v[174:177], 0
	v_mfma_f32_16x16x32_bf16 v[92:95], v[136:139], v[174:177], 0
	v_mfma_f32_16x16x32_bf16 v[84:87], v[128:131], v[182:185], 0
	v_mfma_f32_16x16x32_bf16 v[76:79], v[136:139], v[182:185], 0
	v_mfma_f32_16x16x32_bf16 v[124:127], v[132:135], v[148:151], v[124:127]
	v_mfma_f32_16x16x32_bf16 v[120:123], v[140:143], v[148:151], v[120:123]
	v_mfma_f32_16x16x32_bf16 v[116:119], v[132:135], v[170:173], v[116:119]
	v_mfma_f32_16x16x32_bf16 v[108:111], v[140:143], v[170:173], v[108:111]
	v_mfma_f32_16x16x32_bf16 v[100:103], v[132:135], v[178:181], v[100:103]
	v_mfma_f32_16x16x32_bf16 v[92:95], v[140:143], v[178:181], v[92:95]
	v_mfma_f32_16x16x32_bf16 v[84:87], v[132:135], v[186:189], v[84:87]
	v_mfma_f32_16x16x32_bf16 v[76:79], v[140:143], v[186:189], v[76:79]
	s_setprio 0
	s_barrier
	s_add_i32 s21, 0, 0x14000
	s_add_i32 s74, s74, s53
	v_add_u32_e32 v215, s21, v161
	v_lshl_add_u64 v[228:229], s[60:61], 0, v[156:157]
	s_mov_b32 m0, s74
	ds_read_b128 v[206:209], v215
	ds_read_b128 v[216:219], v215 offset:1024
	ds_read_b128 v[220:223], v215 offset:2048
	ds_read_b128 v[224:227], v215 offset:3072
	global_load_lds_dwordx4 v[228:229], off
	v_lshl_add_u64 v[230:231], s[60:61], 0, v[162:163]
	s_add_i32 m0, s74, 0x2000
	s_nop 0
	global_load_lds_dwordx4 v[230:231], off
	s_barrier
	s_waitcnt lgkmcnt(0)
	s_setprio 1
	s_waitcnt lgkmcnt(0)
	v_mfma_f32_16x16x32_bf16 v[112:115], v[206:209], v[144:147], 0
	v_mfma_f32_16x16x32_bf16 v[104:107], v[220:223], v[144:147], 0
	v_mfma_f32_16x16x32_bf16 v[96:99], v[206:209], v[152:155], 0
	v_mfma_f32_16x16x32_bf16 v[88:91], v[220:223], v[152:155], 0
	v_mfma_f32_16x16x32_bf16 v[80:83], v[206:209], v[174:177], 0
	v_mfma_f32_16x16x32_bf16 v[72:75], v[220:223], v[174:177], 0
	v_mfma_f32_16x16x32_bf16 v[68:71], v[206:209], v[182:185], 0
	v_mfma_f32_16x16x32_bf16 v[64:67], v[220:223], v[182:185], 0
	v_mfma_f32_16x16x32_bf16 v[112:115], v[216:219], v[148:151], v[112:115]
	v_mfma_f32_16x16x32_bf16 v[104:107], v[224:227], v[148:151], v[104:107]
	v_mfma_f32_16x16x32_bf16 v[96:99], v[216:219], v[170:173], v[96:99]
	v_mfma_f32_16x16x32_bf16 v[88:91], v[224:227], v[170:173], v[88:91]
	v_mfma_f32_16x16x32_bf16 v[80:83], v[216:219], v[178:181], v[80:83]
	v_mfma_f32_16x16x32_bf16 v[72:75], v[224:227], v[178:181], v[72:75]
	v_mfma_f32_16x16x32_bf16 v[68:71], v[216:219], v[186:189], v[68:71]
	v_mfma_f32_16x16x32_bf16 v[64:67], v[224:227], v[186:189], v[64:67]
	s_setprio 0
	s_mov_b32 m0, s88
	v_lshl_add_u64 v[232:233], s[2:3], 0, v[156:157]
	s_barrier
	ds_read_b128 v[144:147], v214 offset:16384
	ds_read_b128 v[148:151], v214 offset:17408
	ds_read_b128 v[152:155], v214 offset:18432
	ds_read_b128 v[170:173], v214 offset:19456
	ds_read_b128 v[174:177], v214 offset:20480
	ds_read_b128 v[178:181], v214 offset:21504
	ds_read_b128 v[182:185], v214 offset:22528
	ds_read_b128 v[186:189], v214 offset:23552
	global_load_lds_dwordx4 v[232:233], off
	v_lshl_add_u64 v[234:235], s[2:3], 0, v[162:163]
	s_mov_b32 m0, s89
	s_nop 0
	global_load_lds_dwordx4 v[234:235], off
	s_barrier
	s_waitcnt lgkmcnt(0)
	s_setprio 1
	s_waitcnt lgkmcnt(0)
	v_mfma_f32_16x16x32_bf16 v[60:63], v[128:131], v[144:147], 0
	v_mfma_f32_16x16x32_bf16 v[56:59], v[136:139], v[144:147], 0
	v_mfma_f32_16x16x32_bf16 v[52:55], v[128:131], v[152:155], 0
	v_mfma_f32_16x16x32_bf16 v[44:47], v[136:139], v[152:155], 0
	v_mfma_f32_16x16x32_bf16 v[36:39], v[128:131], v[174:177], 0
	v_mfma_f32_16x16x32_bf16 v[28:31], v[136:139], v[174:177], 0
	v_mfma_f32_16x16x32_bf16 v[20:23], v[128:131], v[182:185], 0
	v_mfma_f32_16x16x32_bf16 v[12:15], v[136:139], v[182:185], 0
	v_mfma_f32_16x16x32_bf16 v[60:63], v[132:135], v[148:151], v[60:63]
	v_mfma_f32_16x16x32_bf16 v[56:59], v[140:143], v[148:151], v[56:59]
	v_mfma_f32_16x16x32_bf16 v[52:55], v[132:135], v[170:173], v[52:55]
	v_mfma_f32_16x16x32_bf16 v[44:47], v[140:143], v[170:173], v[44:47]
	v_mfma_f32_16x16x32_bf16 v[36:39], v[132:135], v[178:181], v[36:39]
	v_mfma_f32_16x16x32_bf16 v[28:31], v[140:143], v[178:181], v[28:31]
	v_mfma_f32_16x16x32_bf16 v[20:23], v[132:135], v[186:189], v[20:23]
	v_mfma_f32_16x16x32_bf16 v[12:15], v[140:143], v[186:189], v[12:15]
	s_setprio 0
	s_barrier
	s_add_u32 s60, s60, s54
	s_addc_u32 s61, s61, 0
	s_add_i32 s21, s21, s53
	v_lshl_add_u64 v[236:237], s[60:61], 0, v[156:157]
	s_mov_b32 m0, s21
	v_lshl_add_u64 v[238:239], s[60:61], 0, v[162:163]
	global_load_lds_dwordx4 v[236:237], off
	s_add_i32 m0, s21, 0x2000
	s_nop 0
	global_load_lds_dwordx4 v[238:239], off
	s_waitcnt vmcnt(6)
	s_barrier
	s_setprio 1
	v_mfma_f32_16x16x32_bf16 v[48:51], v[206:209], v[144:147], 0
	v_mfma_f32_16x16x32_bf16 v[40:43], v[220:223], v[144:147], 0
	v_mfma_f32_16x16x32_bf16 v[32:35], v[206:209], v[152:155], 0
	v_mfma_f32_16x16x32_bf16 v[24:27], v[220:223], v[152:155], 0
	v_mfma_f32_16x16x32_bf16 v[16:19], v[206:209], v[174:177], 0
	v_mfma_f32_16x16x32_bf16 v[8:11], v[220:223], v[174:177], 0
	v_mfma_f32_16x16x32_bf16 v[4:7], v[206:209], v[182:185], 0
	v_mfma_f32_16x16x32_bf16 v[0:3], v[220:223], v[182:185], 0
	v_mfma_f32_16x16x32_bf16 v[48:51], v[216:219], v[148:151], v[48:51]
	v_mfma_f32_16x16x32_bf16 v[40:43], v[224:227], v[148:151], v[40:43]
	v_mfma_f32_16x16x32_bf16 v[32:35], v[216:219], v[170:173], v[32:35]
	v_mfma_f32_16x16x32_bf16 v[24:27], v[224:227], v[170:173], v[24:27]
	v_mfma_f32_16x16x32_bf16 v[16:19], v[216:219], v[178:181], v[16:19]
	v_mfma_f32_16x16x32_bf16 v[8:11], v[224:227], v[178:181], v[8:11]
	v_mfma_f32_16x16x32_bf16 v[4:7], v[216:219], v[186:189], v[4:7]
	v_mfma_f32_16x16x32_bf16 v[0:3], v[224:227], v[186:189], v[0:3]
	s_setprio 0
	s_add_i32 s21, 0, 0x18000
	v_add_u32_e32 v140, s21, v161
	s_barrier
	ds_read_b128 v[128:131], v140
	ds_read_b128 v[132:135], v140 offset:1024
	ds_read_b128 v[136:139], v140 offset:2048
	ds_read_b128 v[140:143], v140 offset:3072
	s_add_u32 s2, s2, s54
	s_addc_u32 s3, s3, 0
	s_mov_b32 m0, s94
	v_lshl_add_u64 v[206:207], s[2:3], 0, v[156:157]
	ds_read_b128 v[144:147], v214 offset:32768
	ds_read_b128 v[148:151], v214 offset:33792
	ds_read_b128 v[152:155], v214 offset:34816
	ds_read_b128 v[170:173], v214 offset:35840
	ds_read_b128 v[174:177], v214 offset:36864
	ds_read_b128 v[178:181], v214 offset:37888
	ds_read_b128 v[182:185], v214 offset:38912
	ds_read_b128 v[186:189], v214 offset:39936
	global_load_lds_dwordx4 v[206:207], off
	v_lshl_add_u64 v[206:207], s[2:3], 0, v[162:163]
	s_mov_b32 m0, s95
	s_nop 0
	global_load_lds_dwordx4 v[206:207], off
	s_waitcnt lgkmcnt(8)
	s_barrier
	s_waitcnt lgkmcnt(0)
	s_setprio 1
	s_waitcnt lgkmcnt(0)
	v_mfma_f32_16x16x32_bf16 v[124:127], v[128:131], v[144:147], v[124:127]
	v_mfma_f32_16x16x32_bf16 v[120:123], v[136:139], v[144:147], v[120:123]
	v_mfma_f32_16x16x32_bf16 v[116:119], v[128:131], v[152:155], v[116:119]
	v_mfma_f32_16x16x32_bf16 v[108:111], v[136:139], v[152:155], v[108:111]
	v_mfma_f32_16x16x32_bf16 v[100:103], v[128:131], v[174:177], v[100:103]
	v_mfma_f32_16x16x32_bf16 v[92:95], v[136:139], v[174:177], v[92:95]
	v_mfma_f32_16x16x32_bf16 v[84:87], v[128:131], v[182:185], v[84:87]
	v_mfma_f32_16x16x32_bf16 v[76:79], v[136:139], v[182:185], v[76:79]
	v_mfma_f32_16x16x32_bf16 v[124:127], v[132:135], v[148:151], v[124:127]
	v_mfma_f32_16x16x32_bf16 v[120:123], v[140:143], v[148:151], v[120:123]
	v_mfma_f32_16x16x32_bf16 v[116:119], v[132:135], v[170:173], v[116:119]
	v_mfma_f32_16x16x32_bf16 v[108:111], v[140:143], v[170:173], v[108:111]
	v_mfma_f32_16x16x32_bf16 v[100:103], v[132:135], v[178:181], v[100:103]
	v_mfma_f32_16x16x32_bf16 v[92:95], v[140:143], v[178:181], v[92:95]
	v_mfma_f32_16x16x32_bf16 v[84:87], v[132:135], v[186:189], v[84:87]
	v_mfma_f32_16x16x32_bf16 v[76:79], v[140:143], v[186:189], v[76:79]
	s_setprio 0
	s_barrier
	s_add_i32 s2, 0, 0x1c000
	s_add_i32 s3, s21, s53
	v_add_u32_e32 v215, s2, v161
	v_lshl_add_u64 v[228:229], v[228:229], 0, s[50:51]
	s_mov_b32 m0, s3
	ds_read_b128 v[206:209], v215
	ds_read_b128 v[216:219], v215 offset:1024
	ds_read_b128 v[220:223], v215 offset:2048
	ds_read_b128 v[224:227], v215 offset:3072
	global_load_lds_dwordx4 v[228:229], off
	v_lshl_add_u64 v[228:229], v[230:231], 0, s[50:51]
	s_add_i32 m0, s3, 0x2000
	s_nop 0
	global_load_lds_dwordx4 v[228:229], off
	s_barrier
	s_waitcnt lgkmcnt(0)
	s_setprio 1
	s_waitcnt lgkmcnt(0)
	v_mfma_f32_16x16x32_bf16 v[112:115], v[206:209], v[144:147], v[112:115]
	v_mfma_f32_16x16x32_bf16 v[104:107], v[220:223], v[144:147], v[104:107]
	v_mfma_f32_16x16x32_bf16 v[96:99], v[206:209], v[152:155], v[96:99]
	v_mfma_f32_16x16x32_bf16 v[88:91], v[220:223], v[152:155], v[88:91]
	v_mfma_f32_16x16x32_bf16 v[80:83], v[206:209], v[174:177], v[80:83]
	v_mfma_f32_16x16x32_bf16 v[72:75], v[220:223], v[174:177], v[72:75]
	v_mfma_f32_16x16x32_bf16 v[68:71], v[206:209], v[182:185], v[68:71]
	v_mfma_f32_16x16x32_bf16 v[64:67], v[220:223], v[182:185], v[64:67]
	v_mfma_f32_16x16x32_bf16 v[112:115], v[216:219], v[148:151], v[112:115]
	v_mfma_f32_16x16x32_bf16 v[104:107], v[224:227], v[148:151], v[104:107]
	v_mfma_f32_16x16x32_bf16 v[96:99], v[216:219], v[170:173], v[96:99]
	v_mfma_f32_16x16x32_bf16 v[88:91], v[224:227], v[170:173], v[88:91]
	v_mfma_f32_16x16x32_bf16 v[80:83], v[216:219], v[178:181], v[80:83]
	v_mfma_f32_16x16x32_bf16 v[72:75], v[224:227], v[178:181], v[72:75]
	v_mfma_f32_16x16x32_bf16 v[68:71], v[216:219], v[186:189], v[68:71]
	v_mfma_f32_16x16x32_bf16 v[64:67], v[224:227], v[186:189], v[64:67]
	s_setprio 0
	s_mov_b32 m0, s96
	v_lshl_add_u64 v[228:229], v[232:233], 0, s[50:51]
	s_barrier
	ds_read_b128 v[144:147], v214 offset:49152
	ds_read_b128 v[148:151], v214 offset:50176
	ds_read_b128 v[152:155], v214 offset:51200
	ds_read_b128 v[170:173], v214 offset:52224
	ds_read_b128 v[174:177], v214 offset:53248
	ds_read_b128 v[178:181], v214 offset:54272
	ds_read_b128 v[182:185], v214 offset:55296
	ds_read_b128 v[186:189], v214 offset:56320
	global_load_lds_dwordx4 v[228:229], off
	v_lshl_add_u64 v[228:229], v[234:235], 0, s[50:51]
	s_mov_b32 m0, s97
	s_nop 0
	global_load_lds_dwordx4 v[228:229], off
	s_barrier
	s_waitcnt lgkmcnt(0)
	s_setprio 1
	s_waitcnt lgkmcnt(0)
	v_mfma_f32_16x16x32_bf16 v[60:63], v[128:131], v[144:147], v[60:63]
	v_mfma_f32_16x16x32_bf16 v[56:59], v[136:139], v[144:147], v[56:59]
	v_mfma_f32_16x16x32_bf16 v[52:55], v[128:131], v[152:155], v[52:55]
	v_mfma_f32_16x16x32_bf16 v[44:47], v[136:139], v[152:155], v[44:47]
	v_mfma_f32_16x16x32_bf16 v[36:39], v[128:131], v[174:177], v[36:39]
	v_mfma_f32_16x16x32_bf16 v[28:31], v[136:139], v[174:177], v[28:31]
	v_mfma_f32_16x16x32_bf16 v[20:23], v[128:131], v[182:185], v[20:23]
	v_mfma_f32_16x16x32_bf16 v[12:15], v[136:139], v[182:185], v[12:15]
	v_mfma_f32_16x16x32_bf16 v[60:63], v[132:135], v[148:151], v[60:63]
	v_mfma_f32_16x16x32_bf16 v[56:59], v[140:143], v[148:151], v[56:59]
	v_mfma_f32_16x16x32_bf16 v[52:55], v[132:135], v[170:173], v[52:55]
	v_mfma_f32_16x16x32_bf16 v[44:47], v[140:143], v[170:173], v[44:47]
	v_mfma_f32_16x16x32_bf16 v[36:39], v[132:135], v[178:181], v[36:39]
	v_mfma_f32_16x16x32_bf16 v[28:31], v[140:143], v[178:181], v[28:31]
	v_mfma_f32_16x16x32_bf16 v[20:23], v[132:135], v[186:189], v[20:23]
	v_mfma_f32_16x16x32_bf16 v[12:15], v[140:143], v[186:189], v[12:15]
	s_setprio 0
	s_barrier
	s_add_i32 s2, s2, s53
	v_lshl_add_u64 v[128:129], v[236:237], 0, s[50:51]
	s_mov_b32 m0, s2
	s_nop 0
	global_load_lds_dwordx4 v[128:129], off
	v_lshl_add_u64 v[128:129], v[238:239], 0, s[50:51]
	s_add_i32 m0, s2, 0x2000
	s_nop 0
	global_load_lds_dwordx4 v[128:129], off
	s_waitcnt vmcnt(6)
	s_barrier
	s_setprio 1
	v_mfma_f32_16x16x32_bf16 v[48:51], v[206:209], v[144:147], v[48:51]
	v_mfma_f32_16x16x32_bf16 v[40:43], v[220:223], v[144:147], v[40:43]
	v_mfma_f32_16x16x32_bf16 v[32:35], v[206:209], v[152:155], v[32:35]
	v_mfma_f32_16x16x32_bf16 v[24:27], v[220:223], v[152:155], v[24:27]
	v_mfma_f32_16x16x32_bf16 v[16:19], v[206:209], v[174:177], v[16:19]
	v_mfma_f32_16x16x32_bf16 v[8:11], v[220:223], v[174:177], v[8:11]
	v_mfma_f32_16x16x32_bf16 v[4:7], v[206:209], v[182:185], v[4:7]
	v_mfma_f32_16x16x32_bf16 v[0:3], v[220:223], v[182:185], v[0:3]
	v_mfma_f32_16x16x32_bf16 v[48:51], v[216:219], v[148:151], v[48:51]
	v_mfma_f32_16x16x32_bf16 v[40:43], v[224:227], v[148:151], v[40:43]
	v_mfma_f32_16x16x32_bf16 v[32:35], v[216:219], v[170:173], v[32:35]
	v_mfma_f32_16x16x32_bf16 v[24:27], v[224:227], v[170:173], v[24:27]
	v_mfma_f32_16x16x32_bf16 v[16:19], v[216:219], v[178:181], v[16:19]
	v_mfma_f32_16x16x32_bf16 v[8:11], v[224:227], v[178:181], v[8:11]
	v_mfma_f32_16x16x32_bf16 v[4:7], v[216:219], v[186:189], v[4:7]
	v_mfma_f32_16x16x32_bf16 v[0:3], v[224:227], v[186:189], v[0:3]
	s_setprio 0
	s_add_u32 s83, s83, 0x100
	s_addc_u32 vcc_lo, vcc_lo, 0
	s_add_u32 s6, s6, 0x100
	s_addc_u32 s7, s7, 0
	s_cmp_ge_u32 vcc_hi, s84
	s_mov_b32 s2, vcc_hi
	s_barrier
	s_cbranch_scc1 .Lpost_514

.Lpost_514:
	s_min_i32 s2, s85, 0x80
	s_ashr_i32 s2, s2, 4
	s_lshl_b32 s84, s85, 8
	s_mul_hi_i32 s3, s2, 0x9000
	s_mul_i32 s2, s2, 0x9000
	s_add_u32 s2, s42, s2
	v_lshl_or_b32 v144, s24, 8, v213
	s_addc_u32 s3, s43, s3
	v_ashrrev_i32_e32 v145, 31, v144
	v_lshl_add_u64 v[140:141], v[144:145], 2, s[2:3]
	global_load_dwordx4 v[128:131], v[140:141], off
	global_load_dwordx4 v[132:135], v[140:141], off offset:64
	global_load_dwordx4 v[136:139], v[140:141], off offset:512
	s_nop 0
	global_load_dwordx4 v[140:143], v[140:141], off offset:576
	v_lshl_add_u64 v[170:171], v[164:165], 0, v[144:145]
	s_cmpk_lt_i32 s85, 0x80
	s_mov_b64 s[2:3], -1
	s_waitcnt vmcnt(0)
	v_pk_mul_f32 v[184:185], s[68:69], v[130:131]
	v_pk_mul_f32 v[186:187], s[46:47], v[128:129]
	v_pk_mul_f32 v[180:181], s[68:69], v[134:135]
	v_pk_mul_f32 v[182:183], s[46:47], v[132:133]
	v_pk_mul_f32 v[176:177], s[68:69], v[138:139]
	v_pk_mul_f32 v[178:179], s[46:47], v[136:137]
	v_pk_mul_f32 v[172:173], s[68:69], v[142:143]
	v_pk_mul_f32 v[174:175], s[46:47], v[140:141]
	s_cbranch_scc0 .LBB0_517
	s_ashr_i32 s85, s84, 31
	s_lshl_b64 s[2:3], s[84:85], 12
	s_add_u32 s6, s62, s2
	s_addc_u32 s7, s63, s3
	v_lshlrev_b64 v[128:129], 2, v[170:171]
	v_lshl_add_u64 v[140:141], s[6:7], 0, v[128:129]
	s_add_u32 s82, s66, s2
	global_load_dwordx4 v[142:145], v[140:141], off
	global_load_dwordx4 v[146:149], v[140:141], off offset:64
	global_load_dwordx4 v[150:153], v[140:141], off offset:512
	global_load_dwordx4 v[216:219], v[140:141], off offset:576
	s_addc_u32 s83, s67, s3
	s_mov_b32 s2, 0x10000
	v_lshl_add_u64 v[188:189], s[82:83], 0, v[128:129]
	v_add_co_u32_e32 v128, vcc, s2, v140
	s_mov_b32 s3, 0x20000
	s_nop 0
	v_addc_co_u32_e32 v129, vcc, 0, v141, vcc
	global_load_dwordx4 v[220:223], v[128:129], off
	global_load_dwordx4 v[224:227], v[128:129], off offset:64
	global_load_dwordx4 v[228:231], v[128:129], off offset:512
	global_load_dwordx4 v[232:235], v[128:129], off offset:576
	v_add_co_u32_e32 v128, vcc, s3, v140
	s_mov_b32 s6, 0x30000
	s_nop 0
	v_addc_co_u32_e32 v129, vcc, 0, v141, vcc
	global_load_dwordx4 v[236:239], v[128:129], off
	global_load_dwordx4 v[240:243], v[128:129], off offset:64
	global_load_dwordx4 v[244:247], v[128:129], off offset:512
	global_load_dwordx4 v[248:251], v[128:129], off offset:576
	v_add_co_u32_e32 v128, vcc, s6, v140
	s_mov_b32 s7, 0xb0000
	s_nop 0
	v_addc_co_u32_e32 v129, vcc, 0, v141, vcc
	global_load_dwordx4 v[206:209], v[128:129], off
	global_load_dwordx4 v[136:139], v[128:129], off offset:64
	global_load_dwordx4 v[132:135], v[128:129], off offset:512
	s_nop 0
	global_load_dwordx4 v[128:131], v[128:129], off offset:576
	s_waitcnt vmcnt(0)
	v_pk_fma_f32 v[144:145], v[126:127], v[184:185], v[144:145]
	v_pk_fma_f32 v[142:143], v[124:125], v[186:187], v[142:143]
	global_store_dwordx4 v[188:189], v[142:145], off
	v_pk_fma_f32 v[138:139], v[78:79], v[180:181], v[138:139]
	s_nop 0
	v_pk_fma_f32 v[144:145], v[122:123], v[180:181], v[148:149]
	v_pk_fma_f32 v[142:143], v[120:121], v[182:183], v[146:147]
	global_store_dwordx4 v[188:189], v[142:145], off offset:64
	v_add_co_u32_e32 v146, vcc, s2, v188
	s_nop 0
	v_pk_fma_f32 v[144:145], v[114:115], v[176:177], v[152:153]
	v_pk_fma_f32 v[142:143], v[112:113], v[178:179], v[150:151]
	global_store_dwordx4 v[188:189], v[142:145], off offset:512
	v_addc_co_u32_e32 v147, vcc, 0, v189, vcc
	s_nop 0
	v_pk_fma_f32 v[144:145], v[106:107], v[172:173], v[218:219]
	v_pk_fma_f32 v[142:143], v[104:105], v[174:175], v[216:217]
	global_store_dwordx4 v[188:189], v[142:145], off offset:576
	v_pk_fma_f32 v[130:131], v[66:67], v[172:173], v[130:131]
	v_pk_fma_f32 v[128:129], v[64:65], v[174:175], v[128:129]
	v_pk_fma_f32 v[144:145], v[118:119], v[184:185], v[222:223]
	v_pk_fma_f32 v[142:143], v[116:117], v[186:187], v[220:221]
	global_store_dwordx4 v[146:147], v[142:145], off
	s_mov_b32 s2, 0x80000
	v_pk_fma_f32 v[136:137], v[76:77], v[182:183], v[136:137]
	v_pk_fma_f32 v[144:145], v[110:111], v[180:181], v[226:227]
	v_pk_fma_f32 v[142:143], v[108:109], v[182:183], v[224:225]
	global_store_dwordx4 v[146:147], v[142:145], off offset:64
	v_pk_fma_f32 v[134:135], v[70:71], v[176:177], v[134:135]
	v_pk_fma_f32 v[132:133], v[68:69], v[178:179], v[132:133]
	v_pk_fma_f32 v[144:145], v[98:99], v[176:177], v[230:231]
	v_pk_fma_f32 v[142:143], v[96:97], v[178:179], v[228:229]
	global_store_dwordx4 v[146:147], v[142:145], off offset:512
	s_nop 1
	v_pk_fma_f32 v[144:145], v[90:91], v[172:173], v[234:235]
	v_pk_fma_f32 v[142:143], v[88:89], v[174:175], v[232:233]
	global_store_dwordx4 v[146:147], v[142:145], off offset:576
	v_add_co_u32_e32 v146, vcc, s3, v188
	s_nop 0
	v_pk_fma_f32 v[144:145], v[102:103], v[184:185], v[238:239]
	v_pk_fma_f32 v[142:143], v[100:101], v[186:187], v[236:237]
	v_addc_co_u32_e32 v147, vcc, 0, v189, vcc
	global_store_dwordx4 v[146:147], v[142:145], off
	s_mov_b32 s3, 0x90000
	s_nop 0
	v_pk_fma_f32 v[144:145], v[94:95], v[180:181], v[242:243]
	v_pk_fma_f32 v[142:143], v[92:93], v[182:183], v[240:241]
	global_store_dwordx4 v[146:147], v[142:145], off offset:64
	s_nop 1
	v_pk_fma_f32 v[144:145], v[82:83], v[176:177], v[246:247]
	v_pk_fma_f32 v[142:143], v[80:81], v[178:179], v[244:245]
	global_store_dwordx4 v[146:147], v[142:145], off offset:512
	s_nop 1
	v_pk_fma_f32 v[144:145], v[74:75], v[172:173], v[250:251]
	v_pk_fma_f32 v[142:143], v[72:73], v[174:175], v[248:249]
	global_store_dwordx4 v[146:147], v[142:145], off offset:576
	v_add_co_u32_e32 v146, vcc, s6, v188
	s_nop 0
	v_pk_fma_f32 v[144:145], v[86:87], v[184:185], v[208:209]
	v_addc_co_u32_e32 v147, vcc, 0, v189, vcc
	v_pk_fma_f32 v[142:143], v[84:85], v[186:187], v[206:207]
	global_store_dwordx4 v[146:147], v[128:131], off offset:576
	global_store_dwordx4 v[146:147], v[142:145], off
	global_store_dwordx4 v[146:147], v[136:139], off offset:64
	v_add_co_u32_e32 v128, vcc, s2, v140
	global_store_dwordx4 v[146:147], v[132:135], off offset:512
	s_nop 0
	v_addc_co_u32_e32 v129, vcc, 0, v141, vcc
	global_load_dwordx4 v[206:209], v[128:129], off
	global_load_dwordx4 v[216:219], v[128:129], off offset:64
	global_load_dwordx4 v[220:223], v[128:129], off offset:512
	global_load_dwordx4 v[224:227], v[128:129], off offset:576
	v_add_co_u32_e32 v128, vcc, s3, v140
	s_mov_b32 s6, 0xa0000
	s_nop 0
	v_addc_co_u32_e32 v129, vcc, 0, v141, vcc
	global_load_dwordx4 v[228:231], v[128:129], off
	global_load_dwordx4 v[232:235], v[128:129], off offset:64
	global_load_dwordx4 v[236:239], v[128:129], off offset:512
	global_load_dwordx4 v[240:243], v[128:129], off offset:576
	v_add_co_u32_e32 v128, vcc, s6, v140
	s_waitcnt vmcnt(0)
	v_pk_fma_f32 v[208:209], v[62:63], v[184:185], v[208:209]
	v_addc_co_u32_e32 v129, vcc, 0, v141, vcc
	global_load_dwordx4 v[244:247], v[128:129], off
	global_load_dwordx4 v[152:155], v[128:129], off offset:64
	global_load_dwordx4 v[148:151], v[128:129], off offset:512
	global_load_dwordx4 v[144:147], v[128:129], off offset:576
	v_add_co_u32_e32 v128, vcc, s7, v140
	v_pk_fma_f32 v[206:207], v[60:61], v[186:187], v[206:207]
	s_nop 0
	v_addc_co_u32_e32 v129, vcc, 0, v141, vcc
	global_load_dwordx4 v[140:143], v[128:129], off
	global_load_dwordx4 v[136:139], v[128:129], off offset:64
	global_load_dwordx4 v[132:135], v[128:129], off offset:512
	s_nop 0
	global_load_dwordx4 v[128:131], v[128:129], off offset:576
	v_add_co_u32_e32 v248, vcc, s2, v188
	s_waitcnt vmcnt(0)
	v_pk_fma_f32 v[154:155], v[30:31], v[180:181], v[154:155]
	v_addc_co_u32_e32 v249, vcc, 0, v189, vcc
	global_store_dwordx4 v[248:249], v[206:209], off
	v_pk_fma_f32 v[146:147], v[10:11], v[172:173], v[146:147]
	v_pk_fma_f32 v[144:145], v[8:9], v[174:175], v[144:145]
	v_pk_fma_f32 v[208:209], v[58:59], v[180:181], v[218:219]
	v_pk_fma_f32 v[206:207], v[56:57], v[182:183], v[216:217]
	global_store_dwordx4 v[248:249], v[206:209], off offset:64
	v_add_co_u32_e32 v216, vcc, s3, v188
	s_nop 0
	v_pk_fma_f32 v[208:209], v[50:51], v[176:177], v[222:223]
	v_pk_fma_f32 v[206:207], v[48:49], v[178:179], v[220:221]
	global_store_dwordx4 v[248:249], v[206:209], off offset:512
	v_addc_co_u32_e32 v217, vcc, 0, v189, vcc
	s_nop 0
	v_pk_fma_f32 v[208:209], v[42:43], v[172:173], v[226:227]
	v_pk_fma_f32 v[206:207], v[40:41], v[174:175], v[224:225]
	global_store_dwordx4 v[248:249], v[206:209], off offset:576
	v_pk_fma_f32 v[152:153], v[28:29], v[182:183], v[152:153]
	v_pk_fma_f32 v[150:151], v[18:19], v[176:177], v[150:151]
	v_pk_fma_f32 v[208:209], v[54:55], v[184:185], v[230:231]
	v_pk_fma_f32 v[206:207], v[52:53], v[186:187], v[228:229]
	global_store_dwordx4 v[216:217], v[206:209], off
	v_pk_fma_f32 v[148:149], v[16:17], v[178:179], v[148:149]
	v_pk_fma_f32 v[142:143], v[22:23], v[184:185], v[142:143]
	v_pk_fma_f32 v[208:209], v[46:47], v[180:181], v[234:235]
	v_pk_fma_f32 v[206:207], v[44:45], v[182:183], v[232:233]
	global_store_dwordx4 v[216:217], v[206:209], off offset:64
	v_pk_fma_f32 v[140:141], v[20:21], v[186:187], v[140:141]
	v_pk_fma_f32 v[138:139], v[14:15], v[180:181], v[138:139]
	v_pk_fma_f32 v[208:209], v[34:35], v[176:177], v[238:239]
	v_pk_fma_f32 v[206:207], v[32:33], v[178:179], v[236:237]
	global_store_dwordx4 v[216:217], v[206:209], off offset:512
	v_pk_fma_f32 v[136:137], v[12:13], v[182:183], v[136:137]
	v_pk_fma_f32 v[134:135], v[6:7], v[176:177], v[134:135]
	v_pk_fma_f32 v[208:209], v[26:27], v[172:173], v[242:243]
	v_pk_fma_f32 v[206:207], v[24:25], v[174:175], v[240:241]
	global_store_dwordx4 v[216:217], v[206:209], off offset:576
	v_add_co_u32_e32 v216, vcc, s6, v188
	s_nop 0
	v_pk_fma_f32 v[208:209], v[38:39], v[184:185], v[246:247]
	v_addc_co_u32_e32 v217, vcc, 0, v189, vcc
	global_store_dwordx4 v[216:217], v[144:147], off offset:576
	v_pk_fma_f32 v[206:207], v[36:37], v[186:187], v[244:245]
	v_pk_fma_f32 v[132:133], v[4:5], v[178:179], v[132:133]
	v_add_co_u32_e32 v144, vcc, s7, v188
	global_store_dwordx4 v[216:217], v[206:209], off
	s_nop 0
	v_addc_co_u32_e32 v145, vcc, 0, v189, vcc
	global_store_dwordx4 v[216:217], v[152:155], off offset:64
	global_store_dwordx4 v[216:217], v[148:151], off offset:512
	global_store_dwordx4 v[144:145], v[140:143], off
	global_store_dwordx4 v[144:145], v[136:139], off offset:64
	global_store_dwordx4 v[144:145], v[132:135], off offset:512
	v_pk_fma_f32 v[130:131], v[2:3], v[172:173], v[130:131]
	v_pk_fma_f32 v[128:129], v[0:1], v[174:175], v[128:129]
	s_mov_b64 s[2:3], 0

.LBB0_554:
	s_add_i32 s68, s68, 1
	s_mul_i32 s2, s68, s18
	s_add_i32 s10, s2, s20
	s_cmp_lt_i32 s10, s19
	s_cselect_b64 s[2:3], -1, 0
	s_cmp_ge_i32 s10, s19
	s_cselect_b64 s[38:39], -1, 0
	s_and_b64 s[6:7], s[2:3], exec
	s_cselect_b32 s6, s10, 0
	s_ashr_i32 s7, s6, 31
	s_lshr_b32 s7, s7, 29
	s_add_i32 s7, s6, s7
	s_ashr_i32 s10, s7, 3
	s_and_b32 s7, s7, -8
	s_sub_i32 s6, s6, s7
	s_cmp_lt_i32 s6, 0
	s_cselect_b32 s7, s61, s60
	s_mul_i32 s6, s7, s6
	s_add_i32 s10, s6, s10
	s_mul_hi_i32 s6, s10, 0x2e8ba2e9
	s_lshr_b32 s7, s6, 31
	s_ashr_i32 s6, s6, 4
	s_add_i32 s24, s6, s7
	s_lshl_b32 s25, s24, 2
	s_sub_i32 s6, s9, s25
	s_min_i32 s41, s6, 4
	s_abs_i32 s40, s41
	v_cvt_f32_u32_e32 v0, s40
	s_mov_b64 s[6:7], s[34:35]
	s_mov_b64 s[54:55], s[36:37]
	s_sub_i32 s35, 0, s40
	v_rcp_iflag_f32_e32 v0, v0
	s_mulk_i32 s24, 0x58
	s_sub_i32 s10, s10, s24
	s_abs_i32 s34, s10
	v_mul_f32_e32 v0, 0x4f7ffffe, v0
	v_cvt_u32_f32_e32 v0, v0
	s_xor_b32 s24, s10, s41
	s_ashr_i32 s24, s24, 31
	s_mov_b32 s73, -2
	v_readfirstlane_b32 s36, v0
	s_mul_i32 s35, s35, s36
	s_mul_hi_u32 s35, s36, s35
	s_add_i32 s36, s36, s35
	s_mul_hi_u32 s35, s34, s36
	s_mul_i32 s36, s35, s40
	s_sub_i32 s34, s34, s36
	s_add_i32 s36, s35, 1
	s_sub_i32 s37, s34, s40
	s_cmp_ge_u32 s34, s40
	s_cselect_b32 s35, s36, s35
	s_cselect_b32 s34, s37, s34
	s_add_i32 s36, s35, 1
	s_cmp_ge_u32 s34, s40
	s_cselect_b32 s34, s36, s35
	s_xor_b32 s34, s34, s24
	s_sub_i32 s40, s34, s24
	s_mul_i32 s24, s40, s41
	s_sub_i32 s10, s10, s24
	s_add_i32 s42, s25, s10
	s_ashr_i32 s43, s42, 31
	s_lshl_b64 s[24:25], s[42:43], 19
	s_add_u32 s34, s58, s24
	s_addc_u32 s35, s59, s25
	s_and_b64 s[24:25], s[2:3], exec
	s_cselect_b32 s10, s35, s7
	s_cselect_b32 s24, s34, s6
	s_ashr_i32 s41, s40, 31
	s_lshl_b64 s[36:37], s[40:41], 19
	s_add_u32 s36, s44, s36
	s_addc_u32 s37, s45, s37
	s_and_b64 s[2:3], s[2:3], exec
	s_cselect_b32 s25, s37, s55
	s_cselect_b32 s41, s36, s54
	s_add_u32 s43, s54, 0x100
	s_addc_u32 s69, s55, 0
	s_add_u32 s6, s6, 0x40080
	s_addc_u32 s7, s7, 0
	s_add_u32 s2, s6, 0xfffc0080
	s_addc_u32 s3, s7, -1
	s_add_i32 s77, 0, 0x10000
	v_add_u32_e32 v150, s77, v139
	ds_read_b128 v[134:137], v150
	ds_read_b128 v[142:145], v150 offset:1024
	ds_read_b128 v[146:149], v150 offset:2048
	ds_read_b128 v[150:153], v150 offset:3072
	s_cmp_eq_u32 s73, 12
	s_cselect_b32 s3, s10, s3
	s_cselect_b32 s2, s24, s2
	s_cselect_b32 s55, s25, s69
	s_cselect_b32 s54, s41, s43
	v_lshl_add_u64 v[154:155], s[6:7], 0, v[132:133]
	s_add_i32 m0, s47, 0xc000
	ds_read_b128 v[162:165], v141
	ds_read_b128 v[166:169], v141 offset:1024
	ds_read_b128 v[170:173], v141 offset:2048
	ds_read_b128 v[174:177], v141 offset:3072
	ds_read_b128 v[178:181], v141 offset:4096
	ds_read_b128 v[182:185], v141 offset:5120
	ds_read_b128 v[186:189], v141 offset:6144
	ds_read_b128 v[214:217], v141 offset:7168
	global_load_lds_dwordx4 v[154:155], off
	v_lshl_add_u64 v[154:155], s[6:7], 0, v[130:131]
	s_add_i32 m0, s47, 0xe000
	s_nop 0
	global_load_lds_dwordx4 v[154:155], off
	s_waitcnt lgkmcnt(8)
	s_barrier
	s_waitcnt lgkmcnt(0)
	s_setprio 1
	s_waitcnt lgkmcnt(0)
	v_mfma_f32_16x16x32_bf16 v[124:127], v[134:137], v[162:165], 0
	v_mfma_f32_16x16x32_bf16 v[116:119], v[146:149], v[162:165], 0
	v_mfma_f32_16x16x32_bf16 v[108:111], v[134:137], v[170:173], 0
	v_mfma_f32_16x16x32_bf16 v[100:103], v[146:149], v[170:173], 0
	v_mfma_f32_16x16x32_bf16 v[92:95], v[134:137], v[178:181], 0
	v_mfma_f32_16x16x32_bf16 v[84:87], v[146:149], v[178:181], 0
	v_mfma_f32_16x16x32_bf16 v[76:79], v[134:137], v[186:189], 0
	v_mfma_f32_16x16x32_bf16 v[68:71], v[146:149], v[186:189], 0
	v_mfma_f32_16x16x32_bf16 v[124:127], v[142:145], v[166:169], v[124:127]
	v_mfma_f32_16x16x32_bf16 v[116:119], v[150:153], v[166:169], v[116:119]
	v_mfma_f32_16x16x32_bf16 v[108:111], v[142:145], v[174:177], v[108:111]
	v_mfma_f32_16x16x32_bf16 v[100:103], v[150:153], v[174:177], v[100:103]
	v_mfma_f32_16x16x32_bf16 v[92:95], v[142:145], v[182:185], v[92:95]
	v_mfma_f32_16x16x32_bf16 v[84:87], v[150:153], v[182:185], v[84:87]
	v_mfma_f32_16x16x32_bf16 v[76:79], v[142:145], v[214:217], v[76:79]
	v_mfma_f32_16x16x32_bf16 v[68:71], v[150:153], v[214:217], v[68:71]
	s_setprio 0
	s_barrier
	s_add_i32 s80, 0, 0x14000
	v_add_u32_e32 v154, s80, v139
	s_add_i32 s77, s77, s53
	ds_read_b128 v[218:221], v154
	ds_read_b128 v[222:225], v154 offset:1024
	ds_read_b128 v[226:229], v154 offset:2048
	ds_read_b128 v[230:233], v154 offset:3072
	v_lshl_add_u64 v[154:155], s[54:55], 0, v[156:157]
	s_mov_b32 m0, s77
	v_lshl_add_u64 v[206:207], s[54:55], 0, v[128:129]
	global_load_lds_dwordx4 v[154:155], off
	s_add_i32 m0, s77, 0x2000
	s_nop 0
	global_load_lds_dwordx4 v[206:207], off
	s_barrier
	s_waitcnt lgkmcnt(0)
	s_setprio 1
	s_waitcnt lgkmcnt(0)
	v_mfma_f32_16x16x32_bf16 v[120:123], v[218:221], v[162:165], 0
	v_mfma_f32_16x16x32_bf16 v[112:115], v[226:229], v[162:165], 0
	v_mfma_f32_16x16x32_bf16 v[104:107], v[218:221], v[170:173], 0
	v_mfma_f32_16x16x32_bf16 v[96:99], v[226:229], v[170:173], 0
	v_mfma_f32_16x16x32_bf16 v[88:91], v[218:221], v[178:181], 0
	v_mfma_f32_16x16x32_bf16 v[80:83], v[226:229], v[178:181], 0
	v_mfma_f32_16x16x32_bf16 v[72:75], v[218:221], v[186:189], 0
	v_mfma_f32_16x16x32_bf16 v[64:67], v[226:229], v[186:189], 0
	v_mfma_f32_16x16x32_bf16 v[120:123], v[222:225], v[166:169], v[120:123]
	v_mfma_f32_16x16x32_bf16 v[112:115], v[230:233], v[166:169], v[112:115]
	v_mfma_f32_16x16x32_bf16 v[104:107], v[222:225], v[174:177], v[104:107]
	v_mfma_f32_16x16x32_bf16 v[96:99], v[230:233], v[174:177], v[96:99]
	v_mfma_f32_16x16x32_bf16 v[88:91], v[222:225], v[182:185], v[88:91]
	v_mfma_f32_16x16x32_bf16 v[80:83], v[230:233], v[182:185], v[80:83]
	v_mfma_f32_16x16x32_bf16 v[72:75], v[222:225], v[214:217], v[72:75]
	v_mfma_f32_16x16x32_bf16 v[64:67], v[230:233], v[214:217], v[64:67]
	s_setprio 0
	s_mov_b32 m0, s47
	v_lshl_add_u64 v[208:209], s[2:3], 0, v[156:157]
	s_barrier
	ds_read_b128 v[162:165], v141 offset:16384
	ds_read_b128 v[166:169], v141 offset:17408
	ds_read_b128 v[170:173], v141 offset:18432
	ds_read_b128 v[174:177], v141 offset:19456
	ds_read_b128 v[178:181], v141 offset:20480
	ds_read_b128 v[182:185], v141 offset:21504
	ds_read_b128 v[186:189], v141 offset:22528
	ds_read_b128 v[214:217], v141 offset:23552
	global_load_lds_dwordx4 v[208:209], off
	v_lshl_add_u64 v[234:235], s[2:3], 0, v[128:129]
	s_mov_b32 m0, s49
	s_nop 0
	global_load_lds_dwordx4 v[234:235], off
	s_barrier
	s_waitcnt lgkmcnt(0)
	s_setprio 1
	s_waitcnt lgkmcnt(0)
	v_mfma_f32_16x16x32_bf16 v[60:63], v[134:137], v[162:165], 0
	v_mfma_f32_16x16x32_bf16 v[52:55], v[146:149], v[162:165], 0
	v_mfma_f32_16x16x32_bf16 v[44:47], v[134:137], v[170:173], 0
	v_mfma_f32_16x16x32_bf16 v[36:39], v[146:149], v[170:173], 0
	v_mfma_f32_16x16x32_bf16 v[28:31], v[134:137], v[178:181], 0
	v_mfma_f32_16x16x32_bf16 v[20:23], v[146:149], v[178:181], 0
	v_mfma_f32_16x16x32_bf16 v[12:15], v[134:137], v[186:189], 0
	v_mfma_f32_16x16x32_bf16 v[4:7], v[146:149], v[186:189], 0
	v_mfma_f32_16x16x32_bf16 v[60:63], v[142:145], v[166:169], v[60:63]
	v_mfma_f32_16x16x32_bf16 v[52:55], v[150:153], v[166:169], v[52:55]
	v_mfma_f32_16x16x32_bf16 v[44:47], v[142:145], v[174:177], v[44:47]
	v_mfma_f32_16x16x32_bf16 v[36:39], v[150:153], v[174:177], v[36:39]
	v_mfma_f32_16x16x32_bf16 v[28:31], v[142:145], v[182:185], v[28:31]
	v_mfma_f32_16x16x32_bf16 v[20:23], v[150:153], v[182:185], v[20:23]
	v_mfma_f32_16x16x32_bf16 v[12:15], v[142:145], v[214:217], v[12:15]
	v_mfma_f32_16x16x32_bf16 v[4:7], v[150:153], v[214:217], v[4:7]
	s_setprio 0
	s_barrier
	s_add_u32 s78, s54, 0x40000
	s_addc_u32 s79, s55, 0
	s_add_i32 s77, s80, s53
	v_lshl_add_u64 v[134:135], s[78:79], 0, v[156:157]
	s_mov_b32 m0, s77
	s_nop 0
	global_load_lds_dwordx4 v[134:135], off
	v_lshl_add_u64 v[134:135], s[78:79], 0, v[128:129]
	s_add_i32 m0, s77, 0x2000
	s_nop 0
	global_load_lds_dwordx4 v[134:135], off
	s_waitcnt vmcnt(6)
	s_barrier
	s_setprio 1
	v_mfma_f32_16x16x32_bf16 v[56:59], v[218:221], v[162:165], 0
	v_mfma_f32_16x16x32_bf16 v[48:51], v[226:229], v[162:165], 0
	v_mfma_f32_16x16x32_bf16 v[40:43], v[218:221], v[170:173], 0
	v_mfma_f32_16x16x32_bf16 v[32:35], v[226:229], v[170:173], 0
	v_mfma_f32_16x16x32_bf16 v[24:27], v[218:221], v[178:181], 0
	v_mfma_f32_16x16x32_bf16 v[16:19], v[226:229], v[178:181], 0
	v_mfma_f32_16x16x32_bf16 v[8:11], v[218:221], v[186:189], 0
	v_mfma_f32_16x16x32_bf16 v[0:3], v[226:229], v[186:189], 0
	v_mfma_f32_16x16x32_bf16 v[56:59], v[222:225], v[166:169], v[56:59]
	v_mfma_f32_16x16x32_bf16 v[48:51], v[230:233], v[166:169], v[48:51]
	v_mfma_f32_16x16x32_bf16 v[40:43], v[222:225], v[174:177], v[40:43]
	v_mfma_f32_16x16x32_bf16 v[32:35], v[230:233], v[174:177], v[32:35]
	v_mfma_f32_16x16x32_bf16 v[24:27], v[222:225], v[182:185], v[24:27]
	v_mfma_f32_16x16x32_bf16 v[16:19], v[230:233], v[182:185], v[16:19]
	v_mfma_f32_16x16x32_bf16 v[8:11], v[222:225], v[214:217], v[8:11]
	v_mfma_f32_16x16x32_bf16 v[0:3], v[230:233], v[214:217], v[0:3]
	s_setprio 0
	s_add_i32 s77, 0, 0x18000
	v_add_u32_e32 v150, s77, v139
	s_barrier
	ds_read_b128 v[134:137], v150
	ds_read_b128 v[142:145], v150 offset:1024
	ds_read_b128 v[146:149], v150 offset:2048
	ds_read_b128 v[150:153], v150 offset:3072
	s_add_u32 s2, s2, 0x40000
	s_addc_u32 s3, s3, 0
	s_mov_b32 m0, s62
	v_lshl_add_u64 v[218:219], s[2:3], 0, v[156:157]
	ds_read_b128 v[162:165], v141 offset:32768
	ds_read_b128 v[166:169], v141 offset:33792
	ds_read_b128 v[170:173], v141 offset:34816
	ds_read_b128 v[174:177], v141 offset:35840
	ds_read_b128 v[178:181], v141 offset:36864
	ds_read_b128 v[182:185], v141 offset:37888
	ds_read_b128 v[186:189], v141 offset:38912
	ds_read_b128 v[214:217], v141 offset:39936
	global_load_lds_dwordx4 v[218:219], off
	v_lshl_add_u64 v[218:219], s[2:3], 0, v[128:129]
	s_mov_b32 m0, s63
	s_nop 0
	global_load_lds_dwordx4 v[218:219], off
	s_waitcnt lgkmcnt(8)
	s_barrier
	s_waitcnt lgkmcnt(0)
	s_setprio 1
	s_waitcnt lgkmcnt(0)
	v_mfma_f32_16x16x32_bf16 v[124:127], v[134:137], v[162:165], v[124:127]
	v_mfma_f32_16x16x32_bf16 v[116:119], v[146:149], v[162:165], v[116:119]
	v_mfma_f32_16x16x32_bf16 v[108:111], v[134:137], v[170:173], v[108:111]
	v_mfma_f32_16x16x32_bf16 v[100:103], v[146:149], v[170:173], v[100:103]
	v_mfma_f32_16x16x32_bf16 v[92:95], v[134:137], v[178:181], v[92:95]
	v_mfma_f32_16x16x32_bf16 v[84:87], v[146:149], v[178:181], v[84:87]
	v_mfma_f32_16x16x32_bf16 v[76:79], v[134:137], v[186:189], v[76:79]
	v_mfma_f32_16x16x32_bf16 v[68:71], v[146:149], v[186:189], v[68:71]
	v_mfma_f32_16x16x32_bf16 v[124:127], v[142:145], v[166:169], v[124:127]
	v_mfma_f32_16x16x32_bf16 v[116:119], v[150:153], v[166:169], v[116:119]
	v_mfma_f32_16x16x32_bf16 v[108:111], v[142:145], v[174:177], v[108:111]
	v_mfma_f32_16x16x32_bf16 v[100:103], v[150:153], v[174:177], v[100:103]
	v_mfma_f32_16x16x32_bf16 v[92:95], v[142:145], v[182:185], v[92:95]
	v_mfma_f32_16x16x32_bf16 v[84:87], v[150:153], v[182:185], v[84:87]
	v_mfma_f32_16x16x32_bf16 v[76:79], v[142:145], v[214:217], v[76:79]
	v_mfma_f32_16x16x32_bf16 v[68:71], v[150:153], v[214:217], v[68:71]
	s_setprio 0
	s_barrier
	s_add_i32 s78, 0, 0x1c000
	s_add_i32 s2, s77, s53
	v_add_u32_e32 v161, s78, v139
	v_lshl_add_u64 v[154:155], v[154:155], 0, s[50:51]
	s_mov_b32 m0, s2
	ds_read_b128 v[218:221], v161
	ds_read_b128 v[222:225], v161 offset:1024
	ds_read_b128 v[226:229], v161 offset:2048
	ds_read_b128 v[230:233], v161 offset:3072
	global_load_lds_dwordx4 v[154:155], off
	v_lshl_add_u64 v[154:155], v[206:207], 0, s[50:51]
	s_add_i32 m0, s2, 0x2000
	s_nop 0
	global_load_lds_dwordx4 v[154:155], off
	s_barrier
	s_waitcnt lgkmcnt(0)
	s_setprio 1
	s_waitcnt lgkmcnt(0)
	v_mfma_f32_16x16x32_bf16 v[120:123], v[218:221], v[162:165], v[120:123]
	v_mfma_f32_16x16x32_bf16 v[112:115], v[226:229], v[162:165], v[112:115]
	v_mfma_f32_16x16x32_bf16 v[104:107], v[218:221], v[170:173], v[104:107]
	v_mfma_f32_16x16x32_bf16 v[96:99], v[226:229], v[170:173], v[96:99]
	v_mfma_f32_16x16x32_bf16 v[88:91], v[218:221], v[178:181], v[88:91]
	v_mfma_f32_16x16x32_bf16 v[80:83], v[226:229], v[178:181], v[80:83]
	v_mfma_f32_16x16x32_bf16 v[72:75], v[218:221], v[186:189], v[72:75]
	v_mfma_f32_16x16x32_bf16 v[64:67], v[226:229], v[186:189], v[64:67]
	v_mfma_f32_16x16x32_bf16 v[120:123], v[222:225], v[166:169], v[120:123]
	v_mfma_f32_16x16x32_bf16 v[112:115], v[230:233], v[166:169], v[112:115]
	v_mfma_f32_16x16x32_bf16 v[104:107], v[222:225], v[174:177], v[104:107]
	v_mfma_f32_16x16x32_bf16 v[96:99], v[230:233], v[174:177], v[96:99]
	v_mfma_f32_16x16x32_bf16 v[88:91], v[222:225], v[182:185], v[88:91]
	v_mfma_f32_16x16x32_bf16 v[80:83], v[230:233], v[182:185], v[80:83]
	v_mfma_f32_16x16x32_bf16 v[72:75], v[222:225], v[214:217], v[72:75]
	v_mfma_f32_16x16x32_bf16 v[64:67], v[230:233], v[214:217], v[64:67]
	s_setprio 0
	s_mov_b32 m0, s66
	v_lshl_add_u64 v[154:155], v[208:209], 0, s[50:51]
	s_barrier
	ds_read_b128 v[162:165], v141 offset:49152
	ds_read_b128 v[166:169], v141 offset:50176
	ds_read_b128 v[170:173], v141 offset:51200
	ds_read_b128 v[174:177], v141 offset:52224
	ds_read_b128 v[178:181], v141 offset:53248
	ds_read_b128 v[182:185], v141 offset:54272
	ds_read_b128 v[186:189], v141 offset:55296
	ds_read_b128 v[214:217], v141 offset:56320
	global_load_lds_dwordx4 v[154:155], off
	v_lshl_add_u64 v[154:155], v[234:235], 0, s[50:51]
	s_mov_b32 m0, s67
	s_nop 0
	global_load_lds_dwordx4 v[154:155], off
	s_barrier
	s_waitcnt lgkmcnt(0)
	s_setprio 1
	s_waitcnt lgkmcnt(0)
	v_mfma_f32_16x16x32_bf16 v[60:63], v[134:137], v[162:165], v[60:63]
	v_mfma_f32_16x16x32_bf16 v[52:55], v[146:149], v[162:165], v[52:55]
	v_mfma_f32_16x16x32_bf16 v[44:47], v[134:137], v[170:173], v[44:47]
	v_mfma_f32_16x16x32_bf16 v[36:39], v[146:149], v[170:173], v[36:39]
	v_mfma_f32_16x16x32_bf16 v[28:31], v[134:137], v[178:181], v[28:31]
	v_mfma_f32_16x16x32_bf16 v[20:23], v[146:149], v[178:181], v[20:23]
	v_mfma_f32_16x16x32_bf16 v[12:15], v[134:137], v[186:189], v[12:15]
	v_mfma_f32_16x16x32_bf16 v[4:7], v[146:149], v[186:189], v[4:7]
	v_mfma_f32_16x16x32_bf16 v[60:63], v[142:145], v[166:169], v[60:63]
	v_mfma_f32_16x16x32_bf16 v[52:55], v[150:153], v[166:169], v[52:55]
	v_mfma_f32_16x16x32_bf16 v[44:47], v[142:145], v[174:177], v[44:47]
	v_mfma_f32_16x16x32_bf16 v[36:39], v[150:153], v[174:177], v[36:39]
	v_mfma_f32_16x16x32_bf16 v[28:31], v[142:145], v[182:185], v[28:31]
	v_mfma_f32_16x16x32_bf16 v[20:23], v[150:153], v[182:185], v[20:23]
	v_mfma_f32_16x16x32_bf16 v[12:15], v[142:145], v[214:217], v[12:15]
	v_mfma_f32_16x16x32_bf16 v[4:7], v[150:153], v[214:217], v[4:7]
	s_setprio 0
	s_barrier
	s_add_u32 s2, s54, 0x40080
	s_addc_u32 s3, s55, 0
	s_add_i32 s54, s78, s53
	v_lshl_add_u64 v[134:135], s[2:3], 0, v[156:157]
	s_mov_b32 m0, s54
	s_nop 0
	global_load_lds_dwordx4 v[134:135], off
	v_lshl_add_u64 v[134:135], s[2:3], 0, v[128:129]
	s_add_i32 m0, s54, 0x2000
	s_nop 0
	global_load_lds_dwordx4 v[134:135], off
	s_waitcnt vmcnt(6)
	s_barrier
	s_setprio 1
	v_mfma_f32_16x16x32_bf16 v[56:59], v[218:221], v[162:165], v[56:59]
	v_mfma_f32_16x16x32_bf16 v[48:51], v[226:229], v[162:165], v[48:51]
	v_mfma_f32_16x16x32_bf16 v[40:43], v[218:221], v[170:173], v[40:43]
	v_mfma_f32_16x16x32_bf16 v[32:35], v[226:229], v[170:173], v[32:35]
	v_mfma_f32_16x16x32_bf16 v[24:27], v[218:221], v[178:181], v[24:27]
	v_mfma_f32_16x16x32_bf16 v[16:19], v[226:229], v[178:181], v[16:19]
	v_mfma_f32_16x16x32_bf16 v[8:11], v[218:221], v[186:189], v[8:11]
	v_mfma_f32_16x16x32_bf16 v[0:3], v[226:229], v[186:189], v[0:3]
	v_mfma_f32_16x16x32_bf16 v[56:59], v[222:225], v[166:169], v[56:59]
	v_mfma_f32_16x16x32_bf16 v[48:51], v[230:233], v[166:169], v[48:51]
	v_mfma_f32_16x16x32_bf16 v[40:43], v[222:225], v[174:177], v[40:43]
	v_mfma_f32_16x16x32_bf16 v[32:35], v[230:233], v[174:177], v[32:35]
	v_mfma_f32_16x16x32_bf16 v[24:27], v[222:225], v[182:185], v[24:27]
	v_mfma_f32_16x16x32_bf16 v[16:19], v[230:233], v[182:185], v[16:19]
	v_mfma_f32_16x16x32_bf16 v[8:11], v[222:225], v[214:217], v[8:11]
	v_mfma_f32_16x16x32_bf16 v[0:3], v[230:233], v[214:217], v[0:3]
	s_setprio 0
	s_add_i32 s73, s73, 2
	s_add_u32 s43, s43, 0x100
	s_addc_u32 s69, s69, 0
	s_add_u32 s6, s6, 0x100
	s_addc_u32 s7, s7, 0
	s_cmp_gt_u32 s73, 13
	s_barrier
	s_cbranch_scc1 .Lpost_555

.Lpost_555:
	v_lshl_or_b32 v136, s46, 7, v140
	v_lshl_add_u32 v142, s48, 8, v138
	v_ashrrev_i32_e32 v137, 31, v136
	v_mov_b64_e32 v[134:135], s[30:31]
	v_lshlrev_b64 v[136:137], 1, v[136:137]
	s_and_b64 vcc, exec, s[38:39]
	s_mov_b32 s48, s42
	s_mov_b32 s46, s40
	v_mad_i64_i32 v[144:145], s[2:3], v142, s33, v[134:135]
	v_or_b32_e32 v186, 16, v142
	v_mul_f32_e32 v162, 0xbfb8aa3b, v124
	v_mad_i64_i32 v[186:187], s[2:3], v186, s33, v[134:135]
	v_mul_f32_e32 v163, 0xbfb8aa3b, v125
	v_mul_f32_e32 v170, 0xbfb8aa3b, v108
	v_mul_f32_e32 v164, 0xbfb8aa3b, v126
	v_mul_f32_e32 v171, 0xbfb8aa3b, v109
	v_mul_f32_e32 v165, 0xbfb8aa3b, v127
	v_mul_f32_e32 v172, 0xbfb8aa3b, v110
	v_mul_f32_e32 v166, 0xbfb8aa3b, v116
	v_mul_f32_e32 v173, 0xbfb8aa3b, v111
	v_mul_f32_e32 v167, 0xbfb8aa3b, v117
	v_mul_f32_e32 v174, 0xbfb8aa3b, v100
	v_mul_f32_e32 v168, 0xbfb8aa3b, v118
	v_mul_f32_e32 v175, 0xbfb8aa3b, v101
	v_mul_f32_e32 v169, 0xbfb8aa3b, v119
	v_mul_f32_e32 v176, 0xbfb8aa3b, v102
	v_lshl_add_u64 v[144:145], v[144:145], 0, v[136:137]
	v_mul_f32_e32 v177, 0xbfb8aa3b, v103
	v_exp_f32_e32 v162, v162
	v_lshl_add_u64 v[186:187], v[186:187], 0, v[136:137]
	v_exp_f32_e32 v163, v163
	v_exp_f32_e32 v170, v170
	v_exp_f32_e32 v164, v164
	v_exp_f32_e32 v171, v171
	v_exp_f32_e32 v165, v165
	v_exp_f32_e32 v172, v172
	v_exp_f32_e32 v166, v166
	v_exp_f32_e32 v173, v173
	v_exp_f32_e32 v167, v167
	v_exp_f32_e32 v174, v174
	v_exp_f32_e32 v168, v168
	v_exp_f32_e32 v175, v175
	v_exp_f32_e32 v169, v169
	v_exp_f32_e32 v176, v176
	v_pk_add_f32 v[162:163], v[162:163], 1.0 op_sel_hi:[1,0]
	v_exp_f32_e32 v177, v177
	v_pk_add_f32 v[164:165], v[164:165], 1.0 op_sel_hi:[1,0]
	v_pk_add_f32 v[170:171], v[170:171], 1.0 op_sel_hi:[1,0]
	v_pk_add_f32 v[166:167], v[166:167], 1.0 op_sel_hi:[1,0]
	v_pk_add_f32 v[172:173], v[172:173], 1.0 op_sel_hi:[1,0]
	v_pk_add_f32 v[168:169], v[168:169], 1.0 op_sel_hi:[1,0]
	v_pk_add_f32 v[174:175], v[174:175], 1.0 op_sel_hi:[1,0]
	v_rcp_f32_e32 v162, v162
	v_pk_add_f32 v[176:177], v[176:177], 1.0 op_sel_hi:[1,0]
	v_rcp_f32_e32 v163, v163
	v_rcp_f32_e32 v170, v170
	v_rcp_f32_e32 v164, v164
	v_rcp_f32_e32 v171, v171
	v_rcp_f32_e32 v165, v165
	v_rcp_f32_e32 v172, v172
	v_rcp_f32_e32 v166, v166
	v_rcp_f32_e32 v173, v173
	v_rcp_f32_e32 v167, v167
	v_rcp_f32_e32 v174, v174
	v_rcp_f32_e32 v168, v168
	v_rcp_f32_e32 v175, v175
	v_rcp_f32_e32 v169, v169
	v_rcp_f32_e32 v176, v176
	v_pk_mul_f32 v[162:163], v[124:125], v[162:163]
	v_rcp_f32_e32 v177, v177
	v_pk_mul_f32 v[164:165], v[126:127], v[164:165]
	v_pk_mul_f32 v[170:171], v[108:109], v[170:171]
	v_pk_mul_f32 v[166:167], v[116:117], v[166:167]
	v_pk_mul_f32 v[172:173], v[110:111], v[172:173]
	v_pk_mul_f32 v[168:169], v[118:119], v[168:169]
	v_pk_mul_f32 v[174:175], v[100:101], v[174:175]
	v_pk_mul_f32 v[162:163], v[162:163], v[120:121]
	v_pk_mul_f32 v[176:177], v[102:103], v[176:177]
	v_pk_mul_f32 v[164:165], v[164:165], v[122:123]
	v_pk_mul_f32 v[170:171], v[170:171], v[104:105]
	v_pk_mul_f32 v[166:167], v[166:167], v[112:113]
	v_pk_mul_f32 v[172:173], v[172:173], v[106:107]
	v_pk_mul_f32 v[168:169], v[168:169], v[114:115]
	v_pk_mul_f32 v[174:175], v[174:175], v[96:97]
	v_cvt_pk_bf16_f32 v178, v162, v163
	v_pk_mul_f32 v[176:177], v[176:177], v[98:99]
	v_cvt_pk_bf16_f32 v179, v164, v165
	v_cvt_pk_bf16_f32 v182, v170, v171
	v_cvt_pk_bf16_f32 v180, v166, v167
	v_cvt_pk_bf16_f32 v183, v172, v173
	v_cvt_pk_bf16_f32 v181, v168, v169
	v_cvt_pk_bf16_f32 v184, v174, v175
	global_store_dwordx4 v[144:145], v[178:181], off
	v_cvt_pk_bf16_f32 v185, v176, v177
	global_store_dwordx4 v[186:187], v[182:185], off
	v_or_b32_e32 v144, 32, v142
	v_or_b32_e32 v186, 48, v142
	v_mad_i64_i32 v[144:145], s[2:3], v144, s33, v[134:135]
	v_mad_i64_i32 v[186:187], s[2:3], v186, s33, v[134:135]
	v_mul_f32_e32 v162, 0xbfb8aa3b, v92
	v_mul_f32_e32 v170, 0xbfb8aa3b, v76
	v_mul_f32_e32 v163, 0xbfb8aa3b, v93
	v_mul_f32_e32 v171, 0xbfb8aa3b, v77
	v_mul_f32_e32 v164, 0xbfb8aa3b, v94
	v_mul_f32_e32 v172, 0xbfb8aa3b, v78
	v_mul_f32_e32 v165, 0xbfb8aa3b, v95
	v_mul_f32_e32 v173, 0xbfb8aa3b, v79
	v_mul_f32_e32 v166, 0xbfb8aa3b, v84
	v_mul_f32_e32 v174, 0xbfb8aa3b, v68
	v_mul_f32_e32 v167, 0xbfb8aa3b, v85
	v_mul_f32_e32 v175, 0xbfb8aa3b, v69
	v_mul_f32_e32 v168, 0xbfb8aa3b, v86
	v_mul_f32_e32 v176, 0xbfb8aa3b, v70
	v_mul_f32_e32 v169, 0xbfb8aa3b, v87
	v_mul_f32_e32 v177, 0xbfb8aa3b, v71
	v_lshl_add_u64 v[144:145], v[144:145], 0, v[136:137]
	v_lshl_add_u64 v[186:187], v[186:187], 0, v[136:137]
	v_exp_f32_e32 v162, v162
	v_exp_f32_e32 v170, v170
	v_exp_f32_e32 v163, v163
	v_exp_f32_e32 v171, v171
	v_exp_f32_e32 v164, v164
	v_exp_f32_e32 v172, v172
	v_exp_f32_e32 v165, v165
	v_exp_f32_e32 v173, v173
	v_exp_f32_e32 v166, v166
	v_exp_f32_e32 v174, v174
	v_exp_f32_e32 v167, v167
	v_exp_f32_e32 v175, v175
	v_exp_f32_e32 v168, v168
	v_exp_f32_e32 v176, v176
	v_exp_f32_e32 v169, v169
	v_exp_f32_e32 v177, v177
	v_pk_add_f32 v[162:163], v[162:163], 1.0 op_sel_hi:[1,0]
	v_pk_add_f32 v[170:171], v[170:171], 1.0 op_sel_hi:[1,0]
	v_pk_add_f32 v[164:165], v[164:165], 1.0 op_sel_hi:[1,0]
	v_pk_add_f32 v[172:173], v[172:173], 1.0 op_sel_hi:[1,0]
	v_pk_add_f32 v[166:167], v[166:167], 1.0 op_sel_hi:[1,0]
	v_pk_add_f32 v[174:175], v[174:175], 1.0 op_sel_hi:[1,0]
	v_pk_add_f32 v[168:169], v[168:169], 1.0 op_sel_hi:[1,0]
	v_pk_add_f32 v[176:177], v[176:177], 1.0 op_sel_hi:[1,0]
	v_rcp_f32_e32 v162, v162
	v_rcp_f32_e32 v170, v170
	v_rcp_f32_e32 v163, v163
	v_rcp_f32_e32 v171, v171
	v_rcp_f32_e32 v164, v164
	v_rcp_f32_e32 v172, v172
	v_rcp_f32_e32 v165, v165
	v_rcp_f32_e32 v173, v173
	v_rcp_f32_e32 v166, v166
	v_rcp_f32_e32 v174, v174
	v_rcp_f32_e32 v167, v167
	v_rcp_f32_e32 v175, v175
	v_rcp_f32_e32 v168, v168
	v_rcp_f32_e32 v176, v176
	v_rcp_f32_e32 v169, v169
	v_rcp_f32_e32 v177, v177
	v_pk_mul_f32 v[162:163], v[92:93], v[162:163]
	v_pk_mul_f32 v[170:171], v[76:77], v[170:171]
	v_pk_mul_f32 v[164:165], v[94:95], v[164:165]
	v_pk_mul_f32 v[172:173], v[78:79], v[172:173]
	v_pk_mul_f32 v[166:167], v[84:85], v[166:167]
	v_pk_mul_f32 v[174:175], v[68:69], v[174:175]
	v_pk_mul_f32 v[168:169], v[86:87], v[168:169]
	v_pk_mul_f32 v[176:177], v[70:71], v[176:177]
	v_pk_mul_f32 v[162:163], v[162:163], v[88:89]
	v_pk_mul_f32 v[170:171], v[170:171], v[72:73]
	v_pk_mul_f32 v[164:165], v[164:165], v[90:91]
	v_pk_mul_f32 v[172:173], v[172:173], v[74:75]
	v_pk_mul_f32 v[166:167], v[166:167], v[80:81]
	v_pk_mul_f32 v[174:175], v[174:175], v[64:65]
	v_pk_mul_f32 v[168:169], v[168:169], v[82:83]
	v_pk_mul_f32 v[176:177], v[176:177], v[66:67]
	v_cvt_pk_bf16_f32 v178, v162, v163
	v_cvt_pk_bf16_f32 v182, v170, v171
	v_cvt_pk_bf16_f32 v179, v164, v165
	v_cvt_pk_bf16_f32 v183, v172, v173
	v_cvt_pk_bf16_f32 v180, v166, v167
	v_cvt_pk_bf16_f32 v184, v174, v175
	v_cvt_pk_bf16_f32 v181, v168, v169
	v_cvt_pk_bf16_f32 v185, v176, v177
	global_store_dwordx4 v[144:145], v[178:181], off
	global_store_dwordx4 v[186:187], v[182:185], off
	v_add_u32_e32 v144, 0x80, v142
	v_add_u32_e32 v186, 0x90, v142
	v_mad_i64_i32 v[144:145], s[2:3], v144, s33, v[134:135]
	v_mad_i64_i32 v[186:187], s[2:3], v186, s33, v[134:135]
	v_mul_f32_e32 v162, 0xbfb8aa3b, v60
	v_mul_f32_e32 v170, 0xbfb8aa3b, v44
	v_mul_f32_e32 v163, 0xbfb8aa3b, v61
	v_mul_f32_e32 v171, 0xbfb8aa3b, v45
	v_mul_f32_e32 v164, 0xbfb8aa3b, v62
	v_mul_f32_e32 v172, 0xbfb8aa3b, v46
	v_mul_f32_e32 v165, 0xbfb8aa3b, v63
	v_mul_f32_e32 v173, 0xbfb8aa3b, v47
	v_mul_f32_e32 v166, 0xbfb8aa3b, v52
	v_mul_f32_e32 v174, 0xbfb8aa3b, v36
	v_mul_f32_e32 v167, 0xbfb8aa3b, v53
	v_mul_f32_e32 v175, 0xbfb8aa3b, v37
	v_mul_f32_e32 v168, 0xbfb8aa3b, v54
	v_mul_f32_e32 v176, 0xbfb8aa3b, v38
	v_mul_f32_e32 v169, 0xbfb8aa3b, v55
	v_mul_f32_e32 v177, 0xbfb8aa3b, v39
	v_lshl_add_u64 v[144:145], v[144:145], 0, v[136:137]
	v_lshl_add_u64 v[186:187], v[186:187], 0, v[136:137]
	v_exp_f32_e32 v162, v162
	v_exp_f32_e32 v170, v170
	v_exp_f32_e32 v163, v163
	v_exp_f32_e32 v171, v171
	v_exp_f32_e32 v164, v164
	v_exp_f32_e32 v172, v172
	v_exp_f32_e32 v165, v165
	v_exp_f32_e32 v173, v173
	v_exp_f32_e32 v166, v166
	v_exp_f32_e32 v174, v174
	v_exp_f32_e32 v167, v167
	v_exp_f32_e32 v175, v175
	v_exp_f32_e32 v168, v168
	v_exp_f32_e32 v176, v176
	v_exp_f32_e32 v169, v169
	v_exp_f32_e32 v177, v177
	v_pk_add_f32 v[162:163], v[162:163], 1.0 op_sel_hi:[1,0]
	v_pk_add_f32 v[170:171], v[170:171], 1.0 op_sel_hi:[1,0]
	v_pk_add_f32 v[164:165], v[164:165], 1.0 op_sel_hi:[1,0]
	v_pk_add_f32 v[172:173], v[172:173], 1.0 op_sel_hi:[1,0]
	v_pk_add_f32 v[166:167], v[166:167], 1.0 op_sel_hi:[1,0]
	v_pk_add_f32 v[174:175], v[174:175], 1.0 op_sel_hi:[1,0]
	v_pk_add_f32 v[168:169], v[168:169], 1.0 op_sel_hi:[1,0]
	v_pk_add_f32 v[176:177], v[176:177], 1.0 op_sel_hi:[1,0]
	v_rcp_f32_e32 v162, v162
	v_rcp_f32_e32 v170, v170
	v_rcp_f32_e32 v163, v163
	v_rcp_f32_e32 v171, v171
	v_rcp_f32_e32 v164, v164
	v_rcp_f32_e32 v172, v172
	v_rcp_f32_e32 v165, v165
	v_rcp_f32_e32 v173, v173
	v_rcp_f32_e32 v166, v166
	v_rcp_f32_e32 v174, v174
	v_rcp_f32_e32 v167, v167
	v_rcp_f32_e32 v175, v175
	v_rcp_f32_e32 v168, v168
	v_rcp_f32_e32 v176, v176
	v_rcp_f32_e32 v169, v169
	v_rcp_f32_e32 v177, v177
	v_pk_mul_f32 v[162:163], v[60:61], v[162:163]
	v_pk_mul_f32 v[170:171], v[44:45], v[170:171]
	v_pk_mul_f32 v[164:165], v[62:63], v[164:165]
	v_pk_mul_f32 v[172:173], v[46:47], v[172:173]
	v_pk_mul_f32 v[166:167], v[52:53], v[166:167]
	v_pk_mul_f32 v[174:175], v[36:37], v[174:175]
	v_pk_mul_f32 v[168:169], v[54:55], v[168:169]
	v_pk_mul_f32 v[176:177], v[38:39], v[176:177]
	v_pk_mul_f32 v[162:163], v[162:163], v[56:57]
	v_pk_mul_f32 v[170:171], v[170:171], v[40:41]
	v_pk_mul_f32 v[164:165], v[164:165], v[58:59]
	v_pk_mul_f32 v[172:173], v[172:173], v[42:43]
	v_pk_mul_f32 v[166:167], v[166:167], v[48:49]
	v_pk_mul_f32 v[174:175], v[174:175], v[32:33]
	v_pk_mul_f32 v[168:169], v[168:169], v[50:51]
	v_pk_mul_f32 v[176:177], v[176:177], v[34:35]
	v_cvt_pk_bf16_f32 v178, v162, v163
	v_cvt_pk_bf16_f32 v182, v170, v171
	v_cvt_pk_bf16_f32 v179, v164, v165
	v_cvt_pk_bf16_f32 v183, v172, v173
	v_cvt_pk_bf16_f32 v180, v166, v167
	v_cvt_pk_bf16_f32 v184, v174, v175
	v_cvt_pk_bf16_f32 v181, v168, v169
	v_cvt_pk_bf16_f32 v185, v176, v177
	global_store_dwordx4 v[144:145], v[178:181], off
	global_store_dwordx4 v[186:187], v[182:185], off
	v_add_u32_e32 v144, 0xa0, v142
	v_add_u32_e32 v186, 0xb0, v142
	v_mad_i64_i32 v[144:145], s[2:3], v144, s33, v[134:135]
	v_mad_i64_i32 v[186:187], s[2:3], v186, s33, v[134:135]
	v_mul_f32_e32 v162, 0xbfb8aa3b, v28
	v_mul_f32_e32 v170, 0xbfb8aa3b, v12
	v_mul_f32_e32 v163, 0xbfb8aa3b, v29
	v_mul_f32_e32 v171, 0xbfb8aa3b, v13
	v_mul_f32_e32 v164, 0xbfb8aa3b, v30
	v_mul_f32_e32 v172, 0xbfb8aa3b, v14
	v_mul_f32_e32 v165, 0xbfb8aa3b, v31
	v_mul_f32_e32 v173, 0xbfb8aa3b, v15
	v_mul_f32_e32 v166, 0xbfb8aa3b, v20
	v_mul_f32_e32 v174, 0xbfb8aa3b, v4
	v_mul_f32_e32 v167, 0xbfb8aa3b, v21
	v_mul_f32_e32 v175, 0xbfb8aa3b, v5
	v_mul_f32_e32 v168, 0xbfb8aa3b, v22
	v_mul_f32_e32 v176, 0xbfb8aa3b, v6
	v_mul_f32_e32 v169, 0xbfb8aa3b, v23
	v_mul_f32_e32 v177, 0xbfb8aa3b, v7
	v_lshl_add_u64 v[144:145], v[144:145], 0, v[136:137]
	v_lshl_add_u64 v[186:187], v[186:187], 0, v[136:137]
	v_exp_f32_e32 v162, v162
	v_exp_f32_e32 v170, v170
	v_exp_f32_e32 v163, v163
	v_exp_f32_e32 v171, v171
	v_exp_f32_e32 v164, v164
	v_exp_f32_e32 v172, v172
	v_exp_f32_e32 v165, v165
	v_exp_f32_e32 v173, v173
	v_exp_f32_e32 v166, v166
	v_exp_f32_e32 v174, v174
	v_exp_f32_e32 v167, v167
	v_exp_f32_e32 v175, v175
	v_exp_f32_e32 v168, v168
	v_exp_f32_e32 v176, v176
	v_exp_f32_e32 v169, v169
	v_exp_f32_e32 v177, v177
	v_pk_add_f32 v[162:163], v[162:163], 1.0 op_sel_hi:[1,0]
	v_pk_add_f32 v[170:171], v[170:171], 1.0 op_sel_hi:[1,0]
	v_pk_add_f32 v[164:165], v[164:165], 1.0 op_sel_hi:[1,0]
	v_pk_add_f32 v[172:173], v[172:173], 1.0 op_sel_hi:[1,0]
	v_pk_add_f32 v[166:167], v[166:167], 1.0 op_sel_hi:[1,0]
	v_pk_add_f32 v[174:175], v[174:175], 1.0 op_sel_hi:[1,0]
	v_pk_add_f32 v[168:169], v[168:169], 1.0 op_sel_hi:[1,0]
	v_pk_add_f32 v[176:177], v[176:177], 1.0 op_sel_hi:[1,0]
	v_rcp_f32_e32 v162, v162
	v_rcp_f32_e32 v170, v170
	v_rcp_f32_e32 v163, v163
	v_rcp_f32_e32 v171, v171
	v_rcp_f32_e32 v164, v164
	v_rcp_f32_e32 v172, v172
	v_rcp_f32_e32 v165, v165
	v_rcp_f32_e32 v173, v173
	v_rcp_f32_e32 v166, v166
	v_rcp_f32_e32 v174, v174
	v_rcp_f32_e32 v167, v167
	v_rcp_f32_e32 v175, v175
	v_rcp_f32_e32 v168, v168
	v_rcp_f32_e32 v176, v176
	v_rcp_f32_e32 v169, v169
	v_rcp_f32_e32 v177, v177
	v_pk_mul_f32 v[162:163], v[28:29], v[162:163]
	v_pk_mul_f32 v[170:171], v[12:13], v[170:171]
	v_pk_mul_f32 v[164:165], v[30:31], v[164:165]
	v_pk_mul_f32 v[172:173], v[14:15], v[172:173]
	v_pk_mul_f32 v[166:167], v[20:21], v[166:167]
	v_pk_mul_f32 v[174:175], v[4:5], v[174:175]
	v_pk_mul_f32 v[168:169], v[22:23], v[168:169]
	v_pk_mul_f32 v[176:177], v[6:7], v[176:177]
	v_pk_mul_f32 v[162:163], v[162:163], v[24:25]
	v_pk_mul_f32 v[170:171], v[170:171], v[8:9]
	v_pk_mul_f32 v[164:165], v[164:165], v[26:27]
	v_pk_mul_f32 v[172:173], v[172:173], v[10:11]
	v_pk_mul_f32 v[166:167], v[166:167], v[16:17]
	v_pk_mul_f32 v[174:175], v[174:175], v[0:1]
	v_pk_mul_f32 v[168:169], v[168:169], v[18:19]
	v_pk_mul_f32 v[176:177], v[176:177], v[2:3]
	v_cvt_pk_bf16_f32 v178, v162, v163
	v_cvt_pk_bf16_f32 v182, v170, v171
	v_cvt_pk_bf16_f32 v179, v164, v165
	v_cvt_pk_bf16_f32 v183, v172, v173
	v_cvt_pk_bf16_f32 v180, v166, v167
	v_cvt_pk_bf16_f32 v184, v174, v175
	v_cvt_pk_bf16_f32 v181, v168, v169
	v_cvt_pk_bf16_f32 v185, v176, v177
	global_store_dwordx4 v[144:145], v[178:181], off
	global_store_dwordx4 v[186:187], v[182:185], off
	s_cbranch_vccz .LBB0_554
	s_waitcnt vmcnt(0)
	s_cmpk_gt_u32 s21, 0xff
	s_cbranch_scc1 .LBB0_559
	s_barrier
